# v29 with one lgkmcnt wait per pair of MFMAs in the attention QK^T and PV segments (fewer instructions in the issue-bound tile loop)
# baseline (speedup 1.0000x reference)
.LBB0_497:
	v_exp_f32_e64 v151, -|v85|
	v_cmp_lt_f32_e32 vcc, 0, v85
	v_add_f32_e32 v168, 1.0, v151
	v_rcp_f32_e32 v168, v168
	s_nop 0
	v_mul_f32_e32 v151, v151, v168
	v_cndmask_b32_e32 v85, v151, v168, vcc
	v_cndmask_b32_e32 v151, v168, v151, vcc
	v_exp_f32_e64 v168, -|v69|
	v_cmp_lt_f32_e32 vcc, 0, v69
	v_add_f32_e32 v169, 1.0, v168
	v_rcp_f32_e32 v169, v169
	s_nop 0
	v_mul_f32_e32 v168, v168, v169
	v_cndmask_b32_e32 v69, v168, v169, vcc
	v_cndmask_b32_e32 v168, v169, v168, vcc
	v_exp_f32_e64 v169, -|v84|
	v_cmp_lt_f32_e32 vcc, 0, v84
	v_add_f32_e32 v179, 1.0, v169
	v_rcp_f32_e32 v179, v179
	s_nop 0
	v_mul_f32_e32 v169, v169, v179
	v_cndmask_b32_e32 v84, v169, v179, vcc
	v_cndmask_b32_e32 v169, v179, v169, vcc
	v_mul_f32_e32 v84, v151, v84
	v_mul_f32_e32 v151, v151, v169
	v_exp_f32_e64 v169, -|v68|
	v_cmp_lt_f32_e32 vcc, 0, v68
	v_add_f32_e32 v179, 1.0, v169
	v_rcp_f32_e32 v179, v179
	s_nop 0
	v_mul_f32_e32 v169, v169, v179
	v_cndmask_b32_e32 v68, v169, v179, vcc
	v_cndmask_b32_e32 v169, v179, v169, vcc
	v_mul_f32_e32 v68, v168, v68
	v_mul_f32_e32 v168, v168, v169
	v_exp_f32_e64 v169, -|v83|
	v_cmp_lt_f32_e32 vcc, 0, v83
	v_add_f32_e32 v179, 1.0, v169
	v_rcp_f32_e32 v179, v179
	s_nop 0
	v_mul_f32_e32 v169, v169, v179
	v_cndmask_b32_e32 v83, v169, v179, vcc
	v_cndmask_b32_e32 v169, v179, v169, vcc
	v_mul_f32_e32 v83, v83, v151
	v_mul_f32_e32 v151, v169, v151
	v_exp_f32_e64 v169, -|v67|
	v_cmp_lt_f32_e32 vcc, 0, v67
	v_add_f32_e32 v179, 1.0, v169
	v_rcp_f32_e32 v179, v179
	s_nop 0
	v_mul_f32_e32 v169, v169, v179
	v_cndmask_b32_e32 v67, v169, v179, vcc
	v_cndmask_b32_e32 v169, v179, v169, vcc
	v_mul_f32_e32 v67, v67, v168
	v_mul_f32_e32 v169, v169, v168
	v_exp_f32_e64 v168, -|v82|
	v_cmp_lt_f32_e32 vcc, 0, v82
	v_add_f32_e32 v179, 1.0, v168
	v_rcp_f32_e32 v179, v179
	s_nop 0
	v_mul_f32_e32 v168, v168, v179
	v_cndmask_b32_e32 v82, v168, v179, vcc
	v_cndmask_b32_e32 v168, v179, v168, vcc
	v_mul_f32_e32 v82, v82, v151
	v_mul_f32_e32 v168, v168, v151
	v_exp_f32_e64 v151, -|v66|
	v_cmp_lt_f32_e32 vcc, 0, v66
	v_add_f32_e32 v179, 1.0, v151
	v_rcp_f32_e32 v179, v179
	s_nop 0
	v_mul_f32_e32 v151, v151, v179
	v_cndmask_b32_e32 v66, v151, v179, vcc
	v_cndmask_b32_e32 v151, v179, v151, vcc
	v_mul_f32_e32 v66, v66, v169
	v_mul_f32_e32 v169, v151, v169
	v_exp_f32_e64 v151, -|v89|
	v_cmp_lt_f32_e32 vcc, 0, v89
	v_add_f32_e32 v179, 1.0, v151
	v_rcp_f32_e32 v179, v179
	s_nop 0
	v_mul_f32_e32 v151, v151, v179
	v_cndmask_b32_e32 v89, v151, v179, vcc
	v_cndmask_b32_e32 v151, v179, v151, vcc
	v_exp_f32_e64 v179, -|v73|
	v_cmp_lt_f32_e32 vcc, 0, v73
	v_add_f32_e32 v180, 1.0, v179
	v_rcp_f32_e32 v180, v180
	s_nop 0
	v_mul_f32_e32 v179, v179, v180
	v_cndmask_b32_e32 v73, v179, v180, vcc
	v_cndmask_b32_e32 v179, v180, v179, vcc
	v_exp_f32_e64 v180, -|v88|
	v_cmp_lt_f32_e32 vcc, 0, v88
	v_add_f32_e32 v181, 1.0, v180
	v_rcp_f32_e32 v181, v181
	s_nop 0
	v_mul_f32_e32 v180, v180, v181
	v_cndmask_b32_e32 v88, v180, v181, vcc
	v_cndmask_b32_e32 v180, v181, v180, vcc
	v_mul_f32_e32 v88, v151, v88
	v_mul_f32_e32 v151, v151, v180
	v_exp_f32_e64 v180, -|v72|
	v_cmp_lt_f32_e32 vcc, 0, v72
	v_add_f32_e32 v181, 1.0, v180
	v_rcp_f32_e32 v181, v181
	s_nop 0
	v_mul_f32_e32 v180, v180, v181
	v_cndmask_b32_e32 v72, v180, v181, vcc
	v_cndmask_b32_e32 v180, v181, v180, vcc
	v_mul_f32_e32 v72, v179, v72
	v_mul_f32_e32 v179, v179, v180
	v_exp_f32_e64 v180, -|v87|
	v_cmp_lt_f32_e32 vcc, 0, v87
	v_add_f32_e32 v181, 1.0, v180
	v_rcp_f32_e32 v181, v181
	s_nop 0
	v_mul_f32_e32 v180, v180, v181
	v_cndmask_b32_e32 v87, v180, v181, vcc
	v_cndmask_b32_e32 v180, v181, v180, vcc
	v_mul_f32_e32 v87, v87, v151
	v_mul_f32_e32 v151, v180, v151
	v_exp_f32_e64 v180, -|v71|
	v_cmp_lt_f32_e32 vcc, 0, v71
	v_add_f32_e32 v181, 1.0, v180
	v_rcp_f32_e32 v181, v181
	s_nop 0
	v_mul_f32_e32 v180, v180, v181
	v_cndmask_b32_e32 v71, v180, v181, vcc
	v_cndmask_b32_e32 v180, v181, v180, vcc
	v_mul_f32_e32 v71, v71, v179
	v_mul_f32_e32 v180, v180, v179
	v_exp_f32_e64 v179, -|v86|
	v_cmp_lt_f32_e32 vcc, 0, v86
	v_add_f32_e32 v181, 1.0, v179
	v_rcp_f32_e32 v181, v181
	s_nop 0
	v_mul_f32_e32 v179, v179, v181
	v_cndmask_b32_e32 v86, v179, v181, vcc
	v_cndmask_b32_e32 v179, v181, v179, vcc
	v_mul_f32_e32 v86, v86, v151
	v_mul_f32_e32 v179, v179, v151
	v_exp_f32_e64 v151, -|v70|
	v_cmp_lt_f32_e32 vcc, 0, v70
	v_add_f32_e32 v181, 1.0, v151
	v_rcp_f32_e32 v181, v181
	s_nop 0
	v_mul_f32_e32 v151, v151, v181
	v_cndmask_b32_e32 v70, v151, v181, vcc
	v_cndmask_b32_e32 v151, v181, v151, vcc
	v_mul_f32_e32 v70, v70, v180
	v_mul_f32_e32 v180, v151, v180
	v_exp_f32_e64 v151, -|v93|
	v_cmp_lt_f32_e32 vcc, 0, v93
	v_add_f32_e32 v181, 1.0, v151
	v_rcp_f32_e32 v181, v181
	s_nop 0
	v_mul_f32_e32 v151, v151, v181
	v_cndmask_b32_e32 v93, v151, v181, vcc
	v_cndmask_b32_e32 v151, v181, v151, vcc
	v_exp_f32_e64 v181, -|v77|
	v_cmp_lt_f32_e32 vcc, 0, v77
	v_add_f32_e32 v182, 1.0, v181
	v_rcp_f32_e32 v182, v182
	s_nop 0
	v_mul_f32_e32 v181, v181, v182
	v_cndmask_b32_e32 v77, v181, v182, vcc
	v_cndmask_b32_e32 v181, v182, v181, vcc
	v_exp_f32_e64 v182, -|v92|
	v_cmp_lt_f32_e32 vcc, 0, v92
	v_add_f32_e32 v183, 1.0, v182
	v_rcp_f32_e32 v183, v183
	s_nop 0
	v_mul_f32_e32 v182, v182, v183
	v_cndmask_b32_e32 v92, v182, v183, vcc
	v_cndmask_b32_e32 v182, v183, v182, vcc
	v_mul_f32_e32 v92, v151, v92
	v_mul_f32_e32 v151, v151, v182
	v_exp_f32_e64 v182, -|v76|
	v_cmp_lt_f32_e32 vcc, 0, v76
	v_add_f32_e32 v183, 1.0, v182
	v_rcp_f32_e32 v183, v183
	s_nop 0
	v_mul_f32_e32 v182, v182, v183
	v_cndmask_b32_e32 v76, v182, v183, vcc
	v_cndmask_b32_e32 v182, v183, v182, vcc
	v_mul_f32_e32 v76, v181, v76
	v_mul_f32_e32 v181, v181, v182
	v_exp_f32_e64 v182, -|v91|
	v_cmp_lt_f32_e32 vcc, 0, v91
	v_add_f32_e32 v183, 1.0, v182
	v_rcp_f32_e32 v183, v183
	s_nop 0
	v_mul_f32_e32 v182, v182, v183
	v_cndmask_b32_e32 v91, v182, v183, vcc
	v_cndmask_b32_e32 v182, v183, v182, vcc
	v_mul_f32_e32 v91, v91, v151
	v_mul_f32_e32 v151, v182, v151
	v_exp_f32_e64 v182, -|v75|
	v_cmp_lt_f32_e32 vcc, 0, v75
	v_add_f32_e32 v183, 1.0, v182
	v_rcp_f32_e32 v183, v183
	s_nop 0
	v_mul_f32_e32 v182, v182, v183
	v_cndmask_b32_e32 v75, v182, v183, vcc
	v_cndmask_b32_e32 v182, v183, v182, vcc
	v_mul_f32_e32 v75, v75, v181
	v_mul_f32_e32 v182, v182, v181
	v_exp_f32_e64 v181, -|v90|
	v_cmp_lt_f32_e32 vcc, 0, v90
	v_add_f32_e32 v183, 1.0, v181
	v_rcp_f32_e32 v183, v183
	s_nop 0
	v_mul_f32_e32 v181, v181, v183
	v_cndmask_b32_e32 v90, v181, v183, vcc
	v_cndmask_b32_e32 v181, v183, v181, vcc
	v_mul_f32_e32 v90, v90, v151
	v_mul_f32_e32 v181, v181, v151
	v_exp_f32_e64 v151, -|v74|
	v_cmp_lt_f32_e32 vcc, 0, v74
	v_add_f32_e32 v183, 1.0, v151
	v_rcp_f32_e32 v183, v183
	s_nop 0
	v_mul_f32_e32 v151, v151, v183
	v_cndmask_b32_e32 v74, v151, v183, vcc
	v_cndmask_b32_e32 v151, v183, v151, vcc
	v_mul_f32_e32 v74, v74, v182
	v_mul_f32_e32 v151, v151, v182
	v_exp_f32_e64 v182, -|v97|
	v_cmp_lt_f32_e32 vcc, 0, v97
	v_add_f32_e32 v183, 1.0, v182
	v_rcp_f32_e32 v183, v183
	s_nop 0
	v_mul_f32_e32 v182, v182, v183
	v_cndmask_b32_e32 v97, v182, v183, vcc
	v_cndmask_b32_e32 v182, v183, v182, vcc
	v_exp_f32_e64 v183, -|v81|
	v_cmp_lt_f32_e32 vcc, 0, v81
	v_add_f32_e32 v184, 1.0, v183
	v_rcp_f32_e32 v184, v184
	s_nop 0
	v_mul_f32_e32 v183, v183, v184
	v_cndmask_b32_e32 v185, v183, v184, vcc
	v_cndmask_b32_e32 v81, v184, v183, vcc
	v_exp_f32_e64 v183, -|v96|
	v_cmp_lt_f32_e32 vcc, 0, v96
	v_add_f32_e32 v184, 1.0, v183
	v_rcp_f32_e32 v184, v184
	s_nop 0
	v_mul_f32_e32 v183, v183, v184
	v_cndmask_b32_e32 v96, v183, v184, vcc
	v_cndmask_b32_e32 v183, v184, v183, vcc
	v_mul_f32_e32 v96, v182, v96
	v_mul_f32_e32 v182, v182, v183
	v_exp_f32_e64 v183, -|v80|
	v_cmp_lt_f32_e32 vcc, 0, v80
	v_add_f32_e32 v184, 1.0, v183
	v_rcp_f32_e32 v184, v184
	s_nop 0
	v_mul_f32_e32 v183, v183, v184
	v_cndmask_b32_e32 v80, v183, v184, vcc
	v_mul_f32_e32 v186, v81, v80
	v_cndmask_b32_e32 v80, v184, v183, vcc
	v_mul_f32_e32 v80, v81, v80
	v_exp_f32_e64 v81, -|v95|
	v_cmp_lt_f32_e32 vcc, 0, v95
	v_add_f32_e32 v183, 1.0, v81
	v_rcp_f32_e32 v183, v183
	s_nop 0
	v_mul_f32_e32 v81, v81, v183
	v_cndmask_b32_e32 v95, v81, v183, vcc
	v_cndmask_b32_e32 v81, v183, v81, vcc
	v_mul_f32_e32 v95, v95, v182
	v_mul_f32_e32 v81, v81, v182
	v_exp_f32_e64 v182, -|v79|
	v_cmp_lt_f32_e32 vcc, 0, v79
	v_add_f32_e32 v183, 1.0, v182
	v_rcp_f32_e32 v183, v183
	s_nop 0
	v_mul_f32_e32 v182, v182, v183
	v_cndmask_b32_e32 v79, v182, v183, vcc
	v_mul_f32_e32 v184, v79, v80
	v_cndmask_b32_e32 v79, v183, v182, vcc
	v_mul_f32_e32 v79, v79, v80
	v_exp_f32_e64 v80, -|v94|
	v_cmp_lt_f32_e32 vcc, 0, v94
	v_add_f32_e32 v182, 1.0, v80
	v_rcp_f32_e32 v182, v182
	s_nop 0
	v_mul_f32_e32 v80, v80, v182
	v_cndmask_b32_e32 v94, v80, v182, vcc
	v_cndmask_b32_e32 v80, v182, v80, vcc
	v_mul_f32_e32 v182, v80, v81
	v_exp_f32_e64 v80, -|v78|
	v_mul_f32_e32 v94, v94, v81
	v_cmp_lt_f32_e32 vcc, 0, v78
	v_add_f32_e32 v81, 1.0, v80
	v_rcp_f32_e32 v81, v81
	s_nop 0
	v_mul_f32_e32 v80, v80, v81
	v_cndmask_b32_e32 v78, v80, v81, vcc
	v_mul_f32_e32 v183, v78, v79
	v_cndmask_b32_e32 v78, v81, v80, vcc
	v_mul_f32_e32 v78, v78, v79
	v_mov_b32_e32 v79, v78
	s_nop 1
	v_permlane32_swap_b32_e32 v78, v79
	v_mul_f32_e32 v80, v150, v79
	v_mul_f32_e32 v78, v78, v79
	v_mov_b32_e32 v79, v151
	s_nop 1
	v_permlane32_swap_b32_e32 v151, v79
	v_cndmask_b32_e64 v187, v150, v80, s[38:39]
	v_pk_mul_f32 v[80:81], v[150:151], v[78:79]
	s_nop 0
	v_mul_f32_e32 v78, v80, v79
	v_cndmask_b32_e64 v151, v80, v78, s[38:39]
	v_pk_mul_f32 v[78:79], v[80:81], v[80:81] op_sel:[0,1] op_sel_hi:[1,0]
	v_mov_b32_e32 v81, v169
	v_mov_b32_e32 v79, v180
	s_nop 1
	v_permlane32_swap_b32_e32 v180, v79
	v_mul_f32_e32 v80, v78, v79
	v_permlane32_swap_b32_e32 v169, v81
	v_cndmask_b32_e64 v188, v78, v80, s[38:39]
	v_mul_f32_e32 v80, v180, v79
	v_mov_b32_e32 v79, v169
	v_pk_mul_f32 v[78:79], v[78:79], v[80:81]
	s_nop 0
	v_mul_f32_e32 v80, v78, v81
	v_cndmask_b32_e64 v169, v78, v80, s[38:39]
	v_pk_mul_f32 v[78:79], v[78:79], v[78:79] op_sel:[0,1] op_sel_hi:[1,0]
	v_mov_b32_e32 v81, v181
	v_mov_b32_e32 v79, v182
	s_nop 1
	v_permlane32_swap_b32_e32 v182, v79
	v_mul_f32_e32 v80, v78, v79
	v_permlane32_swap_b32_e32 v181, v81
	v_cndmask_b32_e64 v180, v78, v80, s[38:39]
	v_mul_f32_e32 v80, v182, v79
	v_mov_b32_e32 v79, v181
	v_pk_mul_f32 v[78:79], v[78:79], v[80:81]
	s_nop 0
	v_mul_f32_e32 v80, v78, v81
	v_cndmask_b32_e64 v181, v78, v80, s[38:39]
	v_pk_mul_f32 v[78:79], v[78:79], v[78:79] op_sel:[0,1] op_sel_hi:[1,0]
	v_mov_b32_e32 v81, v168
	v_mov_b32_e32 v79, v179
	s_nop 1
	v_permlane32_swap_b32_e32 v179, v79
	v_mul_f32_e32 v80, v78, v79
	v_permlane32_swap_b32_e32 v168, v81
	v_cndmask_b32_e64 v182, v78, v80, s[38:39]
	v_mul_f32_e32 v80, v179, v79
	v_mov_b32_e32 v79, v168
	v_pk_mul_f32 v[78:79], v[78:79], v[80:81]
	s_nop 0
	v_mul_f32_e32 v80, v78, v81
	v_mul_f32_e32 v150, v78, v79
	v_cndmask_b32_e64 v80, v78, v80, s[38:39]
	v_cmp_eq_f32_e32 vcc, 0, v150
	v_mul_f32_e32 v78, v82, v80
	v_mul_f32_e32 v79, v66, v169
	v_mul_f32_e32 v66, v83, v80
	v_mul_f32_e32 v81, v67, v169
	v_mul_f32_e32 v67, v84, v80
	v_mul_f32_e32 v82, v68, v169
	v_mul_f32_e32 v68, v85, v80
	v_mul_f32_e32 v80, v69, v169
	v_mul_f32_e32 v69, v86, v182
	v_mul_f32_e32 v83, v188, v70
	v_mul_f32_e32 v70, v87, v182
	v_mul_f32_e32 v84, v71, v188
	v_mul_f32_e32 v71, v88, v182
	v_mul_f32_e32 v85, v72, v188
	v_mul_f32_e32 v72, v89, v182
	v_mul_f32_e32 v86, v73, v188
	v_mul_f32_e32 v73, v90, v181
	v_mul_f32_e32 v87, v151, v74
	v_mul_f32_e32 v74, v91, v181
	v_mul_f32_e32 v88, v151, v75
	v_mul_f32_e32 v75, v92, v181
	v_mul_f32_e32 v89, v76, v151
	v_mul_f32_e32 v76, v93, v181
	v_mul_f32_e32 v90, v77, v151
	v_mul_f32_e32 v77, v94, v180
	s_cmp_eq_u64 vcc, exec
	v_mul_f32_e32 v91, v187, v183
	v_mul_f32_e32 v92, v95, v180
	v_mul_f32_e32 v93, v187, v184
	v_mul_f32_e32 v94, v96, v180
	v_mul_f32_e32 v95, v187, v186
	v_mul_f32_e32 v96, v97, v180
	v_mul_f32_e32 v97, v187, v185
	s_cselect_b64 s[0:1], -1, 0
	v_cvt_pk_bf16_f32 v66, v78, v66
	v_cvt_pk_bf16_f32 v67, v67, v68
	v_cvt_pk_bf16_f32 v68, v69, v70
	v_cvt_pk_bf16_f32 v69, v71, v72
	v_cvt_pk_bf16_f32 v70, v73, v74
	v_cvt_pk_bf16_f32 v71, v75, v76
	v_cvt_pk_bf16_f32 v72, v77, v92
	v_cvt_pk_bf16_f32 v73, v94, v96
	v_cvt_pk_bf16_f32 v74, v79, v81
	v_cvt_pk_bf16_f32 v75, v82, v80
	v_cvt_pk_bf16_f32 v76, v83, v84
	v_cvt_pk_bf16_f32 v77, v85, v86
	v_cvt_pk_bf16_f32 v78, v87, v88
	v_cvt_pk_bf16_f32 v79, v89, v90
	v_cvt_pk_bf16_f32 v80, v91, v93
	v_cvt_pk_bf16_f32 v81, v95, v97
	s_nop 0
	v_permlane32_swap_b32_e32 v66, v68
	v_permlane32_swap_b32_e32 v67, v69
	v_permlane32_swap_b32_e32 v70, v72
	v_permlane32_swap_b32_e32 v71, v73
	v_permlane32_swap_b32_e32 v74, v76
	v_permlane32_swap_b32_e32 v75, v77
	v_permlane32_swap_b32_e32 v78, v80
	v_permlane32_swap_b32_e32 v79, v81
	v_add_u32_e32 v151, s21, v165
	ds_read_b64_tr_b16 v[82:83], v151 offset:0
	ds_read_b64_tr_b16 v[84:85], v151 offset:0x800
	ds_read_b64_tr_b16 v[86:87], v151 offset:0x1000
	ds_read_b64_tr_b16 v[88:89], v151 offset:0x1800
	ds_read_b64_tr_b16 v[90:91], v151 offset:0x2000
	ds_read_b64_tr_b16 v[92:93], v151 offset:0x2800
	ds_read_b64_tr_b16 v[94:95], v151 offset:0x3000
	ds_read_b64_tr_b16 v[96:97], v151 offset:0x3800
	s_nop 0
	s_waitcnt lgkmcnt(4)
	v_mfma_f32_32x32x16_bf16 v[50:65], v[66:69], v[82:85], v[50:65]
	ds_read_b64_tr_b16 v[82:83], v151 offset:0x200
	ds_read_b64_tr_b16 v[84:85], v151 offset:0xa00
	v_mfma_f32_32x32x16_bf16 v[50:65], v[70:73], v[86:89], v[50:65]
	ds_read_b64_tr_b16 v[86:87], v151 offset:0x1200
	ds_read_b64_tr_b16 v[88:89], v151 offset:0x1a00
	s_waitcnt lgkmcnt(4)
	v_mfma_f32_32x32x16_bf16 v[50:65], v[74:77], v[90:93], v[50:65]
	ds_read_b64_tr_b16 v[90:91], v151 offset:0x2200
	ds_read_b64_tr_b16 v[92:93], v151 offset:0x2a00
	v_mfma_f32_32x32x16_bf16 v[50:65], v[78:81], v[94:97], v[50:65]
	ds_read_b64_tr_b16 v[94:95], v151 offset:0x3200
	ds_read_b64_tr_b16 v[96:97], v151 offset:0x3a00
	s_waitcnt lgkmcnt(4)
	v_mfma_f32_32x32x16_bf16 v[34:49], v[66:69], v[82:85], v[34:49]
	ds_read_b64_tr_b16 v[82:83], v151 offset:0x400
	ds_read_b64_tr_b16 v[84:85], v151 offset:0xc00
	v_mfma_f32_32x32x16_bf16 v[34:49], v[70:73], v[86:89], v[34:49]
	ds_read_b64_tr_b16 v[86:87], v151 offset:0x1400
	ds_read_b64_tr_b16 v[88:89], v151 offset:0x1c00
	s_waitcnt lgkmcnt(4)
	v_mfma_f32_32x32x16_bf16 v[34:49], v[74:77], v[90:93], v[34:49]
	ds_read_b64_tr_b16 v[90:91], v151 offset:0x2400
	ds_read_b64_tr_b16 v[92:93], v151 offset:0x2c00
	v_mfma_f32_32x32x16_bf16 v[34:49], v[78:81], v[94:97], v[34:49]
	ds_read_b64_tr_b16 v[94:95], v151 offset:0x3400
	ds_read_b64_tr_b16 v[96:97], v151 offset:0x3c00
	s_waitcnt lgkmcnt(4)
	v_mfma_f32_32x32x16_bf16 v[18:33], v[66:69], v[82:85], v[18:33]
	ds_read_b64_tr_b16 v[82:83], v151 offset:0x600
	ds_read_b64_tr_b16 v[84:85], v151 offset:0xe00
	v_mfma_f32_32x32x16_bf16 v[18:33], v[70:73], v[86:89], v[18:33]
	ds_read_b64_tr_b16 v[86:87], v151 offset:0x1600
	ds_read_b64_tr_b16 v[88:89], v151 offset:0x1e00
	s_waitcnt lgkmcnt(4)
	v_mfma_f32_32x32x16_bf16 v[18:33], v[74:77], v[90:93], v[18:33]
	ds_read_b64_tr_b16 v[90:91], v151 offset:0x2600
	ds_read_b64_tr_b16 v[92:93], v151 offset:0x2e00
	v_mfma_f32_32x32x16_bf16 v[18:33], v[78:81], v[94:97], v[18:33]
	ds_read_b64_tr_b16 v[94:95], v151 offset:0x3600
	ds_read_b64_tr_b16 v[96:97], v151 offset:0x3e00
	s_waitcnt lgkmcnt(4)
	v_mfma_f32_32x32x16_bf16 v[2:17], v[66:69], v[82:85], v[2:17]
	v_mfma_f32_32x32x16_bf16 v[2:17], v[70:73], v[86:89], v[2:17]
	s_waitcnt lgkmcnt(0)
	v_mfma_f32_32x32x16_bf16 v[2:17], v[74:77], v[90:93], v[2:17]
	v_mfma_f32_32x32x16_bf16 v[2:17], v[78:81], v[94:97], v[2:17]

.LBB0_645:
	v_add_u32_e32 v218, s11, v192
	v_add_u32_e32 v81, 1, v218
	v_mad_i64_i32 v[82:83], s[0:1], v81, s33, v[164:165]
	v_add_u32_e32 v86, 33, v218
	v_mad_i64_i32 v[84:85], s[0:1], v86, s33, v[164:165]
	global_load_dwordx4 v[146:149], v[82:83], off
	global_load_dwordx4 v[150:153], v[84:85], off
	v_mad_i64_i32 v[82:83], s[0:1], v81, s33, v[166:167]
	v_mad_i64_i32 v[84:85], s[0:1], v86, s33, v[166:167]
	global_load_dwordx4 v[154:157], v[82:83], off
	global_load_dwordx4 v[158:161], v[84:85], off
	ds_read_b128 v[228:231], v191 offset:49152
	ds_read_b128 v[232:235], v190 offset:49152
	ds_read_b128 v[236:239], v191 offset:57344
	ds_read_b128 v[248:251], v190 offset:57344
	ds_read_b128 v[252:255], v189 offset:49152
	s_waitcnt lgkmcnt(3)
	v_mfma_f32_32x32x16_bf16 v[98:113], v[228:231], v[142:145], 0
	ds_read_b128 v[228:231], v189 offset:57344
	v_mfma_f32_32x32x16_bf16 v[98:113], v[232:235], v[138:141], v[98:113]
	ds_read_b128 v[232:235], v188 offset:49152
	s_waitcnt lgkmcnt(3)
	v_mfma_f32_32x32x16_bf16 v[82:97], v[236:239], v[142:145], 0
	ds_read_b128 v[236:239], v188 offset:57344
	v_mfma_f32_32x32x16_bf16 v[82:97], v[248:251], v[138:141], v[82:97]
	ds_read_b128 v[248:251], v191 offset:49280
	s_waitcnt lgkmcnt(3)
	v_mfma_f32_32x32x16_bf16 v[98:113], v[252:255], v[134:137], v[98:113]
	ds_read_b128 v[252:255], v191 offset:57472
	v_mfma_f32_32x32x16_bf16 v[82:97], v[228:231], v[134:137], v[82:97]
	ds_read_b128 v[228:231], v190 offset:49280
	s_waitcnt lgkmcnt(3)
	v_mfma_f32_32x32x16_bf16 v[98:113], v[232:235], v[130:133], v[98:113]
	ds_read_b128 v[232:235], v190 offset:57472
	v_mfma_f32_32x32x16_bf16 v[82:97], v[236:239], v[130:133], v[82:97]
	ds_read_b128 v[236:239], v189 offset:49280
	s_waitcnt lgkmcnt(3)
	v_mfma_f32_32x32x16_bf16 v[98:113], v[248:251], v[126:129], v[98:113]
	ds_read_b128 v[248:251], v189 offset:57472
	v_mfma_f32_32x32x16_bf16 v[82:97], v[252:255], v[126:129], v[82:97]
	ds_read_b128 v[252:255], v188 offset:49280
	s_waitcnt lgkmcnt(3)
	v_mfma_f32_32x32x16_bf16 v[98:113], v[228:231], v[122:125], v[98:113]
	ds_read_b128 v[228:231], v188 offset:57472
	v_mfma_f32_32x32x16_bf16 v[82:97], v[232:235], v[122:125], v[82:97]
	s_waitcnt lgkmcnt(2)
	v_mfma_f32_32x32x16_bf16 v[98:113], v[236:239], v[118:121], v[98:113]
	v_mfma_f32_32x32x16_bf16 v[82:97], v[248:251], v[118:121], v[82:97]
	s_waitcnt lgkmcnt(0)
	v_mfma_f32_32x32x16_bf16 v[98:113], v[252:255], v[114:117], v[98:113]
	v_mfma_f32_32x32x16_bf16 v[82:97], v[228:231], v[114:117], v[82:97]
	v_exp_f32_e32 v226, v66
	v_add_f32_e32 v66, 0, v215
	v_add_f32_e32 v66, v217, v66
	v_add_f32_e32 v66, v213, v66
	v_add_f32_e32 v66, v216, v66
	v_add_f32_e32 v66, v211, v66
	v_add_f32_e32 v66, v214, v66
	v_add_f32_e32 v66, v210, v66
	v_add_f32_e32 v66, v212, v66
	v_add_f32_e32 v66, v207, v66
	v_add_f32_e32 v66, v209, v66
	v_add_f32_e32 v66, v205, v66
	v_add_f32_e32 v66, v208, v66
	v_exp_f32_e32 v80, v80
	v_add_f32_e32 v66, v203, v66
	v_exp_f32_e32 v1, v1
	v_add_f32_e32 v66, v206, v66
	v_exp_f32_e32 v78, v78
	v_add_f32_e32 v66, v202, v66
	v_exp_f32_e32 v79, v79
	v_add_f32_e32 v66, v204, v66
	v_exp_f32_e32 v76, v76
	v_add_f32_e32 v66, v80, v66
	v_exp_f32_e32 v77, v77
	v_add_f32_e32 v66, v1, v66
	v_exp_f32_e32 v81, v74
	v_add_f32_e32 v66, v78, v66
	v_exp_f32_e32 v219, v75
	v_add_f32_e32 v66, v79, v66
	v_exp_f32_e32 v220, v72
	v_add_f32_e32 v66, v76, v66
	v_exp_f32_e32 v221, v73
	v_add_f32_e32 v66, v77, v66
	v_exp_f32_e32 v222, v70
	v_add_f32_e32 v66, v81, v66
	v_exp_f32_e32 v223, v71
	v_add_f32_e32 v66, v219, v66
	v_exp_f32_e32 v224, v68
	v_add_f32_e32 v66, v220, v66
	v_exp_f32_e32 v225, v69
	v_add_f32_e32 v66, v221, v66
	v_add_f32_e32 v66, v222, v66
	v_exp_f32_e32 v227, v67
	v_add_f32_e32 v66, v223, v66
	v_add_f32_e32 v66, v224, v66
	v_add_f32_e32 v66, v225, v66
	v_add_f32_e32 v66, v226, v66
	v_add_f32_e32 v200, v227, v66
	v_mov_b32_e32 v201, v200
	v_cvt_pk_bf16_f32 v66, v215, v217
	v_cvt_pk_bf16_f32 v67, v213, v216
	v_cvt_pk_bf16_f32 v68, v211, v214
	v_cvt_pk_bf16_f32 v69, v210, v212
	v_cvt_pk_bf16_f32 v70, v207, v209
	v_cvt_pk_bf16_f32 v71, v205, v208
	v_cvt_pk_bf16_f32 v72, v203, v206
	v_cvt_pk_bf16_f32 v73, v202, v204
	v_cvt_pk_bf16_f32 v74, v80, v1
	v_cvt_pk_bf16_f32 v75, v78, v79
	v_cvt_pk_bf16_f32 v76, v76, v77
	v_cvt_pk_bf16_f32 v77, v81, v219
	v_cvt_pk_bf16_f32 v78, v220, v221
	v_cvt_pk_bf16_f32 v79, v222, v223
	v_cvt_pk_bf16_f32 v80, v224, v225
	v_cvt_pk_bf16_f32 v81, v226, v227
	s_nop 1
	v_permlane32_swap_b32_e32 v200, v201
	v_permlane32_swap_b32_e32 v66, v68
	v_permlane32_swap_b32_e32 v67, v69
	v_permlane32_swap_b32_e32 v70, v72
	v_permlane32_swap_b32_e32 v71, v73
	v_permlane32_swap_b32_e32 v74, v76
	v_permlane32_swap_b32_e32 v75, v77
	v_permlane32_swap_b32_e32 v78, v80
	v_permlane32_swap_b32_e32 v79, v81
	ds_read_b64_tr_b16 v[202:203], v183 offset:0
	ds_read_b64_tr_b16 v[204:205], v183 offset:0x800
	ds_read_b64_tr_b16 v[206:207], v183 offset:0x1000
	ds_read_b64_tr_b16 v[208:209], v183 offset:0x1800
	ds_read_b64_tr_b16 v[210:211], v183 offset:0x2000
	ds_read_b64_tr_b16 v[212:213], v183 offset:0x2800
	ds_read_b64_tr_b16 v[214:215], v183 offset:0x3000
	ds_read_b64_tr_b16 v[216:217], v183 offset:0x3800
	s_nop 0
	s_waitcnt lgkmcnt(4)
	v_mfma_f32_32x32x16_bf16 v[50:65], v[66:69], v[202:205], v[50:65]
	ds_read_b64_tr_b16 v[202:203], v183 offset:0x200
	ds_read_b64_tr_b16 v[204:205], v183 offset:0xa00
	v_mfma_f32_32x32x16_bf16 v[50:65], v[70:73], v[206:209], v[50:65]
	ds_read_b64_tr_b16 v[206:207], v183 offset:0x1200
	ds_read_b64_tr_b16 v[208:209], v183 offset:0x1a00
	s_waitcnt lgkmcnt(4)
	v_mfma_f32_32x32x16_bf16 v[50:65], v[74:77], v[210:213], v[50:65]
	ds_read_b64_tr_b16 v[210:211], v183 offset:0x2200
	ds_read_b64_tr_b16 v[212:213], v183 offset:0x2a00
	v_mfma_f32_32x32x16_bf16 v[50:65], v[78:81], v[214:217], v[50:65]
	ds_read_b64_tr_b16 v[214:215], v183 offset:0x3200
	ds_read_b64_tr_b16 v[216:217], v183 offset:0x3a00
	s_waitcnt lgkmcnt(4)
	v_mfma_f32_32x32x16_bf16 v[34:49], v[66:69], v[202:205], v[34:49]
	ds_read_b64_tr_b16 v[202:203], v183 offset:0x400
	ds_read_b64_tr_b16 v[204:205], v183 offset:0xc00
	v_mfma_f32_32x32x16_bf16 v[34:49], v[70:73], v[206:209], v[34:49]
	ds_read_b64_tr_b16 v[206:207], v183 offset:0x1400
	ds_read_b64_tr_b16 v[208:209], v183 offset:0x1c00
	s_waitcnt lgkmcnt(4)
	v_mfma_f32_32x32x16_bf16 v[34:49], v[74:77], v[210:213], v[34:49]
	ds_read_b64_tr_b16 v[210:211], v183 offset:0x2400
	ds_read_b64_tr_b16 v[212:213], v183 offset:0x2c00
	v_mfma_f32_32x32x16_bf16 v[34:49], v[78:81], v[214:217], v[34:49]
	ds_read_b64_tr_b16 v[214:215], v183 offset:0x3400
	ds_read_b64_tr_b16 v[216:217], v183 offset:0x3c00
	s_waitcnt lgkmcnt(4)
	v_mfma_f32_32x32x16_bf16 v[18:33], v[66:69], v[202:205], v[18:33]
	ds_read_b64_tr_b16 v[202:203], v183 offset:0x600
	ds_read_b64_tr_b16 v[204:205], v183 offset:0xe00
	v_mfma_f32_32x32x16_bf16 v[18:33], v[70:73], v[206:209], v[18:33]
	ds_read_b64_tr_b16 v[206:207], v183 offset:0x1600
	ds_read_b64_tr_b16 v[208:209], v183 offset:0x1e00
	s_waitcnt lgkmcnt(4)
	v_mfma_f32_32x32x16_bf16 v[18:33], v[74:77], v[210:213], v[18:33]
	ds_read_b64_tr_b16 v[210:211], v183 offset:0x2600
	ds_read_b64_tr_b16 v[212:213], v183 offset:0x2e00
	v_mfma_f32_32x32x16_bf16 v[18:33], v[78:81], v[214:217], v[18:33]
	ds_read_b64_tr_b16 v[214:215], v183 offset:0x3600
	ds_read_b64_tr_b16 v[216:217], v183 offset:0x3e00
	s_waitcnt lgkmcnt(4)
	v_mfma_f32_32x32x16_bf16 v[2:17], v[66:69], v[202:205], v[2:17]
	v_mfma_f32_32x32x16_bf16 v[2:17], v[70:73], v[206:209], v[2:17]
	s_waitcnt lgkmcnt(0)
	v_mfma_f32_32x32x16_bf16 v[2:17], v[74:77], v[210:213], v[2:17]
	v_mfma_f32_32x32x16_bf16 v[2:17], v[78:81], v[214:217], v[2:17]
	ds_read_b128 v[66:69], v198
	ds_read_b128 v[70:73], v198 offset:32
	ds_read_b128 v[202:205], v198 offset:128
	ds_read_b128 v[206:209], v198 offset:160
	ds_read_b128 v[76:79], v198 offset:64
	ds_read_b128 v[210:213], v198 offset:96
	ds_read_b128 v[214:217], v198 offset:192
	ds_read_b128 v[220:223], v198 offset:224
	s_waitcnt lgkmcnt(7)
	v_xor_b32_e32 v69, 0x80000000, v69
	s_waitcnt lgkmcnt(3)
	v_xor_b32_e32 v225, 0x80000000, v79
	v_xor_b32_e32 v224, 0x80000000, v78
	v_xor_b32_e32 v68, 0x80000000, v68
	v_xor_b32_e32 v73, 0x80000000, v73
	v_xor_b32_e32 v72, 0x80000000, v72
	s_waitcnt lgkmcnt(2)
	v_xor_b32_e32 v81, 0x80000000, v213
	v_xor_b32_e32 v80, 0x80000000, v212
	v_pk_fma_f32 v[74:75], v[110:111], s[12:13], v[210:211] op_sel_hi:[1,0,1] neg_lo:[0,0,1] neg_hi:[0,0,1]
	v_pk_fma_f32 v[78:79], v[106:107], s[12:13], v[76:77] op_sel_hi:[1,0,1] neg_lo:[0,0,1] neg_hi:[0,0,1]
	v_pk_fma_f32 v[102:103], v[102:103], s[12:13], v[70:71] op_sel_hi:[1,0,1] neg_lo:[0,0,1] neg_hi:[0,0,1]
	v_pk_fma_f32 v[106:107], v[108:109], s[12:13], v[224:225] op_sel_hi:[1,0,1]
	v_xor_b32_e32 v109, 0x80000000, v205
	v_xor_b32_e32 v108, 0x80000000, v204
	v_xor_b32_e32 v111, 0x80000000, v209
	v_xor_b32_e32 v110, 0x80000000, v208
	s_waitcnt lgkmcnt(1)
	v_xor_b32_e32 v77, 0x80000000, v217
	v_xor_b32_e32 v76, 0x80000000, v216
	s_waitcnt lgkmcnt(0)
	v_xor_b32_e32 v71, 0x80000000, v223
	v_xor_b32_e32 v70, 0x80000000, v222
	v_pk_fma_f32 v[80:81], v[112:113], s[12:13], v[80:81] op_sel_hi:[1,0,1]
	v_pk_fma_f32 v[104:105], v[104:105], s[12:13], v[72:73] op_sel_hi:[1,0,1]
	v_pk_fma_f32 v[100:101], v[100:101], s[12:13], v[68:69] op_sel_hi:[1,0,1]
	v_pk_fma_f32 v[98:99], v[98:99], s[12:13], v[66:67] op_sel_hi:[1,0,1] neg_lo:[0,0,1] neg_hi:[0,0,1]
	v_pk_fma_f32 v[66:67], v[94:95], s[12:13], v[220:221] op_sel_hi:[1,0,1] neg_lo:[0,0,1] neg_hi:[0,0,1]
	v_pk_fma_f32 v[68:69], v[90:91], s[12:13], v[214:215] op_sel_hi:[1,0,1] neg_lo:[0,0,1] neg_hi:[0,0,1]
	v_pk_fma_f32 v[72:73], v[86:87], s[12:13], v[206:207] op_sel_hi:[1,0,1] neg_lo:[0,0,1] neg_hi:[0,0,1]
	v_pk_fma_f32 v[70:71], v[96:97], s[12:13], v[70:71] op_sel_hi:[1,0,1]
	v_pk_fma_f32 v[76:77], v[92:93], s[12:13], v[76:77] op_sel_hi:[1,0,1]
	v_pk_fma_f32 v[86:87], v[88:89], s[12:13], v[110:111] op_sel_hi:[1,0,1]
	v_pk_fma_f32 v[84:85], v[84:85], s[12:13], v[108:109] op_sel_hi:[1,0,1]
	s_cmp_le_i32 s11, s27
	v_pk_fma_f32 v[82:83], v[82:83], s[12:13], v[202:203] op_sel_hi:[1,0,1] neg_lo:[0,0,1] neg_hi:[0,0,1]
	s_cbranch_scc1 .LBB0_647
	v_add_u32_e32 v1, 64, v199
	v_cmp_gt_i32_e64 s[92:93], 26, v1
	v_cmp_gt_i32_e64 s[94:95], 27, v1
	v_cmp_gt_i32_e64 s[90:91], 25, v1
	s_and_b64 s[92:93], s[94:95], s[92:93]
	v_cmp_gt_i32_e64 s[88:89], 24, v1
	s_and_b64 s[90:91], s[92:93], s[90:91]
	v_cmp_gt_i32_e64 s[86:87], 19, v1
	s_and_b64 s[88:89], s[90:91], s[88:89]
	v_cmp_gt_i32_e64 s[84:85], 18, v1
	s_and_b64 s[86:87], s[88:89], s[86:87]
	v_cmp_gt_i32_e64 s[82:83], 17, v1
	s_and_b64 s[84:85], s[86:87], s[84:85]
	v_cmp_gt_i32_e64 s[80:81], 16, v1
	s_and_b64 s[82:83], s[84:85], s[82:83]
	v_cmp_gt_i32_e64 s[78:79], 11, v1
	s_and_b64 s[80:81], s[82:83], s[80:81]
	v_cmp_gt_i32_e64 s[76:77], 10, v1
	s_and_b64 s[78:79], s[80:81], s[78:79]
	v_cmp_gt_i32_e64 s[74:75], 9, v1
	s_and_b64 s[76:77], s[78:79], s[76:77]
	v_cmp_gt_i32_e64 s[72:73], 8, v1
	s_and_b64 s[74:75], s[76:77], s[74:75]
	v_cmp_gt_i32_e64 s[70:71], 3, v1
	s_and_b64 s[72:73], s[74:75], s[72:73]
	v_cmp_gt_i32_e64 s[68:69], 2, v1
	s_and_b64 s[70:71], s[72:73], s[70:71]
	v_cmp_gt_i32_e64 s[2:3], 1, v1
	s_and_b64 s[68:69], s[70:71], s[68:69]
	v_cmp_gt_i32_e64 s[0:1], 0, v1
	s_and_b64 s[2:3], s[68:69], s[2:3]
	s_and_b64 s[0:1], s[2:3], s[0:1]
	v_cmp_gt_i32_e64 s[66:67], 58, v1
	v_cndmask_b32_e64 v98, v98, v175, s[0:1]
	v_cmp_gt_i32_e64 s[0:1], 59, v1
	v_cmp_gt_i32_e64 s[64:65], 57, v1
	v_cmp_gt_i32_e64 s[62:63], 56, v1
	v_cndmask_b32_e64 v71, v71, v175, s[0:1]
	s_and_b64 s[0:1], s[0:1], s[66:67]
	v_cndmask_b32_e64 v70, v70, v175, s[0:1]
	s_and_b64 s[0:1], s[0:1], s[64:65]
	v_cmp_gt_i32_e64 s[60:61], 51, v1
	v_cndmask_b32_e64 v67, v67, v175, s[0:1]
	s_and_b64 s[0:1], s[0:1], s[62:63]
	v_cmp_gt_i32_e64 s[58:59], 50, v1
	v_cndmask_b32_e64 v66, v66, v175, s[0:1]
	s_and_b64 s[0:1], s[0:1], s[60:61]
	v_cmp_gt_i32_e64 s[56:57], 49, v1
	v_cndmask_b32_e64 v77, v77, v175, s[0:1]
	s_and_b64 s[0:1], s[0:1], s[58:59]
	v_cmp_gt_i32_e64 s[54:55], 48, v1
	v_cndmask_b32_e64 v76, v76, v175, s[0:1]
	s_and_b64 s[0:1], s[0:1], s[56:57]
	v_cmp_gt_i32_e64 s[52:53], 43, v1
	v_cndmask_b32_e64 v69, v69, v175, s[0:1]
	s_and_b64 s[0:1], s[0:1], s[54:55]
	v_cmp_gt_i32_e64 s[50:51], 42, v1
	v_cndmask_b32_e64 v68, v68, v175, s[0:1]
	s_and_b64 s[0:1], s[0:1], s[52:53]
	v_cmp_gt_i32_e64 s[48:49], 41, v1
	v_cndmask_b32_e64 v87, v87, v175, s[0:1]
	s_and_b64 s[0:1], s[0:1], s[50:51]
	v_cmp_gt_i32_e64 s[46:47], 40, v1
	v_cndmask_b32_e64 v86, v86, v175, s[0:1]
	s_and_b64 s[0:1], s[0:1], s[48:49]
	v_cmp_gt_i32_e64 s[44:45], 35, v1
	v_cndmask_b32_e64 v73, v73, v175, s[0:1]
	s_and_b64 s[0:1], s[0:1], s[46:47]
	v_cmp_gt_i32_e64 s[42:43], 34, v1
	v_cndmask_b32_e64 v72, v72, v175, s[0:1]
	s_and_b64 s[0:1], s[0:1], s[44:45]
	v_cmp_gt_i32_e64 s[40:41], 33, v1
	v_cndmask_b32_e64 v85, v85, v175, s[0:1]
	s_and_b64 s[0:1], s[0:1], s[42:43]
	v_cmp_gt_i32_e32 vcc, 32, v1
	v_cndmask_b32_e64 v84, v84, v175, s[0:1]
	s_and_b64 s[0:1], s[0:1], s[40:41]
	v_cndmask_b32_e64 v74, v74, v175, s[88:89]
	v_readlane_b32 s88, v242, 2
	s_and_b64 vcc, s[0:1], vcc
	v_cndmask_b32_e64 v81, v81, v175, s[94:95]
	v_cndmask_b32_e64 v80, v80, v175, s[92:93]
	s_movk_i32 s93, 0x6018
	s_mov_b32 s92, 0xf800000
	v_cndmask_b32_e64 v75, v75, v175, s[90:91]
	s_mov_b64 s[90:91], s[16:17]
	v_readlane_b32 s89, v242, 3
	v_cndmask_b32_e64 v107, v107, v175, s[86:87]
	v_readlane_b32 s86, v242, 0
	v_cndmask_b32_e64 v106, v106, v175, s[84:85]
	v_cndmask_b32_e64 v79, v79, v175, s[82:83]
	s_movk_i32 s83, 0x6000
	v_cndmask_b32_e64 v78, v78, v175, s[80:81]
	v_cndmask_b32_e64 v105, v105, v175, s[78:79]
	v_cndmask_b32_e64 v104, v104, v175, s[76:77]
	v_cndmask_b32_e64 v103, v103, v175, s[74:75]
	v_cndmask_b32_e64 v102, v102, v175, s[72:73]
	v_cndmask_b32_e64 v101, v101, v175, s[70:71]
	v_cndmask_b32_e64 v100, v100, v175, s[68:69]
	v_cndmask_b32_e64 v99, v99, v175, s[2:3]
	s_mov_b32 s56, s30
	v_cndmask_b32_e64 v83, v83, v175, s[0:1]
	v_cndmask_b32_e32 v82, v82, v175, vcc
	v_readlane_b32 s87, v242, 1

.LBB0_653:
	v_sub_f32_e32 v104, v82, v1
	v_sub_f32_e32 v105, v83, v1
	v_sub_f32_e32 v208, v84, v1
	v_sub_f32_e32 v209, v85, v1
	v_sub_f32_e32 v210, v72, v1
	v_sub_f32_e32 v211, v73, v1
	v_sub_f32_e32 v212, v86, v1
	v_sub_f32_e32 v213, v87, v1
	v_sub_f32_e32 v214, v68, v1
	v_sub_f32_e32 v215, v69, v1
	v_sub_f32_e32 v216, v76, v1
	v_sub_f32_e32 v217, v77, v1
	v_sub_f32_e32 v218, v66, v1
	v_sub_f32_e32 v219, v67, v1
	v_sub_f32_e32 v220, v70, v1
	v_sub_f32_e32 v221, v71, v1
	ds_read_b128 v[228:231], v191 offset:32768
	ds_read_b128 v[232:235], v190 offset:32768
	ds_read_b128 v[236:239], v191 offset:40960
	ds_read_b128 v[248:251], v190 offset:40960
	ds_read_b128 v[252:255], v189 offset:32768
	s_waitcnt lgkmcnt(3)
	v_mfma_f32_32x32x16_bf16 v[82:97], v[228:231], v[142:145], 0
	ds_read_b128 v[228:231], v189 offset:40960
	v_mfma_f32_32x32x16_bf16 v[82:97], v[232:235], v[138:141], v[82:97]
	ds_read_b128 v[232:235], v188 offset:32768
	s_waitcnt lgkmcnt(3)
	v_mfma_f32_32x32x16_bf16 v[66:81], v[236:239], v[142:145], 0
	ds_read_b128 v[236:239], v188 offset:40960
	v_mfma_f32_32x32x16_bf16 v[66:81], v[248:251], v[138:141], v[66:81]
	ds_read_b128 v[248:251], v191 offset:32896
	s_waitcnt lgkmcnt(3)
	v_mfma_f32_32x32x16_bf16 v[82:97], v[252:255], v[134:137], v[82:97]
	ds_read_b128 v[252:255], v191 offset:41088
	v_mfma_f32_32x32x16_bf16 v[66:81], v[228:231], v[134:137], v[66:81]
	ds_read_b128 v[228:231], v190 offset:32896
	s_waitcnt lgkmcnt(3)
	v_mfma_f32_32x32x16_bf16 v[82:97], v[232:235], v[130:133], v[82:97]
	ds_read_b128 v[232:235], v190 offset:41088
	v_mfma_f32_32x32x16_bf16 v[66:81], v[236:239], v[130:133], v[66:81]
	ds_read_b128 v[236:239], v189 offset:32896
	s_waitcnt lgkmcnt(3)
	v_mfma_f32_32x32x16_bf16 v[82:97], v[248:251], v[126:129], v[82:97]
	ds_read_b128 v[248:251], v189 offset:41088
	v_mfma_f32_32x32x16_bf16 v[66:81], v[252:255], v[126:129], v[66:81]
	ds_read_b128 v[252:255], v188 offset:32896
	s_waitcnt lgkmcnt(3)
	v_mfma_f32_32x32x16_bf16 v[82:97], v[228:231], v[122:125], v[82:97]
	ds_read_b128 v[228:231], v188 offset:41088
	v_mfma_f32_32x32x16_bf16 v[66:81], v[232:235], v[122:125], v[66:81]
	s_waitcnt lgkmcnt(2)
	v_mfma_f32_32x32x16_bf16 v[82:97], v[236:239], v[118:121], v[82:97]
	v_mfma_f32_32x32x16_bf16 v[66:81], v[248:251], v[118:121], v[66:81]
	s_waitcnt lgkmcnt(0)
	v_mfma_f32_32x32x16_bf16 v[82:97], v[252:255], v[114:117], v[82:97]
	v_mfma_f32_32x32x16_bf16 v[66:81], v[228:231], v[114:117], v[66:81]
	v_exp_f32_e32 v222, v104
	v_add_f32_e32 v104, 0, v196
	v_add_f32_e32 v104, v203, v104
	v_add_f32_e32 v104, v112, v104
	v_add_f32_e32 v104, v202, v104
	v_add_f32_e32 v104, v110, v104
	v_add_f32_e32 v104, v113, v104
	v_add_f32_e32 v104, v109, v104
	v_add_f32_e32 v104, v111, v104
	v_add_f32_e32 v104, v103, v104
	v_add_f32_e32 v104, v107, v104
	v_add_f32_e32 v104, v101, v104
	v_add_f32_e32 v104, v106, v104
	v_add_f32_e32 v104, v99, v104
	v_exp_f32_e32 v223, v105
	v_add_f32_e32 v104, v102, v104
	v_exp_f32_e32 v208, v208
	v_add_f32_e32 v104, v98, v104
	v_exp_f32_e32 v209, v209
	v_add_f32_e32 v104, v100, v104
	v_exp_f32_e32 v210, v210
	v_add_f32_e32 v104, v222, v104
	v_exp_f32_e32 v211, v211
	v_add_f32_e32 v104, v223, v104
	v_exp_f32_e32 v212, v212
	v_add_f32_e32 v104, v208, v104
	v_exp_f32_e32 v213, v213
	v_add_f32_e32 v104, v209, v104
	v_exp_f32_e32 v214, v214
	v_add_f32_e32 v104, v210, v104
	v_exp_f32_e32 v215, v215
	v_add_f32_e32 v104, v211, v104
	v_exp_f32_e32 v216, v216
	v_add_f32_e32 v104, v212, v104
	v_exp_f32_e32 v217, v217
	v_add_f32_e32 v104, v213, v104
	v_exp_f32_e32 v218, v218
	v_add_f32_e32 v104, v214, v104
	v_exp_f32_e32 v219, v219
	v_add_f32_e32 v104, v215, v104
	v_exp_f32_e32 v220, v220
	v_add_f32_e32 v104, v216, v104
	v_exp_f32_e32 v221, v221
	v_add_f32_e32 v104, v217, v104
	v_add_f32_e32 v104, v218, v104
	v_add_f32_e32 v104, v219, v104
	v_add_f32_e32 v104, v220, v104
	v_add_f32_e32 v104, v221, v104
	v_mov_b32_e32 v105, v104
	v_cvt_pk_bf16_f32 v204, v196, v203
	v_cvt_pk_bf16_f32 v205, v112, v202
	v_cvt_pk_bf16_f32 v206, v110, v113
	v_cvt_pk_bf16_f32 v207, v109, v111
	v_cvt_pk_bf16_f32 v110, v103, v107
	v_cvt_pk_bf16_f32 v111, v101, v106
	v_cvt_pk_bf16_f32 v112, v99, v102
	v_cvt_pk_bf16_f32 v113, v98, v100
	v_cvt_pk_bf16_f32 v98, v222, v223
	v_cvt_pk_bf16_f32 v99, v208, v209
	v_cvt_pk_bf16_f32 v100, v210, v211
	v_cvt_pk_bf16_f32 v101, v212, v213
	s_nop 1
	v_permlane32_swap_b32_e32 v104, v105
	v_permlane32_swap_b32_e32 v98, v100
	v_permlane32_swap_b32_e32 v99, v101
	v_cvt_pk_bf16_f32 v208, v214, v215
	v_cvt_pk_bf16_f32 v209, v216, v217
	v_cvt_pk_bf16_f32 v210, v218, v219
	v_cvt_pk_bf16_f32 v211, v220, v221
	v_permlane32_swap_b32_e32 v204, v206
	v_permlane32_swap_b32_e32 v205, v207
	v_permlane32_swap_b32_e32 v110, v112
	v_permlane32_swap_b32_e32 v111, v113
	v_permlane32_swap_b32_e32 v208, v210
	v_permlane32_swap_b32_e32 v209, v211
	ds_read_b64_tr_b16 v[212:213], v183 offset:0x4000
	ds_read_b64_tr_b16 v[214:215], v183 offset:0x4800
	ds_read_b64_tr_b16 v[216:217], v183 offset:0x5000
	ds_read_b64_tr_b16 v[218:219], v183 offset:0x5800
	ds_read_b64_tr_b16 v[220:221], v183 offset:0x6000
	ds_read_b64_tr_b16 v[222:223], v183 offset:0x6800
	ds_read_b64_tr_b16 v[224:225], v183 offset:0x7000
	ds_read_b64_tr_b16 v[226:227], v183 offset:0x7800
	s_nop 0
	s_waitcnt lgkmcnt(4)
	v_mfma_f32_32x32x16_bf16 v[50:65], v[204:207], v[212:215], v[50:65]
	ds_read_b64_tr_b16 v[212:213], v183 offset:0x4200
	ds_read_b64_tr_b16 v[214:215], v183 offset:0x4a00
	v_mfma_f32_32x32x16_bf16 v[50:65], v[110:113], v[216:219], v[50:65]
	ds_read_b64_tr_b16 v[216:217], v183 offset:0x5200
	ds_read_b64_tr_b16 v[218:219], v183 offset:0x5a00
	s_waitcnt lgkmcnt(4)
	v_mfma_f32_32x32x16_bf16 v[50:65], v[98:101], v[220:223], v[50:65]
	ds_read_b64_tr_b16 v[220:221], v183 offset:0x6200
	ds_read_b64_tr_b16 v[222:223], v183 offset:0x6a00
	v_mfma_f32_32x32x16_bf16 v[50:65], v[208:211], v[224:227], v[50:65]
	ds_read_b64_tr_b16 v[224:225], v183 offset:0x7200
	ds_read_b64_tr_b16 v[226:227], v183 offset:0x7a00
	s_waitcnt lgkmcnt(4)
	v_mfma_f32_32x32x16_bf16 v[34:49], v[204:207], v[212:215], v[34:49]
	ds_read_b64_tr_b16 v[212:213], v183 offset:0x4400
	ds_read_b64_tr_b16 v[214:215], v183 offset:0x4c00
	v_mfma_f32_32x32x16_bf16 v[34:49], v[110:113], v[216:219], v[34:49]
	ds_read_b64_tr_b16 v[216:217], v183 offset:0x5400
	ds_read_b64_tr_b16 v[218:219], v183 offset:0x5c00
	s_waitcnt lgkmcnt(4)
	v_mfma_f32_32x32x16_bf16 v[34:49], v[98:101], v[220:223], v[34:49]
	ds_read_b64_tr_b16 v[220:221], v183 offset:0x6400
	ds_read_b64_tr_b16 v[222:223], v183 offset:0x6c00
	v_mfma_f32_32x32x16_bf16 v[34:49], v[208:211], v[224:227], v[34:49]
	ds_read_b64_tr_b16 v[224:225], v183 offset:0x7400
	ds_read_b64_tr_b16 v[226:227], v183 offset:0x7c00
	s_waitcnt lgkmcnt(4)
	v_mfma_f32_32x32x16_bf16 v[18:33], v[204:207], v[212:215], v[18:33]
	ds_read_b64_tr_b16 v[212:213], v183 offset:0x4600
	ds_read_b64_tr_b16 v[214:215], v183 offset:0x4e00
	v_mfma_f32_32x32x16_bf16 v[18:33], v[110:113], v[216:219], v[18:33]
	ds_read_b64_tr_b16 v[216:217], v183 offset:0x5600
	ds_read_b64_tr_b16 v[218:219], v183 offset:0x5e00
	s_waitcnt lgkmcnt(4)
	v_mfma_f32_32x32x16_bf16 v[18:33], v[98:101], v[220:223], v[18:33]
	ds_read_b64_tr_b16 v[220:221], v183 offset:0x6600
	ds_read_b64_tr_b16 v[222:223], v183 offset:0x6e00
	v_mfma_f32_32x32x16_bf16 v[18:33], v[208:211], v[224:227], v[18:33]
	ds_read_b64_tr_b16 v[224:225], v183 offset:0x7600
	ds_read_b64_tr_b16 v[226:227], v183 offset:0x7e00
	s_waitcnt lgkmcnt(4)
	v_mfma_f32_32x32x16_bf16 v[2:17], v[204:207], v[212:215], v[2:17]
	v_mfma_f32_32x32x16_bf16 v[2:17], v[110:113], v[216:219], v[2:17]
	s_waitcnt lgkmcnt(0)
	v_mfma_f32_32x32x16_bf16 v[2:17], v[98:101], v[220:223], v[2:17]
	v_mfma_f32_32x32x16_bf16 v[2:17], v[208:211], v[224:227], v[2:17]
	ds_read_b128 v[100:103], v198 offset:256
	ds_read_b128 v[110:113], v198 offset:288
	ds_read_b128 v[202:205], v198 offset:384
	ds_read_b128 v[206:209], v198 offset:416
	ds_read_b128 v[210:213], v198 offset:320
	ds_read_b128 v[214:217], v198 offset:352
	ds_read_b128 v[218:221], v198 offset:448
	ds_read_b128 v[222:225], v198 offset:480
	s_waitcnt lgkmcnt(7)
	v_xor_b32_e32 v103, 0x80000000, v103
	v_xor_b32_e32 v102, 0x80000000, v102
	s_waitcnt lgkmcnt(6)
	v_xor_b32_e32 v107, 0x80000000, v113
	v_xor_b32_e32 v106, 0x80000000, v112
	s_waitcnt lgkmcnt(3)
	v_xor_b32_e32 v113, 0x80000000, v213
	v_xor_b32_e32 v112, 0x80000000, v212
	s_waitcnt lgkmcnt(2)
	v_xor_b32_e32 v213, 0x80000000, v217
	v_xor_b32_e32 v212, 0x80000000, v216
	v_pk_fma_f32 v[98:99], v[86:87], s[12:13], v[110:111] op_sel_hi:[1,0,1] neg_lo:[0,0,1] neg_hi:[0,0,1]
	v_pk_fma_f32 v[86:87], v[96:97], s[12:13], v[212:213] op_sel_hi:[1,0,1]
	v_pk_fma_f32 v[88:89], v[88:89], s[12:13], v[106:107] op_sel_hi:[1,0,1]
	v_pk_fma_f32 v[84:85], v[84:85], s[12:13], v[102:103] op_sel_hi:[1,0,1]
	v_pk_fma_f32 v[96:97], v[82:83], s[12:13], v[100:101] op_sel_hi:[1,0,1] neg_lo:[0,0,1] neg_hi:[0,0,1]
	v_xor_b32_e32 v103, 0x80000000, v205
	v_xor_b32_e32 v102, 0x80000000, v204
	v_xor_b32_e32 v101, 0x80000000, v209
	v_xor_b32_e32 v100, 0x80000000, v208
	s_waitcnt lgkmcnt(1)
	v_xor_b32_e32 v107, 0x80000000, v221
	v_xor_b32_e32 v106, 0x80000000, v220
	s_waitcnt lgkmcnt(0)
	v_xor_b32_e32 v111, 0x80000000, v225
	v_xor_b32_e32 v110, 0x80000000, v224
	s_add_i32 s0, s11, 64
	v_pk_fma_f32 v[94:95], v[94:95], s[12:13], v[214:215] op_sel_hi:[1,0,1] neg_lo:[0,0,1] neg_hi:[0,0,1]
	v_pk_fma_f32 v[90:91], v[90:91], s[12:13], v[210:211] op_sel_hi:[1,0,1] neg_lo:[0,0,1] neg_hi:[0,0,1]
	v_pk_fma_f32 v[92:93], v[92:93], s[12:13], v[112:113] op_sel_hi:[1,0,1]
	v_pk_fma_f32 v[82:83], v[78:79], s[12:13], v[222:223] op_sel_hi:[1,0,1] neg_lo:[0,0,1] neg_hi:[0,0,1]
	v_pk_fma_f32 v[74:75], v[74:75], s[12:13], v[218:219] op_sel_hi:[1,0,1] neg_lo:[0,0,1] neg_hi:[0,0,1]
	v_pk_fma_f32 v[78:79], v[70:71], s[12:13], v[206:207] op_sel_hi:[1,0,1] neg_lo:[0,0,1] neg_hi:[0,0,1]
	v_pk_fma_f32 v[70:71], v[80:81], s[12:13], v[110:111] op_sel_hi:[1,0,1]
	v_pk_fma_f32 v[76:77], v[76:77], s[12:13], v[106:107] op_sel_hi:[1,0,1]
	v_pk_fma_f32 v[100:101], v[72:73], s[12:13], v[100:101] op_sel_hi:[1,0,1]
	v_pk_fma_f32 v[102:103], v[68:69], s[12:13], v[102:103] op_sel_hi:[1,0,1]
	s_cmp_le_i32 s0, s27
	v_pk_fma_f32 v[80:81], v[66:67], s[12:13], v[202:203] op_sel_hi:[1,0,1] neg_lo:[0,0,1] neg_hi:[0,0,1]
	s_cbranch_scc1 .LBB0_655
	v_cmp_gt_i32_e64 s[92:93], 26, v199
	v_cmp_gt_i32_e64 s[94:95], 27, v199
	v_cmp_gt_i32_e64 s[90:91], 25, v199
	s_and_b64 s[92:93], s[94:95], s[92:93]
	v_cmp_gt_i32_e64 s[88:89], 24, v199
	s_and_b64 s[90:91], s[92:93], s[90:91]
	v_cmp_gt_i32_e64 s[86:87], 19, v199
	s_and_b64 s[88:89], s[90:91], s[88:89]
	v_cmp_gt_i32_e64 s[84:85], 18, v199
	s_and_b64 s[86:87], s[88:89], s[86:87]
	v_cmp_gt_i32_e64 s[82:83], 17, v199
	s_and_b64 s[84:85], s[86:87], s[84:85]
	v_cmp_gt_i32_e64 s[80:81], 16, v199
	s_and_b64 s[82:83], s[84:85], s[82:83]
	v_cmp_gt_i32_e64 s[78:79], 11, v199
	s_and_b64 s[80:81], s[82:83], s[80:81]
	v_cmp_gt_i32_e64 s[76:77], 10, v199
	s_and_b64 s[78:79], s[80:81], s[78:79]
	v_cmp_gt_i32_e64 s[74:75], 9, v199
	s_and_b64 s[76:77], s[78:79], s[76:77]
	v_cmp_gt_i32_e64 s[72:73], 8, v199
	s_and_b64 s[74:75], s[76:77], s[74:75]
	v_cmp_gt_i32_e64 s[70:71], 3, v199
	s_and_b64 s[72:73], s[74:75], s[72:73]
	v_cmp_gt_i32_e64 s[68:69], 2, v199
	s_and_b64 s[70:71], s[72:73], s[70:71]
	v_cmp_gt_i32_e64 s[2:3], 1, v199
	s_and_b64 s[68:69], s[70:71], s[68:69]
	v_cmp_gt_i32_e64 s[0:1], 0, v199
	s_and_b64 s[2:3], s[68:69], s[2:3]
	s_and_b64 s[0:1], s[2:3], s[0:1]
	v_cmp_gt_i32_e64 s[66:67], 58, v199
	v_cndmask_b32_e64 v96, v96, v175, s[0:1]
	v_cmp_gt_i32_e64 s[0:1], 59, v199
	v_cmp_gt_i32_e64 s[64:65], 57, v199
	v_cmp_gt_i32_e64 s[62:63], 56, v199
	v_cndmask_b32_e64 v71, v71, v175, s[0:1]
	s_and_b64 s[0:1], s[0:1], s[66:67]
	v_cndmask_b32_e64 v70, v70, v175, s[0:1]
	s_and_b64 s[0:1], s[0:1], s[64:65]
	v_cmp_gt_i32_e64 s[60:61], 51, v199
	v_cndmask_b32_e64 v83, v83, v175, s[0:1]
	s_and_b64 s[0:1], s[0:1], s[62:63]
	v_cmp_gt_i32_e64 s[58:59], 50, v199
	v_cndmask_b32_e64 v82, v82, v175, s[0:1]
	s_and_b64 s[0:1], s[0:1], s[60:61]
	v_cmp_gt_i32_e64 s[56:57], 49, v199
	v_cndmask_b32_e64 v77, v77, v175, s[0:1]
	s_and_b64 s[0:1], s[0:1], s[58:59]
	v_cmp_gt_i32_e64 s[54:55], 48, v199
	v_cndmask_b32_e64 v76, v76, v175, s[0:1]
	s_and_b64 s[0:1], s[0:1], s[56:57]
	v_cmp_gt_i32_e64 s[52:53], 43, v199
	v_cndmask_b32_e64 v75, v75, v175, s[0:1]
	s_and_b64 s[0:1], s[0:1], s[54:55]
	v_cmp_gt_i32_e64 s[50:51], 42, v199
	v_cndmask_b32_e64 v74, v74, v175, s[0:1]
	s_and_b64 s[0:1], s[0:1], s[52:53]
	v_cmp_gt_i32_e64 s[48:49], 41, v199
	v_cndmask_b32_e64 v101, v101, v175, s[0:1]
	s_and_b64 s[0:1], s[0:1], s[50:51]
	v_cmp_gt_i32_e64 s[46:47], 40, v199
	v_cndmask_b32_e64 v100, v100, v175, s[0:1]
	s_and_b64 s[0:1], s[0:1], s[48:49]
	v_cmp_gt_i32_e64 s[44:45], 35, v199
	v_cndmask_b32_e64 v79, v79, v175, s[0:1]
	s_and_b64 s[0:1], s[0:1], s[46:47]
	v_cmp_gt_i32_e64 s[42:43], 34, v199
	v_cndmask_b32_e64 v78, v78, v175, s[0:1]
	s_and_b64 s[0:1], s[0:1], s[44:45]
	v_cmp_gt_i32_e64 s[40:41], 33, v199
	v_cndmask_b32_e64 v103, v103, v175, s[0:1]
	s_and_b64 s[0:1], s[0:1], s[42:43]
	v_cmp_gt_i32_e32 vcc, 32, v199
	v_cndmask_b32_e64 v102, v102, v175, s[0:1]
	s_and_b64 s[0:1], s[0:1], s[40:41]
	v_cndmask_b32_e64 v94, v94, v175, s[88:89]
	v_readlane_b32 s88, v242, 2
	s_and_b64 vcc, s[0:1], vcc
	v_cndmask_b32_e64 v87, v87, v175, s[94:95]
	v_cndmask_b32_e64 v86, v86, v175, s[92:93]
	s_movk_i32 s93, 0x6018
	s_mov_b32 s92, 0xf800000
	v_cndmask_b32_e64 v95, v95, v175, s[90:91]
	s_mov_b64 s[90:91], s[16:17]
	v_readlane_b32 s89, v242, 3
	v_cndmask_b32_e64 v93, v93, v175, s[86:87]
	v_readlane_b32 s86, v242, 0
	v_cndmask_b32_e64 v92, v92, v175, s[84:85]
	v_cndmask_b32_e64 v91, v91, v175, s[82:83]
	s_movk_i32 s83, 0x6000
	v_cndmask_b32_e64 v90, v90, v175, s[80:81]
	v_cndmask_b32_e64 v89, v89, v175, s[78:79]
	v_cndmask_b32_e64 v88, v88, v175, s[76:77]
	v_cndmask_b32_e64 v99, v99, v175, s[74:75]
	v_cndmask_b32_e64 v98, v98, v175, s[72:73]
	v_cndmask_b32_e64 v85, v85, v175, s[70:71]
	v_cndmask_b32_e64 v84, v84, v175, s[68:69]
	v_cndmask_b32_e64 v97, v97, v175, s[2:3]
	s_mov_b32 s56, s30
	v_cndmask_b32_e64 v81, v81, v175, s[0:1]
	v_cndmask_b32_e32 v80, v80, v175, vcc
	v_readlane_b32 s87, v242, 1

.LBB0_664:
	ds_read_b128 v[82:85], v191 offset:49152
	ds_read_b128 v[86:89], v191 offset:57344
	s_waitcnt lgkmcnt(1)
	v_mfma_f32_32x32x16_bf16 v[98:113], v[82:85], v[142:145], 0
	s_waitcnt lgkmcnt(0)
	v_mfma_f32_32x32x16_bf16 v[82:97], v[86:89], v[142:145], 0
	ds_read_b128 v[142:145], v190 offset:49152
	s_waitcnt vmcnt(2)
	ds_read_b128 v[148:151], v190 offset:57344
	s_waitcnt lgkmcnt(1)
	v_mfma_f32_32x32x16_bf16 v[98:113], v[142:145], v[138:141], v[98:113]
	s_waitcnt lgkmcnt(0)
	v_mfma_f32_32x32x16_bf16 v[82:97], v[148:151], v[138:141], v[82:97]
	ds_read_b128 v[138:141], v189 offset:49152
	ds_read_b128 v[142:145], v189 offset:57344
	s_waitcnt lgkmcnt(1)
	v_mfma_f32_32x32x16_bf16 v[98:113], v[138:141], v[134:137], v[98:113]
	s_waitcnt lgkmcnt(0)
	v_mfma_f32_32x32x16_bf16 v[82:97], v[142:145], v[134:137], v[82:97]
	ds_read_b128 v[134:137], v188 offset:49152
	ds_read_b128 v[138:141], v188 offset:57344
	s_waitcnt lgkmcnt(1)
	v_mfma_f32_32x32x16_bf16 v[98:113], v[134:137], v[130:133], v[98:113]
	s_waitcnt lgkmcnt(0)
	v_mfma_f32_32x32x16_bf16 v[82:97], v[138:141], v[130:133], v[82:97]
	ds_read_b128 v[130:133], v191 offset:49280
	ds_read_b128 v[134:137], v191 offset:57472
	s_waitcnt lgkmcnt(1)
	v_mfma_f32_32x32x16_bf16 v[98:113], v[130:133], v[126:129], v[98:113]
	s_waitcnt lgkmcnt(0)
	v_mfma_f32_32x32x16_bf16 v[82:97], v[134:137], v[126:129], v[82:97]
	ds_read_b128 v[126:129], v190 offset:49280
	ds_read_b128 v[130:133], v190 offset:57472
	s_waitcnt lgkmcnt(1)
	v_mfma_f32_32x32x16_bf16 v[98:113], v[126:129], v[122:125], v[98:113]
	s_waitcnt lgkmcnt(0)
	v_mfma_f32_32x32x16_bf16 v[82:97], v[130:133], v[122:125], v[82:97]
	ds_read_b128 v[122:125], v189 offset:49280
	ds_read_b128 v[126:129], v189 offset:57472
	s_waitcnt lgkmcnt(1)
	v_mfma_f32_32x32x16_bf16 v[98:113], v[122:125], v[118:121], v[98:113]
	s_waitcnt lgkmcnt(0)
	v_mfma_f32_32x32x16_bf16 v[82:97], v[126:129], v[118:121], v[82:97]
	ds_read_b128 v[118:121], v188 offset:49280
	ds_read_b128 v[122:125], v188 offset:57472
	s_waitcnt lgkmcnt(1)
	v_mfma_f32_32x32x16_bf16 v[98:113], v[118:121], v[114:117], v[98:113]
	s_waitcnt lgkmcnt(0)
	v_mfma_f32_32x32x16_bf16 v[82:97], v[122:125], v[114:117], v[82:97]
	v_exp_f32_e32 v81, v1
	v_add_f32_e32 v1, 0, v215
	v_add_f32_e32 v1, v217, v1
	v_add_f32_e32 v1, v213, v1
	v_add_f32_e32 v1, v216, v1
	v_add_f32_e32 v1, v211, v1
	v_add_f32_e32 v1, v214, v1
	v_add_f32_e32 v1, v210, v1
	v_add_f32_e32 v1, v212, v1
	v_add_f32_e32 v1, v207, v1
	v_add_f32_e32 v1, v209, v1
	v_add_f32_e32 v1, v205, v1
	v_add_f32_e32 v1, v208, v1
	v_exp_f32_e32 v80, v80
	v_add_f32_e32 v1, v203, v1
	v_add_f32_e32 v1, v206, v1
	v_exp_f32_e32 v78, v78
	v_add_f32_e32 v1, v202, v1
	v_exp_f32_e32 v79, v79
	v_add_f32_e32 v1, v204, v1
	v_exp_f32_e32 v76, v76
	v_add_f32_e32 v1, v80, v1
	v_exp_f32_e32 v77, v77
	v_add_f32_e32 v1, v81, v1
	v_exp_f32_e32 v115, v74
	v_add_f32_e32 v1, v78, v1
	v_exp_f32_e32 v116, v75
	v_add_f32_e32 v1, v79, v1
	v_exp_f32_e32 v117, v72
	v_add_f32_e32 v1, v76, v1
	v_exp_f32_e32 v118, v73
	v_add_f32_e32 v1, v77, v1
	v_exp_f32_e32 v119, v70
	v_add_f32_e32 v1, v115, v1
	v_exp_f32_e32 v120, v71
	v_add_f32_e32 v1, v116, v1
	v_exp_f32_e32 v121, v68
	v_add_f32_e32 v1, v117, v1
	v_exp_f32_e32 v122, v69
	v_add_f32_e32 v1, v118, v1
	v_exp_f32_e32 v123, v66
	v_add_f32_e32 v1, v119, v1
	v_exp_f32_e32 v124, v67
	v_add_f32_e32 v1, v120, v1
	v_add_f32_e32 v1, v121, v1
	v_add_f32_e32 v1, v122, v1
	v_add_f32_e32 v1, v123, v1
	v_add_f32_e32 v1, v124, v1
	v_mov_b32_e32 v114, v1
	v_cvt_pk_bf16_f32 v66, v215, v217
	v_cvt_pk_bf16_f32 v67, v213, v216
	v_cvt_pk_bf16_f32 v68, v211, v214
	v_cvt_pk_bf16_f32 v69, v210, v212
	v_cvt_pk_bf16_f32 v70, v207, v209
	v_cvt_pk_bf16_f32 v71, v205, v208
	v_cvt_pk_bf16_f32 v72, v203, v206
	v_cvt_pk_bf16_f32 v73, v202, v204
	v_cvt_pk_bf16_f32 v74, v80, v81
	v_cvt_pk_bf16_f32 v75, v78, v79
	v_cvt_pk_bf16_f32 v76, v76, v77
	v_cvt_pk_bf16_f32 v77, v115, v116
	v_cvt_pk_bf16_f32 v78, v117, v118
	v_cvt_pk_bf16_f32 v79, v119, v120
	v_cvt_pk_bf16_f32 v80, v121, v122
	v_cvt_pk_bf16_f32 v81, v123, v124
	s_nop 1
	v_permlane32_swap_b32_e32 v1, v114
	v_permlane32_swap_b32_e32 v66, v68
	v_permlane32_swap_b32_e32 v67, v69
	v_permlane32_swap_b32_e32 v70, v72
	v_permlane32_swap_b32_e32 v71, v73
	v_permlane32_swap_b32_e32 v74, v76
	v_permlane32_swap_b32_e32 v75, v77
	v_permlane32_swap_b32_e32 v78, v80
	v_permlane32_swap_b32_e32 v79, v81
	ds_read_b64_tr_b16 v[116:117], v183 offset:0
	ds_read_b64_tr_b16 v[118:119], v183 offset:0x800
	ds_read_b64_tr_b16 v[120:121], v183 offset:0x1000
	ds_read_b64_tr_b16 v[122:123], v183 offset:0x1800
	ds_read_b64_tr_b16 v[124:125], v183 offset:0x2000
	ds_read_b64_tr_b16 v[126:127], v183 offset:0x2800
	ds_read_b64_tr_b16 v[128:129], v183 offset:0x3000
	ds_read_b64_tr_b16 v[130:131], v183 offset:0x3800
	s_nop 0
	s_waitcnt lgkmcnt(4)
	v_mfma_f32_32x32x16_bf16 v[50:65], v[66:69], v[116:119], v[50:65]
	ds_read_b64_tr_b16 v[116:117], v183 offset:0x200
	ds_read_b64_tr_b16 v[118:119], v183 offset:0xa00
	v_mfma_f32_32x32x16_bf16 v[50:65], v[70:73], v[120:123], v[50:65]
	ds_read_b64_tr_b16 v[120:121], v183 offset:0x1200
	ds_read_b64_tr_b16 v[122:123], v183 offset:0x1a00
	s_waitcnt lgkmcnt(4)
	v_mfma_f32_32x32x16_bf16 v[50:65], v[74:77], v[124:127], v[50:65]
	ds_read_b64_tr_b16 v[124:125], v183 offset:0x2200
	ds_read_b64_tr_b16 v[126:127], v183 offset:0x2a00
	v_mfma_f32_32x32x16_bf16 v[50:65], v[78:81], v[128:131], v[50:65]
	ds_read_b64_tr_b16 v[128:129], v183 offset:0x3200
	ds_read_b64_tr_b16 v[130:131], v183 offset:0x3a00
	s_waitcnt lgkmcnt(4)
	v_mfma_f32_32x32x16_bf16 v[34:49], v[66:69], v[116:119], v[34:49]
	ds_read_b64_tr_b16 v[116:117], v183 offset:0x400
	ds_read_b64_tr_b16 v[118:119], v183 offset:0xc00
	v_mfma_f32_32x32x16_bf16 v[34:49], v[70:73], v[120:123], v[34:49]
	ds_read_b64_tr_b16 v[120:121], v183 offset:0x1400
	ds_read_b64_tr_b16 v[122:123], v183 offset:0x1c00
	s_waitcnt lgkmcnt(4)
	v_mfma_f32_32x32x16_bf16 v[34:49], v[74:77], v[124:127], v[34:49]
	ds_read_b64_tr_b16 v[124:125], v183 offset:0x2400
	ds_read_b64_tr_b16 v[126:127], v183 offset:0x2c00
	v_mfma_f32_32x32x16_bf16 v[34:49], v[78:81], v[128:131], v[34:49]
	ds_read_b64_tr_b16 v[128:129], v183 offset:0x3400
	ds_read_b64_tr_b16 v[130:131], v183 offset:0x3c00
	s_waitcnt lgkmcnt(4)
	v_mfma_f32_32x32x16_bf16 v[18:33], v[66:69], v[116:119], v[18:33]
	ds_read_b64_tr_b16 v[116:117], v183 offset:0x600
	ds_read_b64_tr_b16 v[118:119], v183 offset:0xe00
	v_mfma_f32_32x32x16_bf16 v[18:33], v[70:73], v[120:123], v[18:33]
	ds_read_b64_tr_b16 v[120:121], v183 offset:0x1600
	ds_read_b64_tr_b16 v[122:123], v183 offset:0x1e00
	s_waitcnt lgkmcnt(4)
	v_mfma_f32_32x32x16_bf16 v[18:33], v[74:77], v[124:127], v[18:33]
	ds_read_b64_tr_b16 v[124:125], v183 offset:0x2600
	ds_read_b64_tr_b16 v[126:127], v183 offset:0x2e00
	v_mfma_f32_32x32x16_bf16 v[18:33], v[78:81], v[128:131], v[18:33]
	ds_read_b64_tr_b16 v[128:129], v183 offset:0x3600
	ds_read_b64_tr_b16 v[130:131], v183 offset:0x3e00
	s_waitcnt lgkmcnt(4)
	v_mfma_f32_32x32x16_bf16 v[2:17], v[66:69], v[116:119], v[2:17]
	s_lshl_b32 s1, s25, 6
	s_sub_i32 s0, s1, 64
	s_lshl_b32 s2, s0, 2
	s_add_i32 s2, s2, 0
	v_lshl_add_u32 v66, v186, 2, s2
	v_add_u32_e32 v66, 0x10800, v66
	s_add_i32 s1, s1, -1
	v_mfma_f32_32x32x16_bf16 v[2:17], v[70:73], v[120:123], v[2:17]
	s_cmp_gt_i32 s1, s27
	s_waitcnt lgkmcnt(0)
	v_mfma_f32_32x32x16_bf16 v[2:17], v[74:77], v[124:127], v[2:17]
	v_mfma_f32_32x32x16_bf16 v[2:17], v[78:81], v[128:131], v[2:17]
	ds_read_b128 v[116:119], v66 offset:128
	ds_read_b128 v[120:123], v66
	ds_read_b128 v[68:71], v66 offset:32
	ds_read_b128 v[124:127], v66 offset:160
	ds_read_b128 v[72:75], v66 offset:64
	ds_read_b128 v[128:131], v66 offset:192
	ds_read_b128 v[76:79], v66 offset:96
	ds_read_b128 v[132:135], v66 offset:224
	s_waitcnt lgkmcnt(6)
	v_xor_b32_e32 v81, 0x80000000, v123
	v_xor_b32_e32 v80, 0x80000000, v122
	s_waitcnt lgkmcnt(5)
	v_xor_b32_e32 v123, 0x80000000, v71
	v_xor_b32_e32 v122, 0x80000000, v70
	s_waitcnt lgkmcnt(1)
	v_xor_b32_e32 v79, 0x80000000, v79
	v_xor_b32_e32 v78, 0x80000000, v78
	v_xor_b32_e32 v137, 0x80000000, v75
	v_xor_b32_e32 v136, 0x80000000, v74
	v_pk_fma_f32 v[66:67], v[110:111], s[12:13], v[76:77] op_sel_hi:[1,0,1] neg_lo:[0,0,1] neg_hi:[0,0,1]
	v_pk_fma_f32 v[70:71], v[106:107], s[12:13], v[72:73] op_sel_hi:[1,0,1] neg_lo:[0,0,1] neg_hi:[0,0,1]
	v_pk_fma_f32 v[74:75], v[102:103], s[12:13], v[68:69] op_sel_hi:[1,0,1] neg_lo:[0,0,1] neg_hi:[0,0,1]
	v_pk_fma_f32 v[68:69], v[112:113], s[12:13], v[78:79] op_sel_hi:[1,0,1]
	v_pk_fma_f32 v[76:77], v[104:105], s[12:13], v[122:123] op_sel_hi:[1,0,1]
	v_pk_fma_f32 v[78:79], v[100:101], s[12:13], v[80:81] op_sel_hi:[1,0,1]
	v_xor_b32_e32 v101, 0x80000000, v119
	v_xor_b32_e32 v100, 0x80000000, v118
	v_xor_b32_e32 v103, 0x80000000, v127
	v_xor_b32_e32 v102, 0x80000000, v126
	v_xor_b32_e32 v105, 0x80000000, v131
	v_xor_b32_e32 v104, 0x80000000, v130
	s_waitcnt lgkmcnt(0)
	v_xor_b32_e32 v107, 0x80000000, v135
	v_xor_b32_e32 v106, 0x80000000, v134
	v_pk_fma_f32 v[72:73], v[108:109], s[12:13], v[136:137] op_sel_hi:[1,0,1]
	v_pk_fma_f32 v[80:81], v[98:99], s[12:13], v[120:121] op_sel_hi:[1,0,1] neg_lo:[0,0,1] neg_hi:[0,0,1]
	v_pk_fma_f32 v[94:95], v[94:95], s[12:13], v[132:133] op_sel_hi:[1,0,1] neg_lo:[0,0,1] neg_hi:[0,0,1]
	v_pk_fma_f32 v[90:91], v[90:91], s[12:13], v[128:129] op_sel_hi:[1,0,1] neg_lo:[0,0,1] neg_hi:[0,0,1]
	v_pk_fma_f32 v[98:99], v[86:87], s[12:13], v[124:125] op_sel_hi:[1,0,1] neg_lo:[0,0,1] neg_hi:[0,0,1]
	v_pk_fma_f32 v[86:87], v[96:97], s[12:13], v[106:107] op_sel_hi:[1,0,1]
	v_pk_fma_f32 v[92:93], v[92:93], s[12:13], v[104:105] op_sel_hi:[1,0,1]
	v_pk_fma_f32 v[88:89], v[88:89], s[12:13], v[102:103] op_sel_hi:[1,0,1]
	v_pk_fma_f32 v[84:85], v[84:85], s[12:13], v[100:101] op_sel_hi:[1,0,1]
	v_pk_fma_f32 v[82:83], v[82:83], s[12:13], v[116:117] op_sel_hi:[1,0,1] neg_lo:[0,0,1] neg_hi:[0,0,1]
	s_cbranch_scc0 .LBB0_666
	v_subrev_u32_e32 v96, s0, v187
	v_cmp_gt_i32_e64 s[92:93], 26, v96
	v_cmp_gt_i32_e64 s[94:95], 27, v96
	v_cmp_gt_i32_e64 s[90:91], 25, v96
	s_and_b64 s[92:93], s[94:95], s[92:93]
	v_cmp_gt_i32_e64 s[88:89], 24, v96
	s_and_b64 s[90:91], s[92:93], s[90:91]
	v_cmp_gt_i32_e64 s[86:87], 19, v96
	s_and_b64 s[88:89], s[90:91], s[88:89]
	v_cmp_gt_i32_e64 s[84:85], 18, v96
	s_and_b64 s[86:87], s[88:89], s[86:87]
	v_cmp_gt_i32_e64 s[82:83], 17, v96
	s_and_b64 s[84:85], s[86:87], s[84:85]
	v_cmp_gt_i32_e64 s[80:81], 16, v96
	s_and_b64 s[82:83], s[84:85], s[82:83]
	v_cmp_gt_i32_e64 s[78:79], 11, v96
	s_and_b64 s[80:81], s[82:83], s[80:81]
	v_cmp_gt_i32_e64 s[76:77], 10, v96
	s_and_b64 s[78:79], s[80:81], s[78:79]
	v_cmp_gt_i32_e64 s[74:75], 9, v96
	s_and_b64 s[76:77], s[78:79], s[76:77]
	v_cmp_gt_i32_e64 s[72:73], 8, v96
	s_and_b64 s[74:75], s[76:77], s[74:75]
	v_cmp_gt_i32_e64 s[70:71], 3, v96
	s_and_b64 s[72:73], s[74:75], s[72:73]
	v_cmp_gt_i32_e64 s[68:69], 2, v96
	s_and_b64 s[70:71], s[72:73], s[70:71]
	v_cmp_gt_i32_e64 s[2:3], 1, v96
	s_and_b64 s[68:69], s[70:71], s[68:69]
	v_cmp_gt_i32_e64 s[0:1], 0, v96
	s_and_b64 s[2:3], s[68:69], s[2:3]
	s_and_b64 s[0:1], s[2:3], s[0:1]
	v_cmp_gt_i32_e64 s[66:67], 58, v96
	v_cndmask_b32_e64 v80, v80, v175, s[0:1]
	v_cmp_gt_i32_e64 s[0:1], 59, v96
	v_cmp_gt_i32_e64 s[64:65], 57, v96
	v_cmp_gt_i32_e64 s[62:63], 56, v96
	v_cndmask_b32_e64 v87, v87, v175, s[0:1]
	s_and_b64 s[0:1], s[0:1], s[66:67]
	v_cndmask_b32_e64 v86, v86, v175, s[0:1]
	s_and_b64 s[0:1], s[0:1], s[64:65]
	v_cmp_gt_i32_e64 s[60:61], 51, v96
	v_cndmask_b32_e64 v95, v95, v175, s[0:1]
	s_and_b64 s[0:1], s[0:1], s[62:63]
	v_cmp_gt_i32_e64 s[58:59], 50, v96
	v_cndmask_b32_e64 v94, v94, v175, s[0:1]
	s_and_b64 s[0:1], s[0:1], s[60:61]
	v_cmp_gt_i32_e64 s[56:57], 49, v96
	v_cndmask_b32_e64 v93, v93, v175, s[0:1]
	s_and_b64 s[0:1], s[0:1], s[58:59]
	v_cmp_gt_i32_e64 s[54:55], 48, v96
	v_cndmask_b32_e64 v92, v92, v175, s[0:1]
	s_and_b64 s[0:1], s[0:1], s[56:57]
	v_cmp_gt_i32_e64 s[52:53], 43, v96
	v_cndmask_b32_e64 v91, v91, v175, s[0:1]
	s_and_b64 s[0:1], s[0:1], s[54:55]
	v_cmp_gt_i32_e64 s[50:51], 42, v96
	v_cndmask_b32_e64 v90, v90, v175, s[0:1]
	s_and_b64 s[0:1], s[0:1], s[52:53]
	v_cmp_gt_i32_e64 s[48:49], 41, v96
	v_cndmask_b32_e64 v89, v89, v175, s[0:1]
	s_and_b64 s[0:1], s[0:1], s[50:51]
	v_cmp_gt_i32_e64 s[46:47], 40, v96
	v_cndmask_b32_e64 v88, v88, v175, s[0:1]
	s_and_b64 s[0:1], s[0:1], s[48:49]
	v_cmp_gt_i32_e64 s[44:45], 35, v96
	v_cndmask_b32_e64 v99, v99, v175, s[0:1]
	s_and_b64 s[0:1], s[0:1], s[46:47]
	v_cmp_gt_i32_e64 s[42:43], 34, v96
	v_cndmask_b32_e64 v98, v98, v175, s[0:1]
	s_and_b64 s[0:1], s[0:1], s[44:45]
	v_cmp_gt_i32_e64 s[40:41], 33, v96
	v_cndmask_b32_e64 v85, v85, v175, s[0:1]
	s_and_b64 s[0:1], s[0:1], s[42:43]
	v_cmp_gt_i32_e32 vcc, 32, v96
	v_cndmask_b32_e64 v84, v84, v175, s[0:1]
	s_and_b64 s[0:1], s[0:1], s[40:41]
	v_cndmask_b32_e64 v66, v66, v175, s[88:89]
	v_readlane_b32 s88, v242, 2
	s_and_b64 vcc, s[0:1], vcc
	v_cndmask_b32_e64 v69, v69, v175, s[94:95]
	v_cndmask_b32_e64 v68, v68, v175, s[92:93]
	s_movk_i32 s93, 0x6018
	s_mov_b32 s92, 0xf800000
	v_cndmask_b32_e64 v67, v67, v175, s[90:91]
	s_mov_b64 s[90:91], s[16:17]
	v_readlane_b32 s89, v242, 3
	v_cndmask_b32_e64 v73, v73, v175, s[86:87]
	v_readlane_b32 s86, v242, 0
	v_cndmask_b32_e64 v72, v72, v175, s[84:85]
	v_cndmask_b32_e64 v71, v71, v175, s[82:83]
	s_movk_i32 s83, 0x6000
	v_cndmask_b32_e64 v70, v70, v175, s[80:81]
	v_cndmask_b32_e64 v77, v77, v175, s[78:79]
	v_cndmask_b32_e64 v76, v76, v175, s[76:77]
	v_cndmask_b32_e64 v75, v75, v175, s[74:75]
	v_cndmask_b32_e64 v74, v74, v175, s[72:73]
	v_cndmask_b32_e64 v79, v79, v175, s[70:71]
	v_cndmask_b32_e64 v78, v78, v175, s[68:69]
	v_cndmask_b32_e64 v81, v81, v175, s[2:3]
	s_mov_b32 s56, s30
	v_cndmask_b32_e64 v83, v83, v175, s[0:1]
	v_cndmask_b32_e32 v82, v82, v175, vcc
	v_readlane_b32 s87, v242, 1

.LBB0_670:
	v_cndmask_b32_e64 v97, v97, v196, s[40:41]
	v_sub_f32_e32 v80, v80, v97
	v_sub_f32_e32 v81, v81, v97
	v_exp_f32_e32 v80, v80
	v_sub_f32_e32 v78, v78, v97
	v_exp_f32_e32 v81, v81
	v_sub_f32_e32 v79, v79, v97
	v_exp_f32_e32 v78, v78
	v_sub_f32_e32 v74, v74, v97
	v_sub_f32_e32 v66, v66, v97
	v_exp_f32_e32 v79, v79
	v_sub_f32_e32 v75, v75, v97
	v_exp_f32_e32 v74, v74
	v_exp_f32_e32 v102, v66
	v_add_f32_e32 v66, 0, v80
	v_sub_f32_e32 v76, v76, v97
	v_exp_f32_e32 v75, v75
	v_add_f32_e32 v66, v81, v66
	v_sub_f32_e32 v77, v77, v97
	v_exp_f32_e32 v76, v76
	v_add_f32_e32 v66, v78, v66
	v_sub_f32_e32 v70, v70, v97
	v_exp_f32_e32 v77, v77
	v_add_f32_e32 v66, v79, v66
	v_sub_f32_e32 v82, v82, v97
	v_sub_f32_e32 v83, v83, v97
	v_sub_f32_e32 v84, v84, v97
	v_sub_f32_e32 v85, v85, v97
	v_sub_f32_e32 v98, v98, v97
	v_sub_f32_e32 v99, v99, v97
	v_sub_f32_e32 v88, v88, v97
	v_sub_f32_e32 v89, v89, v97
	v_sub_f32_e32 v90, v90, v97
	v_sub_f32_e32 v71, v71, v97
	v_sub_f32_e32 v91, v91, v97
	v_sub_f32_e32 v72, v72, v97
	v_sub_f32_e32 v92, v92, v97
	v_sub_f32_e32 v73, v73, v97
	v_sub_f32_e32 v93, v93, v97
	v_sub_f32_e32 v94, v94, v97
	v_sub_f32_e32 v67, v67, v97
	v_sub_f32_e32 v95, v95, v97
	v_sub_f32_e32 v68, v68, v97
	v_sub_f32_e32 v86, v86, v97
	v_sub_f32_e32 v69, v69, v97
	v_sub_f32_e32 v87, v87, v97
	v_exp_f32_e32 v97, v70
	v_add_f32_e32 v66, v74, v66
	v_exp_f32_e32 v100, v71
	v_add_f32_e32 v66, v75, v66
	v_exp_f32_e32 v101, v72
	v_add_f32_e32 v66, v76, v66
	v_exp_f32_e32 v73, v73
	v_add_f32_e32 v66, v77, v66
	v_add_f32_e32 v66, v97, v66
	v_exp_f32_e32 v103, v67
	v_add_f32_e32 v66, v100, v66
	v_exp_f32_e32 v104, v68
	v_add_f32_e32 v66, v101, v66
	v_exp_f32_e32 v105, v69
	v_add_f32_e32 v66, v73, v66
	v_exp_f32_e32 v82, v82
	v_add_f32_e32 v66, v102, v66
	v_exp_f32_e32 v83, v83
	v_add_f32_e32 v66, v103, v66
	v_exp_f32_e32 v84, v84
	v_add_f32_e32 v66, v104, v66
	v_exp_f32_e32 v85, v85
	v_add_f32_e32 v66, v105, v66
	v_exp_f32_e32 v98, v98
	v_add_f32_e32 v66, v82, v66
	v_exp_f32_e32 v99, v99
	v_add_f32_e32 v66, v83, v66
	v_exp_f32_e32 v88, v88
	v_add_f32_e32 v66, v84, v66
	v_exp_f32_e32 v89, v89
	v_add_f32_e32 v66, v85, v66
	v_exp_f32_e32 v90, v90
	v_add_f32_e32 v66, v98, v66
	v_exp_f32_e32 v91, v91
	v_add_f32_e32 v66, v99, v66
	v_exp_f32_e32 v92, v92
	v_add_f32_e32 v66, v88, v66
	v_exp_f32_e32 v93, v93
	v_add_f32_e32 v66, v89, v66
	v_exp_f32_e32 v94, v94
	v_add_f32_e32 v66, v90, v66
	v_exp_f32_e32 v95, v95
	v_add_f32_e32 v66, v91, v66
	v_exp_f32_e32 v86, v86
	v_add_f32_e32 v66, v92, v66
	v_exp_f32_e32 v87, v87
	v_add_f32_e32 v66, v93, v66
	v_add_f32_e32 v66, v94, v66
	v_add_f32_e32 v66, v95, v66
	v_add_f32_e32 v66, v86, v66
	v_add_f32_e32 v66, v87, v66
	v_mov_b32_e32 v67, v66
	s_nop 1
	v_permlane32_swap_b32_e32 v66, v67
	v_cvt_pk_bf16_f32 v68, v80, v81
	v_cvt_pk_bf16_f32 v69, v78, v79
	v_cvt_pk_bf16_f32 v70, v74, v75
	v_cvt_pk_bf16_f32 v71, v76, v77
	v_cvt_pk_bf16_f32 v72, v97, v100
	v_cvt_pk_bf16_f32 v73, v101, v73
	v_cvt_pk_bf16_f32 v74, v102, v103
	v_cvt_pk_bf16_f32 v75, v104, v105
	v_cvt_pk_bf16_f32 v76, v82, v83
	v_cvt_pk_bf16_f32 v77, v84, v85
	v_cvt_pk_bf16_f32 v78, v98, v99
	v_cvt_pk_bf16_f32 v79, v88, v89
	v_cvt_pk_bf16_f32 v80, v90, v91
	v_cvt_pk_bf16_f32 v81, v92, v93
	v_cvt_pk_bf16_f32 v82, v94, v95
	v_cvt_pk_bf16_f32 v83, v86, v87
	s_nop 0
	v_permlane32_swap_b32_e32 v68, v70
	v_permlane32_swap_b32_e32 v69, v71
	v_permlane32_swap_b32_e32 v72, v74
	v_permlane32_swap_b32_e32 v73, v75
	v_permlane32_swap_b32_e32 v76, v78
	v_permlane32_swap_b32_e32 v77, v79
	v_permlane32_swap_b32_e32 v80, v82
	v_permlane32_swap_b32_e32 v81, v83
	ds_read_b64_tr_b16 v[84:85], v183 offset:0x4000
	ds_read_b64_tr_b16 v[86:87], v183 offset:0x4800
	ds_read_b64_tr_b16 v[88:89], v183 offset:0x5000
	ds_read_b64_tr_b16 v[90:91], v183 offset:0x5800
	ds_read_b64_tr_b16 v[92:93], v183 offset:0x6000
	ds_read_b64_tr_b16 v[94:95], v183 offset:0x6800
	ds_read_b64_tr_b16 v[98:99], v183 offset:0x7000
	ds_read_b64_tr_b16 v[100:101], v183 offset:0x7800
	s_nop 0
	s_waitcnt lgkmcnt(4)
	v_mfma_f32_32x32x16_bf16 v[50:65], v[68:71], v[84:87], v[50:65]
	ds_read_b64_tr_b16 v[84:85], v183 offset:0x4200
	ds_read_b64_tr_b16 v[86:87], v183 offset:0x4a00
	v_mfma_f32_32x32x16_bf16 v[50:65], v[72:75], v[88:91], v[50:65]
	ds_read_b64_tr_b16 v[88:89], v183 offset:0x5200
	ds_read_b64_tr_b16 v[90:91], v183 offset:0x5a00
	s_waitcnt lgkmcnt(4)
	v_mfma_f32_32x32x16_bf16 v[50:65], v[76:79], v[92:95], v[50:65]
	ds_read_b64_tr_b16 v[92:93], v183 offset:0x6200
	ds_read_b64_tr_b16 v[94:95], v183 offset:0x6a00
	v_mfma_f32_32x32x16_bf16 v[50:65], v[80:83], v[98:101], v[50:65]
	ds_read_b64_tr_b16 v[98:99], v183 offset:0x7200
	ds_read_b64_tr_b16 v[100:101], v183 offset:0x7a00
	s_waitcnt lgkmcnt(4)
	v_mfma_f32_32x32x16_bf16 v[34:49], v[68:71], v[84:87], v[34:49]
	ds_read_b64_tr_b16 v[84:85], v183 offset:0x4400
	ds_read_b64_tr_b16 v[86:87], v183 offset:0x4c00
	v_mfma_f32_32x32x16_bf16 v[34:49], v[72:75], v[88:91], v[34:49]
	ds_read_b64_tr_b16 v[88:89], v183 offset:0x5400
	ds_read_b64_tr_b16 v[90:91], v183 offset:0x5c00
	s_waitcnt lgkmcnt(4)
	v_mfma_f32_32x32x16_bf16 v[34:49], v[76:79], v[92:95], v[34:49]
	ds_read_b64_tr_b16 v[92:93], v183 offset:0x6400
	ds_read_b64_tr_b16 v[94:95], v183 offset:0x6c00
	v_mfma_f32_32x32x16_bf16 v[34:49], v[80:83], v[98:101], v[34:49]
	ds_read_b64_tr_b16 v[98:99], v183 offset:0x7400
	ds_read_b64_tr_b16 v[100:101], v183 offset:0x7c00
	s_waitcnt lgkmcnt(4)
	v_mfma_f32_32x32x16_bf16 v[18:33], v[68:71], v[84:87], v[18:33]
	ds_read_b64_tr_b16 v[84:85], v183 offset:0x4600
	ds_read_b64_tr_b16 v[86:87], v183 offset:0x4e00
	v_mfma_f32_32x32x16_bf16 v[18:33], v[72:75], v[88:91], v[18:33]
	ds_read_b64_tr_b16 v[88:89], v183 offset:0x5600
	ds_read_b64_tr_b16 v[90:91], v183 offset:0x5e00
	s_waitcnt lgkmcnt(4)
	v_mfma_f32_32x32x16_bf16 v[18:33], v[76:79], v[92:95], v[18:33]
	ds_read_b64_tr_b16 v[92:93], v183 offset:0x6600
	ds_read_b64_tr_b16 v[94:95], v183 offset:0x6e00
	v_mfma_f32_32x32x16_bf16 v[18:33], v[80:83], v[98:101], v[18:33]
	ds_read_b64_tr_b16 v[98:99], v183 offset:0x7600
	ds_read_b64_tr_b16 v[100:101], v183 offset:0x7e00
	s_waitcnt lgkmcnt(4)
	v_mfma_f32_32x32x16_bf16 v[2:17], v[68:71], v[84:87], v[2:17]
	v_mfma_f32_32x32x16_bf16 v[2:17], v[72:75], v[88:91], v[2:17]
	s_waitcnt lgkmcnt(0)
	v_mfma_f32_32x32x16_bf16 v[2:17], v[76:79], v[92:95], v[2:17]
	v_mfma_f32_32x32x16_bf16 v[2:17], v[80:83], v[98:101], v[2:17]
	s_and_saveexec_b64 s[0:1], s[38:39]
	v_add_f32_e32 v1, v1, v114
	v_fmac_f32_e32 v1, v162, v146
	v_add_f32_e32 v66, v66, v67
	v_fmac_f32_e32 v66, v1, v96
	ds_write_b32 v185, v66
	s_or_b64 exec, exec, s[0:1]
	s_waitcnt lgkmcnt(0)
	ds_read_b128 v[78:81], v184
	ds_read_b128 v[74:77], v184 offset:32
	ds_read_b128 v[70:73], v184 offset:64
	ds_read_b128 v[66:69], v184 offset:96
	s_lshl_b32 s0, s5, 13
	s_waitcnt lgkmcnt(3)
	v_rcp_f32_e32 v78, v78
	v_and_b32_e32 v1, 1, v180
	s_add_i32 s2, s0, 0
	v_cmp_eq_u32_e32 vcc, 0, v1
	v_lshlrev_b32_e32 v1, 10, v181
	v_lshlrev_b32_e32 v82, 1, v182
	v_mul_f32_e32 v50, v50, v78
	v_add3_u32 v1, s2, v1, v82
	s_waitcnt lgkmcnt(0)
	v_mov_b32_dpp v82, v50 quad_perm:[1,0,3,2] row_mask:0xf bank_mask:0xf bound_ctrl:1
	s_barrier
	s_and_saveexec_b64 s[0:1], vcc
	s_cbranch_execz .LBB0_674
	v_cvt_pk_bf16_f32 v50, v50, v82
	ds_write_b32 v1, v50

.LBB0_823:
	v_add_u32_e32 v182, s9, v158
	v_add_u32_e32 v66, 1, v182
	v_mad_i64_i32 v[66:67], s[0:1], v66, s33, v[130:131]
	v_add_u32_e32 v68, 33, v182
	v_mad_i64_i32 v[68:69], s[0:1], v68, s33, v[130:131]
	global_load_dwordx4 v[114:117], v[66:67], off offset:2048
	global_load_dwordx4 v[122:125], v[66:67], off offset:1024
	global_load_dwordx4 v[118:121], v[68:69], off offset:2048
	global_load_dwordx4 v[126:129], v[68:69], off offset:1024
	ds_read_b128 v[228:231], v159 offset:49152
	ds_read_b128 v[232:235], v160 offset:49152
	ds_read_b128 v[236:239], v159 offset:57344
	ds_read_b128 v[248:251], v160 offset:57344
	ds_read_b128 v[252:255], v161 offset:49152
	s_waitcnt lgkmcnt(3)
	v_mfma_f32_32x32x16_bf16 v[82:97], v[228:231], v[110:113], 0
	ds_read_b128 v[228:231], v161 offset:57344
	v_mfma_f32_32x32x16_bf16 v[82:97], v[232:235], v[106:109], v[82:97]
	ds_read_b128 v[232:235], v162 offset:49152
	s_waitcnt lgkmcnt(3)
	v_mfma_f32_32x32x16_bf16 v[66:81], v[236:239], v[110:113], 0
	ds_read_b128 v[236:239], v162 offset:57344
	v_mfma_f32_32x32x16_bf16 v[66:81], v[248:251], v[106:109], v[66:81]
	s_waitcnt lgkmcnt(2)
	v_mfma_f32_32x32x16_bf16 v[82:97], v[252:255], v[102:105], v[82:97]
	v_mfma_f32_32x32x16_bf16 v[66:81], v[228:231], v[102:105], v[66:81]
	s_waitcnt lgkmcnt(0)
	v_mfma_f32_32x32x16_bf16 v[82:97], v[232:235], v[98:101], v[82:97]
	v_mfma_f32_32x32x16_bf16 v[66:81], v[236:239], v[98:101], v[66:81]
	v_exp_f32_e32 v206, v132
	v_add_f32_e32 v132, 0, v197
	v_add_f32_e32 v132, v199, v132
	v_add_f32_e32 v132, v195, v132
	v_add_f32_e32 v132, v198, v132
	v_add_f32_e32 v132, v193, v132
	v_add_f32_e32 v132, v196, v132
	v_add_f32_e32 v132, v192, v132
	v_add_f32_e32 v132, v194, v132
	v_add_f32_e32 v132, v189, v132
	v_add_f32_e32 v132, v191, v132
	v_add_f32_e32 v132, v187, v132
	v_add_f32_e32 v132, v190, v132
	v_exp_f32_e32 v146, v146
	v_add_f32_e32 v132, v185, v132
	v_exp_f32_e32 v147, v147
	v_add_f32_e32 v132, v188, v132
	v_exp_f32_e32 v144, v144
	v_add_f32_e32 v132, v184, v132
	v_exp_f32_e32 v145, v145
	v_add_f32_e32 v132, v186, v132
	v_exp_f32_e32 v142, v142
	v_add_f32_e32 v132, v146, v132
	v_exp_f32_e32 v143, v143
	v_add_f32_e32 v132, v147, v132
	v_exp_f32_e32 v181, v140
	v_add_f32_e32 v132, v144, v132
	v_exp_f32_e32 v183, v141
	v_add_f32_e32 v132, v145, v132
	v_exp_f32_e32 v200, v138
	v_add_f32_e32 v132, v142, v132
	v_exp_f32_e32 v201, v139
	v_add_f32_e32 v132, v143, v132
	v_exp_f32_e32 v202, v136
	v_add_f32_e32 v132, v181, v132
	v_exp_f32_e32 v203, v137
	v_add_f32_e32 v132, v183, v132
	v_exp_f32_e32 v204, v134
	v_add_f32_e32 v132, v200, v132
	v_exp_f32_e32 v205, v135
	v_add_f32_e32 v132, v201, v132
	v_add_f32_e32 v132, v202, v132
	v_exp_f32_e32 v207, v133
	v_add_f32_e32 v132, v203, v132
	v_add_f32_e32 v132, v204, v132
	v_add_f32_e32 v132, v205, v132
	v_add_f32_e32 v132, v206, v132
	v_add_f32_e32 v179, v207, v132
	v_mov_b32_e32 v180, v179
	s_nop 1
	v_permlane32_swap_b32_e32 v179, v180
	v_cvt_pk_bf16_f32 v132, v197, v199
	v_cvt_pk_bf16_f32 v133, v195, v198
	v_cvt_pk_bf16_f32 v134, v193, v196
	v_cvt_pk_bf16_f32 v135, v192, v194
	v_cvt_pk_bf16_f32 v136, v189, v191
	v_cvt_pk_bf16_f32 v137, v187, v190
	v_cvt_pk_bf16_f32 v138, v185, v188
	v_cvt_pk_bf16_f32 v139, v184, v186
	v_cvt_pk_bf16_f32 v140, v146, v147
	v_cvt_pk_bf16_f32 v141, v144, v145
	v_cvt_pk_bf16_f32 v142, v142, v143
	v_cvt_pk_bf16_f32 v143, v181, v183
	v_cvt_pk_bf16_f32 v144, v200, v201
	v_cvt_pk_bf16_f32 v145, v202, v203
	v_cvt_pk_bf16_f32 v146, v204, v205
	v_cvt_pk_bf16_f32 v147, v206, v207
	s_nop 0
	v_permlane32_swap_b32_e32 v132, v134
	v_permlane32_swap_b32_e32 v133, v135
	v_permlane32_swap_b32_e32 v136, v138
	v_permlane32_swap_b32_e32 v137, v139
	v_permlane32_swap_b32_e32 v140, v142
	v_permlane32_swap_b32_e32 v141, v143
	v_permlane32_swap_b32_e32 v144, v146
	v_permlane32_swap_b32_e32 v145, v147
	ds_read_b64_tr_b16 v[184:185], v153 offset:0
	ds_read_b64_tr_b16 v[186:187], v153 offset:0x800
	ds_read_b64_tr_b16 v[188:189], v153 offset:0x1000
	ds_read_b64_tr_b16 v[190:191], v153 offset:0x1800
	ds_read_b64_tr_b16 v[192:193], v153 offset:0x2000
	ds_read_b64_tr_b16 v[194:195], v153 offset:0x2800
	ds_read_b64_tr_b16 v[196:197], v153 offset:0x3000
	ds_read_b64_tr_b16 v[198:199], v153 offset:0x3800
	s_nop 0
	s_waitcnt lgkmcnt(4)
	v_mfma_f32_32x32x16_bf16 v[50:65], v[132:135], v[184:187], v[50:65]
	ds_read_b64_tr_b16 v[184:185], v153 offset:0x200
	ds_read_b64_tr_b16 v[186:187], v153 offset:0xa00
	v_mfma_f32_32x32x16_bf16 v[50:65], v[136:139], v[188:191], v[50:65]
	ds_read_b64_tr_b16 v[188:189], v153 offset:0x1200
	ds_read_b64_tr_b16 v[190:191], v153 offset:0x1a00
	s_waitcnt lgkmcnt(4)
	v_mfma_f32_32x32x16_bf16 v[50:65], v[140:143], v[192:195], v[50:65]
	ds_read_b64_tr_b16 v[192:193], v153 offset:0x2200
	ds_read_b64_tr_b16 v[194:195], v153 offset:0x2a00
	v_mfma_f32_32x32x16_bf16 v[50:65], v[144:147], v[196:199], v[50:65]
	ds_read_b64_tr_b16 v[196:197], v153 offset:0x3200
	ds_read_b64_tr_b16 v[198:199], v153 offset:0x3a00
	s_waitcnt lgkmcnt(4)
	v_mfma_f32_32x32x16_bf16 v[34:49], v[132:135], v[184:187], v[34:49]
	ds_read_b64_tr_b16 v[184:185], v153 offset:0x400
	ds_read_b64_tr_b16 v[186:187], v153 offset:0xc00
	v_mfma_f32_32x32x16_bf16 v[34:49], v[136:139], v[188:191], v[34:49]
	ds_read_b64_tr_b16 v[188:189], v153 offset:0x1400
	ds_read_b64_tr_b16 v[190:191], v153 offset:0x1c00
	s_waitcnt lgkmcnt(4)
	v_mfma_f32_32x32x16_bf16 v[34:49], v[140:143], v[192:195], v[34:49]
	ds_read_b64_tr_b16 v[192:193], v153 offset:0x2400
	ds_read_b64_tr_b16 v[194:195], v153 offset:0x2c00
	v_mfma_f32_32x32x16_bf16 v[34:49], v[144:147], v[196:199], v[34:49]
	ds_read_b64_tr_b16 v[196:197], v153 offset:0x3400
	ds_read_b64_tr_b16 v[198:199], v153 offset:0x3c00
	s_waitcnt lgkmcnt(4)
	v_mfma_f32_32x32x16_bf16 v[18:33], v[132:135], v[184:187], v[18:33]
	ds_read_b64_tr_b16 v[184:185], v153 offset:0x600
	ds_read_b64_tr_b16 v[186:187], v153 offset:0xe00
	v_mfma_f32_32x32x16_bf16 v[18:33], v[136:139], v[188:191], v[18:33]
	ds_read_b64_tr_b16 v[188:189], v153 offset:0x1600
	ds_read_b64_tr_b16 v[190:191], v153 offset:0x1e00
	s_waitcnt lgkmcnt(4)
	v_mfma_f32_32x32x16_bf16 v[18:33], v[140:143], v[192:195], v[18:33]
	ds_read_b64_tr_b16 v[192:193], v153 offset:0x2600
	ds_read_b64_tr_b16 v[194:195], v153 offset:0x2e00
	v_mfma_f32_32x32x16_bf16 v[18:33], v[144:147], v[196:199], v[18:33]
	ds_read_b64_tr_b16 v[196:197], v153 offset:0x3600
	ds_read_b64_tr_b16 v[198:199], v153 offset:0x3e00
	s_waitcnt lgkmcnt(4)
	v_mfma_f32_32x32x16_bf16 v[2:17], v[132:135], v[184:187], v[2:17]
	v_mfma_f32_32x32x16_bf16 v[2:17], v[136:139], v[188:191], v[2:17]
	s_waitcnt lgkmcnt(0)
	v_mfma_f32_32x32x16_bf16 v[2:17], v[140:143], v[192:195], v[2:17]
	v_mfma_f32_32x32x16_bf16 v[2:17], v[144:147], v[196:199], v[2:17]
	s_cmp_le_i32 s9, s25
	s_cbranch_scc1 .LBB0_825
	v_add_u32_e32 v132, 64, v169
	v_cmp_gt_i32_e64 s[92:93], 26, v132
	v_cmp_gt_i32_e64 s[94:95], 27, v132
	v_cmp_gt_i32_e64 s[90:91], 25, v132
	s_and_b64 s[92:93], s[94:95], s[92:93]
	v_cmp_gt_i32_e64 s[88:89], 24, v132
	s_and_b64 s[90:91], s[92:93], s[90:91]
	v_cmp_gt_i32_e64 s[86:87], 19, v132
	s_and_b64 s[88:89], s[90:91], s[88:89]
	v_cmp_gt_i32_e64 s[84:85], 18, v132
	s_and_b64 s[86:87], s[88:89], s[86:87]
	v_cmp_gt_i32_e64 s[82:83], 17, v132
	s_and_b64 s[84:85], s[86:87], s[84:85]
	v_cmp_gt_i32_e64 s[80:81], 16, v132
	s_and_b64 s[82:83], s[84:85], s[82:83]
	v_cmp_gt_i32_e64 s[78:79], 11, v132
	s_and_b64 s[80:81], s[82:83], s[80:81]
	v_cmp_gt_i32_e64 s[76:77], 10, v132
	s_and_b64 s[78:79], s[80:81], s[78:79]
	v_cmp_gt_i32_e64 s[74:75], 9, v132
	s_and_b64 s[76:77], s[78:79], s[76:77]
	v_cmp_gt_i32_e64 s[72:73], 8, v132
	s_and_b64 s[74:75], s[76:77], s[74:75]
	v_cmp_gt_i32_e64 s[70:71], 3, v132
	s_and_b64 s[72:73], s[74:75], s[72:73]
	v_cmp_gt_i32_e64 s[68:69], 2, v132
	s_and_b64 s[70:71], s[72:73], s[70:71]
	v_cmp_gt_i32_e64 s[2:3], 1, v132
	s_and_b64 s[68:69], s[70:71], s[68:69]
	v_cmp_gt_i32_e64 s[0:1], 0, v132
	s_and_b64 s[2:3], s[68:69], s[2:3]
	s_and_b64 s[0:1], s[2:3], s[0:1]
	v_cmp_gt_i32_e64 s[66:67], 58, v132
	v_cndmask_b32_e64 v82, v82, v175, s[0:1]
	v_cmp_gt_i32_e64 s[0:1], 59, v132
	v_cmp_gt_i32_e64 s[64:65], 57, v132
	v_cmp_gt_i32_e64 s[62:63], 56, v132
	v_cndmask_b32_e64 v81, v81, v175, s[0:1]
	s_and_b64 s[0:1], s[0:1], s[66:67]
	v_cndmask_b32_e64 v80, v80, v175, s[0:1]
	s_and_b64 s[0:1], s[0:1], s[64:65]
	v_cmp_gt_i32_e64 s[60:61], 51, v132
	v_cndmask_b32_e64 v79, v79, v175, s[0:1]
	s_and_b64 s[0:1], s[0:1], s[62:63]
	v_cmp_gt_i32_e64 s[58:59], 50, v132
	v_cndmask_b32_e64 v78, v78, v175, s[0:1]
	s_and_b64 s[0:1], s[0:1], s[60:61]
	v_cmp_gt_i32_e64 s[56:57], 49, v132
	v_cndmask_b32_e64 v77, v77, v175, s[0:1]
	s_and_b64 s[0:1], s[0:1], s[58:59]
	v_cmp_gt_i32_e64 s[54:55], 48, v132
	v_cndmask_b32_e64 v76, v76, v175, s[0:1]
	s_and_b64 s[0:1], s[0:1], s[56:57]
	v_cmp_gt_i32_e64 s[52:53], 43, v132
	v_cndmask_b32_e64 v75, v75, v175, s[0:1]
	s_and_b64 s[0:1], s[0:1], s[54:55]
	v_cmp_gt_i32_e64 s[50:51], 42, v132
	v_cndmask_b32_e64 v74, v74, v175, s[0:1]
	s_and_b64 s[0:1], s[0:1], s[52:53]
	v_cmp_gt_i32_e64 s[48:49], 41, v132
	v_cndmask_b32_e64 v73, v73, v175, s[0:1]
	s_and_b64 s[0:1], s[0:1], s[50:51]
	v_cmp_gt_i32_e64 s[46:47], 40, v132
	v_cndmask_b32_e64 v72, v72, v175, s[0:1]
	s_and_b64 s[0:1], s[0:1], s[48:49]
	v_cmp_gt_i32_e64 s[44:45], 35, v132
	v_cndmask_b32_e64 v71, v71, v175, s[0:1]
	s_and_b64 s[0:1], s[0:1], s[46:47]
	v_cmp_gt_i32_e64 s[42:43], 34, v132
	v_cndmask_b32_e64 v70, v70, v175, s[0:1]
	s_and_b64 s[0:1], s[0:1], s[44:45]
	v_cmp_gt_i32_e64 s[40:41], 33, v132
	v_cndmask_b32_e64 v69, v69, v175, s[0:1]
	s_and_b64 s[0:1], s[0:1], s[42:43]
	v_cmp_gt_i32_e32 vcc, 32, v132
	v_cndmask_b32_e64 v68, v68, v175, s[0:1]
	s_and_b64 s[0:1], s[0:1], s[40:41]
	s_and_b64 vcc, s[0:1], vcc
	v_cndmask_b32_e64 v97, v97, v175, s[94:95]
	v_cndmask_b32_e64 v96, v96, v175, s[92:93]
	v_cndmask_b32_e64 v95, v95, v175, s[90:91]
	v_cndmask_b32_e64 v94, v94, v175, s[88:89]
	v_cndmask_b32_e64 v93, v93, v175, s[86:87]
	v_cndmask_b32_e64 v92, v92, v175, s[84:85]
	v_cndmask_b32_e64 v91, v91, v175, s[82:83]
	v_cndmask_b32_e64 v90, v90, v175, s[80:81]
	v_cndmask_b32_e64 v89, v89, v175, s[78:79]
	v_cndmask_b32_e64 v88, v88, v175, s[76:77]
	v_cndmask_b32_e64 v87, v87, v175, s[74:75]
	v_cndmask_b32_e64 v86, v86, v175, s[72:73]
	v_cndmask_b32_e64 v85, v85, v175, s[70:71]
	v_cndmask_b32_e64 v84, v84, v175, s[68:69]
	v_cndmask_b32_e64 v83, v83, v175, s[2:3]
	v_cndmask_b32_e64 v67, v67, v175, s[0:1]
	v_cndmask_b32_e32 v66, v66, v175, vcc

.LBB0_831:
	ds_read_b128 v[228:231], v159 offset:32768
	ds_read_b128 v[232:235], v160 offset:32768
	ds_read_b128 v[236:239], v159 offset:40960
	ds_read_b128 v[248:251], v160 offset:40960
	ds_read_b128 v[252:255], v161 offset:32768
	s_waitcnt lgkmcnt(3)
	v_mfma_f32_32x32x16_bf16 v[82:97], v[228:231], v[110:113], 0
	ds_read_b128 v[228:231], v161 offset:40960
	v_mfma_f32_32x32x16_bf16 v[82:97], v[232:235], v[106:109], v[82:97]
	ds_read_b128 v[232:235], v162 offset:32768
	s_waitcnt lgkmcnt(3)
	v_mfma_f32_32x32x16_bf16 v[66:81], v[236:239], v[110:113], 0
	ds_read_b128 v[236:239], v162 offset:40960
	v_mfma_f32_32x32x16_bf16 v[66:81], v[248:251], v[106:109], v[66:81]
	s_waitcnt lgkmcnt(2)
	v_mfma_f32_32x32x16_bf16 v[82:97], v[252:255], v[102:105], v[82:97]
	v_mfma_f32_32x32x16_bf16 v[66:81], v[228:231], v[102:105], v[66:81]
	s_waitcnt lgkmcnt(0)
	v_mfma_f32_32x32x16_bf16 v[82:97], v[232:235], v[98:101], v[82:97]
	v_mfma_f32_32x32x16_bf16 v[66:81], v[236:239], v[98:101], v[66:81]
	v_add_f32_e32 v182, 0, v146
	v_add_f32_e32 v182, v168, v182
	v_add_f32_e32 v182, v144, v182
	v_add_f32_e32 v182, v147, v182
	v_add_f32_e32 v182, v142, v182
	v_add_f32_e32 v182, v145, v182
	v_add_f32_e32 v182, v141, v182
	v_add_f32_e32 v182, v143, v182
	v_add_f32_e32 v182, v138, v182
	v_add_f32_e32 v182, v140, v182
	v_add_f32_e32 v182, v136, v182
	v_add_f32_e32 v182, v139, v182
	v_exp_f32_e32 v199, v184
	v_add_f32_e32 v182, v134, v182
	v_exp_f32_e32 v200, v185
	v_add_f32_e32 v182, v137, v182
	v_exp_f32_e32 v201, v186
	v_add_f32_e32 v182, v133, v182
	v_exp_f32_e32 v202, v187
	v_add_f32_e32 v182, v135, v182
	v_exp_f32_e32 v188, v188
	v_add_f32_e32 v182, v199, v182
	v_exp_f32_e32 v189, v189
	v_add_f32_e32 v182, v200, v182
	v_exp_f32_e32 v190, v190
	v_add_f32_e32 v182, v201, v182
	v_exp_f32_e32 v191, v191
	v_add_f32_e32 v182, v202, v182
	v_exp_f32_e32 v192, v192
	v_add_f32_e32 v182, v188, v182
	v_exp_f32_e32 v193, v193
	v_add_f32_e32 v182, v189, v182
	v_exp_f32_e32 v194, v194
	v_add_f32_e32 v182, v190, v182
	v_exp_f32_e32 v195, v195
	v_add_f32_e32 v182, v191, v182
	v_exp_f32_e32 v196, v196
	v_add_f32_e32 v182, v192, v182
	v_exp_f32_e32 v197, v197
	v_add_f32_e32 v182, v193, v182
	v_exp_f32_e32 v198, v198
	v_add_f32_e32 v182, v194, v182
	v_exp_f32_e32 v203, v183
	v_add_f32_e32 v182, v195, v182
	v_add_f32_e32 v182, v196, v182
	v_add_f32_e32 v182, v197, v182
	v_add_f32_e32 v182, v198, v182
	v_add_f32_e32 v182, v203, v182
	v_mov_b32_e32 v183, v182
	s_nop 1
	v_permlane32_swap_b32_e32 v182, v183
	v_cvt_pk_bf16_f32 v184, v146, v168
	v_cvt_pk_bf16_f32 v185, v144, v147
	v_cvt_pk_bf16_f32 v186, v142, v145
	v_cvt_pk_bf16_f32 v187, v141, v143
	v_cvt_pk_bf16_f32 v138, v138, v140
	v_cvt_pk_bf16_f32 v139, v136, v139
	v_cvt_pk_bf16_f32 v140, v134, v137
	v_cvt_pk_bf16_f32 v141, v133, v135
	v_cvt_pk_bf16_f32 v134, v199, v200
	v_cvt_pk_bf16_f32 v135, v201, v202
	v_cvt_pk_bf16_f32 v136, v188, v189
	v_cvt_pk_bf16_f32 v137, v190, v191
	v_cvt_pk_bf16_f32 v142, v192, v193
	v_cvt_pk_bf16_f32 v143, v194, v195
	v_cvt_pk_bf16_f32 v144, v196, v197
	v_cvt_pk_bf16_f32 v145, v198, v203
	s_nop 0
	v_permlane32_swap_b32_e32 v184, v186
	v_permlane32_swap_b32_e32 v185, v187
	v_permlane32_swap_b32_e32 v138, v140
	v_permlane32_swap_b32_e32 v139, v141
	v_permlane32_swap_b32_e32 v134, v136
	v_permlane32_swap_b32_e32 v135, v137
	v_permlane32_swap_b32_e32 v142, v144
	v_permlane32_swap_b32_e32 v143, v145
	ds_read_b64_tr_b16 v[188:189], v153 offset:0x4000
	ds_read_b64_tr_b16 v[190:191], v153 offset:0x4800
	ds_read_b64_tr_b16 v[192:193], v153 offset:0x5000
	ds_read_b64_tr_b16 v[194:195], v153 offset:0x5800
	ds_read_b64_tr_b16 v[196:197], v153 offset:0x6000
	ds_read_b64_tr_b16 v[198:199], v153 offset:0x6800
	ds_read_b64_tr_b16 v[200:201], v153 offset:0x7000
	ds_read_b64_tr_b16 v[202:203], v153 offset:0x7800
	s_nop 0
	s_waitcnt lgkmcnt(4)
	v_mfma_f32_32x32x16_bf16 v[50:65], v[184:187], v[188:191], v[50:65]
	ds_read_b64_tr_b16 v[188:189], v153 offset:0x4200
	ds_read_b64_tr_b16 v[190:191], v153 offset:0x4a00
	v_mfma_f32_32x32x16_bf16 v[50:65], v[138:141], v[192:195], v[50:65]
	ds_read_b64_tr_b16 v[192:193], v153 offset:0x5200
	ds_read_b64_tr_b16 v[194:195], v153 offset:0x5a00
	s_waitcnt lgkmcnt(4)
	v_mfma_f32_32x32x16_bf16 v[50:65], v[134:137], v[196:199], v[50:65]
	ds_read_b64_tr_b16 v[196:197], v153 offset:0x6200
	ds_read_b64_tr_b16 v[198:199], v153 offset:0x6a00
	v_mfma_f32_32x32x16_bf16 v[50:65], v[142:145], v[200:203], v[50:65]
	ds_read_b64_tr_b16 v[200:201], v153 offset:0x7200
	ds_read_b64_tr_b16 v[202:203], v153 offset:0x7a00
	s_waitcnt lgkmcnt(4)
	v_mfma_f32_32x32x16_bf16 v[34:49], v[184:187], v[188:191], v[34:49]
	ds_read_b64_tr_b16 v[188:189], v153 offset:0x4400
	ds_read_b64_tr_b16 v[190:191], v153 offset:0x4c00
	v_mfma_f32_32x32x16_bf16 v[34:49], v[138:141], v[192:195], v[34:49]
	ds_read_b64_tr_b16 v[192:193], v153 offset:0x5400
	ds_read_b64_tr_b16 v[194:195], v153 offset:0x5c00
	s_waitcnt lgkmcnt(4)
	v_mfma_f32_32x32x16_bf16 v[34:49], v[134:137], v[196:199], v[34:49]
	ds_read_b64_tr_b16 v[196:197], v153 offset:0x6400
	ds_read_b64_tr_b16 v[198:199], v153 offset:0x6c00
	v_mfma_f32_32x32x16_bf16 v[34:49], v[142:145], v[200:203], v[34:49]
	ds_read_b64_tr_b16 v[200:201], v153 offset:0x7400
	ds_read_b64_tr_b16 v[202:203], v153 offset:0x7c00
	s_waitcnt lgkmcnt(4)
	v_mfma_f32_32x32x16_bf16 v[18:33], v[184:187], v[188:191], v[18:33]
	ds_read_b64_tr_b16 v[188:189], v153 offset:0x4600
	ds_read_b64_tr_b16 v[190:191], v153 offset:0x4e00
	v_mfma_f32_32x32x16_bf16 v[18:33], v[138:141], v[192:195], v[18:33]
	ds_read_b64_tr_b16 v[192:193], v153 offset:0x5600
	ds_read_b64_tr_b16 v[194:195], v153 offset:0x5e00
	s_waitcnt lgkmcnt(4)
	v_mfma_f32_32x32x16_bf16 v[18:33], v[134:137], v[196:199], v[18:33]
	ds_read_b64_tr_b16 v[196:197], v153 offset:0x6600
	ds_read_b64_tr_b16 v[198:199], v153 offset:0x6e00
	v_mfma_f32_32x32x16_bf16 v[18:33], v[142:145], v[200:203], v[18:33]
	ds_read_b64_tr_b16 v[200:201], v153 offset:0x7600
	ds_read_b64_tr_b16 v[202:203], v153 offset:0x7e00
	s_waitcnt lgkmcnt(4)
	v_mfma_f32_32x32x16_bf16 v[2:17], v[184:187], v[188:191], v[2:17]
	v_mfma_f32_32x32x16_bf16 v[2:17], v[138:141], v[192:195], v[2:17]
	s_waitcnt lgkmcnt(0)
	v_mfma_f32_32x32x16_bf16 v[2:17], v[134:137], v[196:199], v[2:17]
	v_mfma_f32_32x32x16_bf16 v[2:17], v[142:145], v[200:203], v[2:17]
	s_add_i32 s0, s9, 64
	s_cmp_le_i32 s0, s25
	s_cbranch_scc1 .LBB0_833
	v_cmp_gt_i32_e64 s[92:93], 26, v169
	v_cmp_gt_i32_e64 s[94:95], 27, v169
	v_cmp_gt_i32_e64 s[90:91], 25, v169
	s_and_b64 s[92:93], s[94:95], s[92:93]
	v_cmp_gt_i32_e64 s[88:89], 24, v169
	s_and_b64 s[90:91], s[92:93], s[90:91]
	v_cmp_gt_i32_e64 s[86:87], 19, v169
	s_and_b64 s[88:89], s[90:91], s[88:89]
	v_cmp_gt_i32_e64 s[84:85], 18, v169
	s_and_b64 s[86:87], s[88:89], s[86:87]
	v_cmp_gt_i32_e64 s[82:83], 17, v169
	s_and_b64 s[84:85], s[86:87], s[84:85]
	v_cmp_gt_i32_e64 s[80:81], 16, v169
	s_and_b64 s[82:83], s[84:85], s[82:83]
	v_cmp_gt_i32_e64 s[78:79], 11, v169
	s_and_b64 s[80:81], s[82:83], s[80:81]
	v_cmp_gt_i32_e64 s[76:77], 10, v169
	s_and_b64 s[78:79], s[80:81], s[78:79]
	v_cmp_gt_i32_e64 s[74:75], 9, v169
	s_and_b64 s[76:77], s[78:79], s[76:77]
	v_cmp_gt_i32_e64 s[72:73], 8, v169
	s_and_b64 s[74:75], s[76:77], s[74:75]
	v_cmp_gt_i32_e64 s[70:71], 3, v169
	s_and_b64 s[72:73], s[74:75], s[72:73]
	v_cmp_gt_i32_e64 s[68:69], 2, v169
	s_and_b64 s[70:71], s[72:73], s[70:71]
	v_cmp_gt_i32_e64 s[2:3], 1, v169
	s_and_b64 s[68:69], s[70:71], s[68:69]
	v_cmp_gt_i32_e64 s[0:1], 0, v169
	s_and_b64 s[2:3], s[68:69], s[2:3]
	s_and_b64 s[0:1], s[2:3], s[0:1]
	v_cmp_gt_i32_e64 s[66:67], 58, v169
	v_cndmask_b32_e64 v82, v82, v175, s[0:1]
	v_cmp_gt_i32_e64 s[0:1], 59, v169
	v_cmp_gt_i32_e64 s[64:65], 57, v169
	v_cmp_gt_i32_e64 s[62:63], 56, v169
	v_cndmask_b32_e64 v81, v81, v175, s[0:1]
	s_and_b64 s[0:1], s[0:1], s[66:67]
	v_cndmask_b32_e64 v80, v80, v175, s[0:1]
	s_and_b64 s[0:1], s[0:1], s[64:65]
	v_cmp_gt_i32_e64 s[60:61], 51, v169
	v_cndmask_b32_e64 v79, v79, v175, s[0:1]
	s_and_b64 s[0:1], s[0:1], s[62:63]
	v_cmp_gt_i32_e64 s[58:59], 50, v169
	v_cndmask_b32_e64 v78, v78, v175, s[0:1]
	s_and_b64 s[0:1], s[0:1], s[60:61]
	v_cmp_gt_i32_e64 s[56:57], 49, v169
	v_cndmask_b32_e64 v77, v77, v175, s[0:1]
	s_and_b64 s[0:1], s[0:1], s[58:59]
	v_cmp_gt_i32_e64 s[54:55], 48, v169
	v_cndmask_b32_e64 v76, v76, v175, s[0:1]
	s_and_b64 s[0:1], s[0:1], s[56:57]
	v_cmp_gt_i32_e64 s[52:53], 43, v169
	v_cndmask_b32_e64 v75, v75, v175, s[0:1]
	s_and_b64 s[0:1], s[0:1], s[54:55]
	v_cmp_gt_i32_e64 s[50:51], 42, v169
	v_cndmask_b32_e64 v74, v74, v175, s[0:1]
	s_and_b64 s[0:1], s[0:1], s[52:53]
	v_cmp_gt_i32_e64 s[48:49], 41, v169
	v_cndmask_b32_e64 v73, v73, v175, s[0:1]
	s_and_b64 s[0:1], s[0:1], s[50:51]
	v_cmp_gt_i32_e64 s[46:47], 40, v169
	v_cndmask_b32_e64 v72, v72, v175, s[0:1]
	s_and_b64 s[0:1], s[0:1], s[48:49]
	v_cmp_gt_i32_e64 s[44:45], 35, v169
	v_cndmask_b32_e64 v71, v71, v175, s[0:1]
	s_and_b64 s[0:1], s[0:1], s[46:47]
	v_cmp_gt_i32_e64 s[42:43], 34, v169
	v_cndmask_b32_e64 v70, v70, v175, s[0:1]
	s_and_b64 s[0:1], s[0:1], s[44:45]
	v_cmp_gt_i32_e64 s[40:41], 33, v169
	v_cndmask_b32_e64 v69, v69, v175, s[0:1]
	s_and_b64 s[0:1], s[0:1], s[42:43]
	v_cmp_gt_i32_e32 vcc, 32, v169
	v_cndmask_b32_e64 v68, v68, v175, s[0:1]
	s_and_b64 s[0:1], s[0:1], s[40:41]
	s_and_b64 vcc, s[0:1], vcc
	v_cndmask_b32_e64 v97, v97, v175, s[94:95]
	v_cndmask_b32_e64 v96, v96, v175, s[92:93]
	v_cndmask_b32_e64 v95, v95, v175, s[90:91]
	v_cndmask_b32_e64 v94, v94, v175, s[88:89]
	v_cndmask_b32_e64 v93, v93, v175, s[86:87]
	v_cndmask_b32_e64 v92, v92, v175, s[84:85]
	v_cndmask_b32_e64 v91, v91, v175, s[82:83]
	v_cndmask_b32_e64 v90, v90, v175, s[80:81]
	v_cndmask_b32_e64 v89, v89, v175, s[78:79]
	v_cndmask_b32_e64 v88, v88, v175, s[76:77]
	v_cndmask_b32_e64 v87, v87, v175, s[74:75]
	v_cndmask_b32_e64 v86, v86, v175, s[72:73]
	v_cndmask_b32_e64 v85, v85, v175, s[70:71]
	v_cndmask_b32_e64 v84, v84, v175, s[68:69]
	v_cndmask_b32_e64 v83, v83, v175, s[2:3]
	v_cndmask_b32_e64 v67, v67, v175, s[0:1]
	v_cndmask_b32_e32 v66, v66, v175, vcc

.LBB0_842:
	ds_read_b128 v[66:69], v159 offset:49152
	ds_read_b128 v[70:73], v159 offset:57344
	s_waitcnt lgkmcnt(1)
	v_mfma_f32_32x32x16_bf16 v[82:97], v[66:69], v[110:113], 0
	s_waitcnt lgkmcnt(0)
	v_mfma_f32_32x32x16_bf16 v[66:81], v[70:73], v[110:113], 0
	ds_read_b128 v[110:113], v160 offset:49152
	s_waitcnt vmcnt(1)
	ds_read_b128 v[116:119], v160 offset:57344
	s_waitcnt lgkmcnt(1)
	v_mfma_f32_32x32x16_bf16 v[82:97], v[110:113], v[106:109], v[82:97]
	s_waitcnt lgkmcnt(0)
	v_mfma_f32_32x32x16_bf16 v[66:81], v[116:119], v[106:109], v[66:81]
	ds_read_b128 v[106:109], v161 offset:49152
	ds_read_b128 v[110:113], v161 offset:57344
	s_waitcnt lgkmcnt(1)
	v_mfma_f32_32x32x16_bf16 v[82:97], v[106:109], v[102:105], v[82:97]
	s_waitcnt lgkmcnt(0)
	v_mfma_f32_32x32x16_bf16 v[66:81], v[110:113], v[102:105], v[66:81]
	ds_read_b128 v[102:105], v162 offset:49152
	ds_read_b128 v[106:109], v162 offset:57344
	s_waitcnt lgkmcnt(1)
	v_mfma_f32_32x32x16_bf16 v[82:97], v[102:105], v[98:101], v[82:97]
	s_waitcnt lgkmcnt(0)
	v_mfma_f32_32x32x16_bf16 v[66:81], v[106:109], v[98:101], v[66:81]
	v_add_f32_e32 v98, 0, v197
	v_add_f32_e32 v98, v199, v98
	v_add_f32_e32 v98, v195, v98
	v_add_f32_e32 v98, v198, v98
	v_add_f32_e32 v98, v193, v98
	v_add_f32_e32 v98, v196, v98
	v_add_f32_e32 v98, v192, v98
	v_add_f32_e32 v98, v194, v98
	v_add_f32_e32 v98, v189, v98
	v_add_f32_e32 v98, v191, v98
	v_add_f32_e32 v98, v187, v98
	v_add_f32_e32 v98, v190, v98
	v_exp_f32_e32 v108, v146
	v_add_f32_e32 v98, v185, v98
	v_exp_f32_e32 v109, v147
	v_add_f32_e32 v98, v188, v98
	v_exp_f32_e32 v110, v144
	v_add_f32_e32 v98, v184, v98
	v_exp_f32_e32 v111, v145
	v_add_f32_e32 v98, v186, v98
	v_exp_f32_e32 v112, v142
	v_add_f32_e32 v98, v108, v98
	v_exp_f32_e32 v113, v143
	v_add_f32_e32 v98, v109, v98
	v_exp_f32_e32 v115, v140
	v_add_f32_e32 v98, v110, v98
	v_exp_f32_e32 v116, v141
	v_add_f32_e32 v98, v111, v98
	v_exp_f32_e32 v117, v138
	v_add_f32_e32 v98, v112, v98
	v_exp_f32_e32 v118, v139
	v_add_f32_e32 v98, v113, v98
	v_exp_f32_e32 v119, v136
	v_add_f32_e32 v98, v115, v98
	v_exp_f32_e32 v120, v137
	v_add_f32_e32 v98, v116, v98
	v_exp_f32_e32 v121, v134
	v_add_f32_e32 v98, v117, v98
	v_exp_f32_e32 v122, v135
	v_add_f32_e32 v98, v118, v98
	v_exp_f32_e32 v123, v132
	v_add_f32_e32 v98, v119, v98
	v_exp_f32_e32 v124, v133
	v_add_f32_e32 v98, v120, v98
	v_add_f32_e32 v98, v121, v98
	v_add_f32_e32 v98, v122, v98
	v_add_f32_e32 v98, v123, v98
	v_add_f32_e32 v98, v124, v98
	v_mov_b32_e32 v99, v98
	s_nop 1
	v_permlane32_swap_b32_e32 v98, v99
	v_cvt_pk_bf16_f32 v100, v197, v199
	v_cvt_pk_bf16_f32 v101, v195, v198
	v_cvt_pk_bf16_f32 v102, v193, v196
	v_cvt_pk_bf16_f32 v103, v192, v194
	v_cvt_pk_bf16_f32 v104, v189, v191
	v_cvt_pk_bf16_f32 v105, v187, v190
	v_cvt_pk_bf16_f32 v106, v185, v188
	v_cvt_pk_bf16_f32 v107, v184, v186
	v_cvt_pk_bf16_f32 v108, v108, v109
	v_cvt_pk_bf16_f32 v109, v110, v111
	v_cvt_pk_bf16_f32 v110, v112, v113
	v_cvt_pk_bf16_f32 v111, v115, v116
	v_cvt_pk_bf16_f32 v116, v117, v118
	v_cvt_pk_bf16_f32 v117, v119, v120
	v_cvt_pk_bf16_f32 v118, v121, v122
	v_cvt_pk_bf16_f32 v119, v123, v124
	s_nop 0
	v_permlane32_swap_b32_e32 v100, v102
	v_permlane32_swap_b32_e32 v101, v103
	v_permlane32_swap_b32_e32 v104, v106
	v_permlane32_swap_b32_e32 v105, v107
	v_permlane32_swap_b32_e32 v108, v110
	v_permlane32_swap_b32_e32 v109, v111
	v_permlane32_swap_b32_e32 v116, v118
	v_permlane32_swap_b32_e32 v117, v119
	ds_read_b64_tr_b16 v[120:121], v153 offset:0
	ds_read_b64_tr_b16 v[122:123], v153 offset:0x800
	ds_read_b64_tr_b16 v[124:125], v153 offset:0x1000
	s_waitcnt vmcnt(0)
	ds_read_b64_tr_b16 v[126:127], v153 offset:0x1800
	ds_read_b64_tr_b16 v[128:129], v153 offset:0x2000
	ds_read_b64_tr_b16 v[130:131], v153 offset:0x2800
	ds_read_b64_tr_b16 v[132:133], v153 offset:0x3000
	ds_read_b64_tr_b16 v[134:135], v153 offset:0x3800
	s_waitcnt lgkmcnt(4)
	v_mfma_f32_32x32x16_bf16 v[50:65], v[100:103], v[120:123], v[50:65]
	ds_read_b64_tr_b16 v[120:121], v153 offset:0x200
	ds_read_b64_tr_b16 v[122:123], v153 offset:0xa00
	v_mfma_f32_32x32x16_bf16 v[50:65], v[104:107], v[124:127], v[50:65]
	ds_read_b64_tr_b16 v[124:125], v153 offset:0x1200
	ds_read_b64_tr_b16 v[126:127], v153 offset:0x1a00
	s_waitcnt lgkmcnt(4)
	v_mfma_f32_32x32x16_bf16 v[50:65], v[108:111], v[128:131], v[50:65]
	ds_read_b64_tr_b16 v[128:129], v153 offset:0x2200
	ds_read_b64_tr_b16 v[130:131], v153 offset:0x2a00
	v_mfma_f32_32x32x16_bf16 v[50:65], v[116:119], v[132:135], v[50:65]
	ds_read_b64_tr_b16 v[132:133], v153 offset:0x3200
	ds_read_b64_tr_b16 v[134:135], v153 offset:0x3a00
	s_waitcnt lgkmcnt(4)
	v_mfma_f32_32x32x16_bf16 v[34:49], v[100:103], v[120:123], v[34:49]
	ds_read_b64_tr_b16 v[120:121], v153 offset:0x400
	ds_read_b64_tr_b16 v[122:123], v153 offset:0xc00
	v_mfma_f32_32x32x16_bf16 v[34:49], v[104:107], v[124:127], v[34:49]
	ds_read_b64_tr_b16 v[124:125], v153 offset:0x1400
	ds_read_b64_tr_b16 v[126:127], v153 offset:0x1c00
	s_waitcnt lgkmcnt(4)
	v_mfma_f32_32x32x16_bf16 v[34:49], v[108:111], v[128:131], v[34:49]
	ds_read_b64_tr_b16 v[128:129], v153 offset:0x2400
	ds_read_b64_tr_b16 v[130:131], v153 offset:0x2c00
	v_mfma_f32_32x32x16_bf16 v[34:49], v[116:119], v[132:135], v[34:49]
	ds_read_b64_tr_b16 v[132:133], v153 offset:0x3400
	ds_read_b64_tr_b16 v[134:135], v153 offset:0x3c00
	s_waitcnt lgkmcnt(4)
	v_mfma_f32_32x32x16_bf16 v[18:33], v[100:103], v[120:123], v[18:33]
	ds_read_b64_tr_b16 v[120:121], v153 offset:0x600
	ds_read_b64_tr_b16 v[122:123], v153 offset:0xe00
	v_mfma_f32_32x32x16_bf16 v[18:33], v[104:107], v[124:127], v[18:33]
	ds_read_b64_tr_b16 v[124:125], v153 offset:0x1600
	ds_read_b64_tr_b16 v[126:127], v153 offset:0x1e00
	s_waitcnt lgkmcnt(4)
	v_mfma_f32_32x32x16_bf16 v[18:33], v[108:111], v[128:131], v[18:33]
	ds_read_b64_tr_b16 v[128:129], v153 offset:0x2600
	ds_read_b64_tr_b16 v[130:131], v153 offset:0x2e00
	v_mfma_f32_32x32x16_bf16 v[18:33], v[116:119], v[132:135], v[18:33]
	ds_read_b64_tr_b16 v[132:133], v153 offset:0x3600
	ds_read_b64_tr_b16 v[134:135], v153 offset:0x3e00
	s_waitcnt lgkmcnt(4)
	v_mfma_f32_32x32x16_bf16 v[2:17], v[100:103], v[120:123], v[2:17]
	s_lshl_b32 s0, s27, 6
	s_add_i32 s1, s0, -1
	s_cmp_gt_i32 s1, s25
	v_mfma_f32_32x32x16_bf16 v[2:17], v[104:107], v[124:127], v[2:17]
	s_waitcnt lgkmcnt(0)
	v_mfma_f32_32x32x16_bf16 v[2:17], v[108:111], v[128:131], v[2:17]
	v_mfma_f32_32x32x16_bf16 v[2:17], v[116:119], v[132:135], v[2:17]
	s_cbranch_scc0 .LBB0_844
	v_subrev_u32_e32 v100, s0, v156
	v_add_u32_e32 v100, 64, v100
	v_cmp_gt_i32_e64 s[90:91], 26, v100
	v_cmp_gt_i32_e64 s[92:93], 27, v100
	v_cmp_gt_i32_e64 s[88:89], 25, v100
	s_and_b64 s[90:91], s[92:93], s[90:91]
	v_cmp_gt_i32_e64 s[86:87], 24, v100
	s_and_b64 s[88:89], s[90:91], s[88:89]
	v_cmp_gt_i32_e64 s[84:85], 19, v100
	s_and_b64 s[86:87], s[88:89], s[86:87]
	v_cmp_gt_i32_e64 s[82:83], 18, v100
	s_and_b64 s[84:85], s[86:87], s[84:85]
	v_cmp_gt_i32_e64 s[80:81], 17, v100
	s_and_b64 s[82:83], s[84:85], s[82:83]
	v_cmp_gt_i32_e64 s[78:79], 16, v100
	s_and_b64 s[80:81], s[82:83], s[80:81]
	v_cmp_gt_i32_e64 s[76:77], 11, v100
	s_and_b64 s[78:79], s[80:81], s[78:79]
	v_cmp_gt_i32_e64 s[74:75], 10, v100
	s_and_b64 s[76:77], s[78:79], s[76:77]
	v_cmp_gt_i32_e64 s[72:73], 9, v100
	s_and_b64 s[74:75], s[76:77], s[74:75]
	v_cmp_gt_i32_e64 s[70:71], 8, v100
	s_and_b64 s[72:73], s[74:75], s[72:73]
	v_cmp_gt_i32_e64 s[68:69], 3, v100
	s_and_b64 s[70:71], s[72:73], s[70:71]
	v_cmp_gt_i32_e64 s[66:67], 2, v100
	s_and_b64 s[68:69], s[70:71], s[68:69]
	v_cmp_gt_i32_e64 s[2:3], 1, v100
	s_and_b64 s[66:67], s[68:69], s[66:67]
	v_cmp_gt_i32_e64 s[0:1], 0, v100
	s_and_b64 s[2:3], s[66:67], s[2:3]
	s_and_b64 s[0:1], s[2:3], s[0:1]
	v_cmp_gt_i32_e64 s[64:65], 58, v100
	v_cndmask_b32_e64 v82, v82, v175, s[0:1]
	v_cmp_gt_i32_e64 s[0:1], 59, v100
	v_cmp_gt_i32_e64 s[62:63], 57, v100
	v_cmp_gt_i32_e64 s[60:61], 56, v100
	v_cndmask_b32_e64 v81, v81, v175, s[0:1]
	s_and_b64 s[0:1], s[0:1], s[64:65]
	v_cndmask_b32_e64 v80, v80, v175, s[0:1]
	s_and_b64 s[0:1], s[0:1], s[62:63]
	v_cmp_gt_i32_e64 s[58:59], 51, v100
	v_cndmask_b32_e64 v79, v79, v175, s[0:1]
	s_and_b64 s[0:1], s[0:1], s[60:61]
	v_cmp_gt_i32_e64 s[56:57], 50, v100
	v_cndmask_b32_e64 v78, v78, v175, s[0:1]
	s_and_b64 s[0:1], s[0:1], s[58:59]
	v_cmp_gt_i32_e64 s[54:55], 49, v100
	v_cndmask_b32_e64 v77, v77, v175, s[0:1]
	s_and_b64 s[0:1], s[0:1], s[56:57]
	v_cmp_gt_i32_e64 s[52:53], 48, v100
	v_cndmask_b32_e64 v76, v76, v175, s[0:1]
	s_and_b64 s[0:1], s[0:1], s[54:55]
	v_cmp_gt_i32_e64 s[50:51], 43, v100
	v_cndmask_b32_e64 v75, v75, v175, s[0:1]
	s_and_b64 s[0:1], s[0:1], s[52:53]
	v_cmp_gt_i32_e64 s[48:49], 42, v100
	v_cndmask_b32_e64 v74, v74, v175, s[0:1]
	s_and_b64 s[0:1], s[0:1], s[50:51]
	v_cmp_gt_i32_e64 s[46:47], 41, v100
	v_cndmask_b32_e64 v73, v73, v175, s[0:1]
	s_and_b64 s[0:1], s[0:1], s[48:49]
	v_cmp_gt_i32_e64 s[44:45], 40, v100
	v_cndmask_b32_e64 v72, v72, v175, s[0:1]
	s_and_b64 s[0:1], s[0:1], s[46:47]
	v_cmp_gt_i32_e64 s[42:43], 35, v100
	v_cndmask_b32_e64 v71, v71, v175, s[0:1]
	s_and_b64 s[0:1], s[0:1], s[44:45]
	v_cmp_gt_i32_e64 s[40:41], 34, v100
	v_cndmask_b32_e64 v70, v70, v175, s[0:1]
	s_and_b64 s[0:1], s[0:1], s[42:43]
	v_cmp_gt_i32_e64 s[38:39], 33, v100
	v_cndmask_b32_e64 v69, v69, v175, s[0:1]
	s_and_b64 s[0:1], s[0:1], s[40:41]
	v_cmp_gt_i32_e32 vcc, 32, v100
	v_cndmask_b32_e64 v68, v68, v175, s[0:1]
	s_and_b64 s[0:1], s[0:1], s[38:39]
	s_and_b64 vcc, s[0:1], vcc
	v_cndmask_b32_e64 v97, v97, v175, s[92:93]
	v_cndmask_b32_e64 v96, v96, v175, s[90:91]
	v_cndmask_b32_e64 v95, v95, v175, s[88:89]
	v_cndmask_b32_e64 v94, v94, v175, s[86:87]
	v_cndmask_b32_e64 v93, v93, v175, s[84:85]
	v_cndmask_b32_e64 v92, v92, v175, s[82:83]
	v_cndmask_b32_e64 v91, v91, v175, s[80:81]
	v_cndmask_b32_e64 v90, v90, v175, s[78:79]
	v_cndmask_b32_e64 v89, v89, v175, s[76:77]
	v_cndmask_b32_e64 v88, v88, v175, s[74:75]
	v_cndmask_b32_e64 v87, v87, v175, s[72:73]
	v_cndmask_b32_e64 v86, v86, v175, s[70:71]
	v_cndmask_b32_e64 v85, v85, v175, s[68:69]
	v_cndmask_b32_e64 v84, v84, v175, s[66:67]
	v_cndmask_b32_e64 v83, v83, v175, s[2:3]
	v_cndmask_b32_e64 v67, v67, v175, s[0:1]
	v_cndmask_b32_e32 v66, v66, v175, vcc

.LBB0_848:
	v_cndmask_b32_e64 v101, v101, v168, s[38:39]
	v_mul_f32_e32 v101, 0xbe38aa3b, v101
	v_fmamk_f32 v82, v82, 0x3e38aa3b, v101
	v_fmamk_f32 v66, v66, 0x3e38aa3b, v101
	v_fmamk_f32 v83, v83, 0x3e38aa3b, v101
	v_fmamk_f32 v67, v67, 0x3e38aa3b, v101
	v_fmamk_f32 v84, v84, 0x3e38aa3b, v101
	v_fmamk_f32 v68, v68, 0x3e38aa3b, v101
	v_fmamk_f32 v85, v85, 0x3e38aa3b, v101
	v_fmamk_f32 v69, v69, 0x3e38aa3b, v101
	v_fmamk_f32 v86, v86, 0x3e38aa3b, v101
	v_fmamk_f32 v70, v70, 0x3e38aa3b, v101
	v_fmamk_f32 v87, v87, 0x3e38aa3b, v101
	v_fmamk_f32 v71, v71, 0x3e38aa3b, v101
	v_fmamk_f32 v88, v88, 0x3e38aa3b, v101
	v_fmamk_f32 v72, v72, 0x3e38aa3b, v101
	v_fmamk_f32 v89, v89, 0x3e38aa3b, v101
	v_fmamk_f32 v73, v73, 0x3e38aa3b, v101
	v_fmamk_f32 v90, v90, 0x3e38aa3b, v101
	v_fmamk_f32 v74, v74, 0x3e38aa3b, v101
	v_fmamk_f32 v91, v91, 0x3e38aa3b, v101
	v_fmamk_f32 v75, v75, 0x3e38aa3b, v101
	v_fmamk_f32 v92, v92, 0x3e38aa3b, v101
	v_fmamk_f32 v76, v76, 0x3e38aa3b, v101
	v_fmamk_f32 v93, v93, 0x3e38aa3b, v101
	v_fmamk_f32 v77, v77, 0x3e38aa3b, v101
	v_fmamk_f32 v94, v94, 0x3e38aa3b, v101
	v_fmamk_f32 v78, v78, 0x3e38aa3b, v101
	v_fmamk_f32 v95, v95, 0x3e38aa3b, v101
	v_fmamk_f32 v79, v79, 0x3e38aa3b, v101
	v_fmamk_f32 v96, v96, 0x3e38aa3b, v101
	v_fmamk_f32 v80, v80, 0x3e38aa3b, v101
	v_fmamk_f32 v97, v97, 0x3e38aa3b, v101
	v_fmac_f32_e32 v101, 0x3e38aa3b, v81
	v_exp_f32_e32 v81, v82
	v_exp_f32_e32 v82, v83
	v_exp_f32_e32 v83, v84
	v_exp_f32_e32 v84, v85
	v_exp_f32_e32 v85, v86
	v_exp_f32_e32 v86, v87
	v_exp_f32_e32 v87, v88
	v_exp_f32_e32 v88, v89
	v_exp_f32_e32 v89, v90
	v_exp_f32_e32 v90, v91
	v_exp_f32_e32 v91, v92
	v_exp_f32_e32 v92, v93
	v_exp_f32_e32 v93, v94
	v_exp_f32_e32 v94, v95
	v_exp_f32_e32 v95, v96
	v_exp_f32_e32 v96, v97
	v_exp_f32_e32 v97, v66
	v_add_f32_e32 v66, 0, v81
	v_add_f32_e32 v66, v82, v66
	v_add_f32_e32 v66, v83, v66
	v_add_f32_e32 v66, v84, v66
	v_add_f32_e32 v66, v85, v66
	v_add_f32_e32 v66, v86, v66
	v_add_f32_e32 v66, v87, v66
	v_add_f32_e32 v66, v88, v66
	v_add_f32_e32 v66, v89, v66
	v_add_f32_e32 v66, v90, v66
	v_add_f32_e32 v66, v91, v66
	v_add_f32_e32 v66, v92, v66
	v_add_f32_e32 v66, v93, v66
	v_exp_f32_e32 v102, v67
	v_add_f32_e32 v66, v94, v66
	v_exp_f32_e32 v103, v68
	v_add_f32_e32 v66, v95, v66
	v_exp_f32_e32 v104, v69
	v_add_f32_e32 v66, v96, v66
	v_exp_f32_e32 v105, v70
	v_add_f32_e32 v66, v97, v66
	v_exp_f32_e32 v106, v71
	v_add_f32_e32 v66, v102, v66
	v_exp_f32_e32 v107, v72
	v_add_f32_e32 v66, v103, v66
	v_exp_f32_e32 v108, v73
	v_add_f32_e32 v66, v104, v66
	v_exp_f32_e32 v109, v74
	v_add_f32_e32 v66, v105, v66
	v_exp_f32_e32 v110, v75
	v_add_f32_e32 v66, v106, v66
	v_exp_f32_e32 v111, v76
	v_add_f32_e32 v66, v107, v66
	v_exp_f32_e32 v112, v77
	v_add_f32_e32 v66, v108, v66
	v_exp_f32_e32 v113, v78
	v_add_f32_e32 v66, v109, v66
	v_exp_f32_e32 v115, v79
	v_add_f32_e32 v66, v110, v66
	v_exp_f32_e32 v116, v80
	v_add_f32_e32 v66, v111, v66
	v_exp_f32_e32 v101, v101
	v_add_f32_e32 v66, v112, v66
	v_add_f32_e32 v66, v113, v66
	v_add_f32_e32 v66, v115, v66
	v_add_f32_e32 v66, v116, v66
	v_add_f32_e32 v66, v101, v66
	v_mov_b32_e32 v67, v66
	s_nop 1
	v_permlane32_swap_b32_e32 v66, v67
	v_cvt_pk_bf16_f32 v68, v81, v82
	v_cvt_pk_bf16_f32 v69, v83, v84
	v_cvt_pk_bf16_f32 v70, v85, v86
	v_cvt_pk_bf16_f32 v71, v87, v88
	v_cvt_pk_bf16_f32 v72, v89, v90
	v_cvt_pk_bf16_f32 v73, v91, v92
	v_cvt_pk_bf16_f32 v74, v93, v94
	v_cvt_pk_bf16_f32 v75, v95, v96
	v_cvt_pk_bf16_f32 v76, v97, v102
	v_cvt_pk_bf16_f32 v77, v103, v104
	v_cvt_pk_bf16_f32 v78, v105, v106
	v_cvt_pk_bf16_f32 v79, v107, v108
	v_cvt_pk_bf16_f32 v80, v109, v110
	v_cvt_pk_bf16_f32 v81, v111, v112
	v_cvt_pk_bf16_f32 v82, v113, v115
	v_cvt_pk_bf16_f32 v83, v116, v101
	s_nop 0
	v_permlane32_swap_b32_e32 v68, v70
	v_permlane32_swap_b32_e32 v69, v71
	v_permlane32_swap_b32_e32 v72, v74
	v_permlane32_swap_b32_e32 v73, v75
	v_permlane32_swap_b32_e32 v76, v78
	v_permlane32_swap_b32_e32 v77, v79
	v_permlane32_swap_b32_e32 v80, v82
	v_permlane32_swap_b32_e32 v81, v83
	ds_read_b64_tr_b16 v[84:85], v153 offset:0x4000
	ds_read_b64_tr_b16 v[86:87], v153 offset:0x4800
	ds_read_b64_tr_b16 v[88:89], v153 offset:0x5000
	ds_read_b64_tr_b16 v[90:91], v153 offset:0x5800
	ds_read_b64_tr_b16 v[92:93], v153 offset:0x6000
	ds_read_b64_tr_b16 v[94:95], v153 offset:0x6800
	ds_read_b64_tr_b16 v[102:103], v153 offset:0x7000
	ds_read_b64_tr_b16 v[104:105], v153 offset:0x7800
	s_nop 0
	s_waitcnt lgkmcnt(4)
	v_mfma_f32_32x32x16_bf16 v[50:65], v[68:71], v[84:87], v[50:65]
	ds_read_b64_tr_b16 v[84:85], v153 offset:0x4200
	ds_read_b64_tr_b16 v[86:87], v153 offset:0x4a00
	v_mfma_f32_32x32x16_bf16 v[50:65], v[72:75], v[88:91], v[50:65]
	ds_read_b64_tr_b16 v[88:89], v153 offset:0x5200
	ds_read_b64_tr_b16 v[90:91], v153 offset:0x5a00
	s_waitcnt lgkmcnt(4)
	v_mfma_f32_32x32x16_bf16 v[50:65], v[76:79], v[92:95], v[50:65]
	ds_read_b64_tr_b16 v[92:93], v153 offset:0x6200
	ds_read_b64_tr_b16 v[94:95], v153 offset:0x6a00
	v_mfma_f32_32x32x16_bf16 v[50:65], v[80:83], v[102:105], v[50:65]
	ds_read_b64_tr_b16 v[102:103], v153 offset:0x7200
	ds_read_b64_tr_b16 v[104:105], v153 offset:0x7a00
	s_waitcnt lgkmcnt(4)
	v_mfma_f32_32x32x16_bf16 v[34:49], v[68:71], v[84:87], v[34:49]
	ds_read_b64_tr_b16 v[84:85], v153 offset:0x4400
	ds_read_b64_tr_b16 v[86:87], v153 offset:0x4c00
	v_mfma_f32_32x32x16_bf16 v[34:49], v[72:75], v[88:91], v[34:49]
	ds_read_b64_tr_b16 v[88:89], v153 offset:0x5400
	ds_read_b64_tr_b16 v[90:91], v153 offset:0x5c00
	s_waitcnt lgkmcnt(4)
	v_mfma_f32_32x32x16_bf16 v[34:49], v[76:79], v[92:95], v[34:49]
	ds_read_b64_tr_b16 v[92:93], v153 offset:0x6400
	ds_read_b64_tr_b16 v[94:95], v153 offset:0x6c00
	v_mfma_f32_32x32x16_bf16 v[34:49], v[80:83], v[102:105], v[34:49]
	ds_read_b64_tr_b16 v[102:103], v153 offset:0x7400
	ds_read_b64_tr_b16 v[104:105], v153 offset:0x7c00
	s_waitcnt lgkmcnt(4)
	v_mfma_f32_32x32x16_bf16 v[18:33], v[68:71], v[84:87], v[18:33]
	ds_read_b64_tr_b16 v[84:85], v153 offset:0x4600
	ds_read_b64_tr_b16 v[86:87], v153 offset:0x4e00
	v_mfma_f32_32x32x16_bf16 v[18:33], v[72:75], v[88:91], v[18:33]
	ds_read_b64_tr_b16 v[88:89], v153 offset:0x5600
	ds_read_b64_tr_b16 v[90:91], v153 offset:0x5e00
	s_waitcnt lgkmcnt(4)
	v_mfma_f32_32x32x16_bf16 v[18:33], v[76:79], v[92:95], v[18:33]
	ds_read_b64_tr_b16 v[92:93], v153 offset:0x6600
	ds_read_b64_tr_b16 v[94:95], v153 offset:0x6e00
	v_mfma_f32_32x32x16_bf16 v[18:33], v[80:83], v[102:105], v[18:33]
	ds_read_b64_tr_b16 v[102:103], v153 offset:0x7600
	ds_read_b64_tr_b16 v[104:105], v153 offset:0x7e00
	s_waitcnt lgkmcnt(4)
	v_mfma_f32_32x32x16_bf16 v[2:17], v[68:71], v[84:87], v[2:17]
	v_cmp_gt_u32_e32 vcc, 32, v149
	v_mfma_f32_32x32x16_bf16 v[2:17], v[72:75], v[88:91], v[2:17]
	s_waitcnt lgkmcnt(0)
	v_mfma_f32_32x32x16_bf16 v[2:17], v[76:79], v[92:95], v[2:17]
	v_mfma_f32_32x32x16_bf16 v[2:17], v[80:83], v[102:105], v[2:17]
	s_and_saveexec_b64 s[0:1], vcc
	v_add_f32_e32 v68, v98, v99
	v_fmac_f32_e32 v68, v157, v114
	v_add_f32_e32 v66, v66, v67
	v_fmac_f32_e32 v66, v68, v100
	ds_write_b32 v155, v66
	s_or_b64 exec, exec, s[0:1]
	s_waitcnt lgkmcnt(0)
	ds_read_b128 v[78:81], v154
	ds_read_b128 v[74:77], v154 offset:32
	ds_read_b128 v[70:73], v154 offset:64
	ds_read_b128 v[66:69], v154 offset:96
	s_lshl_b32 s0, s29, 13
	s_waitcnt lgkmcnt(3)
	v_rcp_f32_e32 v82, v78
	v_and_b32_e32 v78, 1, v150
	s_add_i32 s2, s0, 0
	v_cmp_eq_u32_e32 vcc, 0, v78
	v_lshlrev_b32_e32 v78, 10, v152
	v_lshlrev_b32_e32 v83, 1, v151
	v_mul_f32_e32 v50, v50, v82
	v_add3_u32 v78, s2, v78, v83
	s_waitcnt lgkmcnt(0)
	v_mov_b32_dpp v83, v50 quad_perm:[1,0,3,2] row_mask:0xf bank_mask:0xf bound_ctrl:1
	s_barrier
	s_and_saveexec_b64 s[0:1], vcc
	s_cbranch_execz .LBB0_852
	v_cvt_pk_bf16_f32 v50, v50, v83
	ds_write_b32 v78, v50

.LBB0_1414:
	s_ashr_i32 s4, s34, 5
	v_readlane_b32 s0, v243, 52
	s_add_i32 s0, s4, s0
	s_ashr_i32 s1, s0, 31
	s_and_b32 s2, s29, 0xe0000
	s_lshl_b64 s[0:1], s[0:1], 20
	s_or_b32 s0, s0, s2
	s_lshl_b64 s[0:1], s[0:1], 1
	v_readlane_b32 s2, v245, 20
	s_add_u32 s2, s2, s0
	v_readlane_b32 s3, v245, 23
	s_addc_u32 s5, s3, s1
	s_and_b32 s3, s28, 0x180
	s_waitcnt vmcnt(0)
	v_mov_b32_e32 v155, v0
	s_lshl_b32 s3, s3, 1
	s_add_u32 s18, s2, s3
	v_ashrrev_i32_e32 v146, 4, v155
	v_lshlrev_b32_e32 v2, 3, v155
	v_and_b32_e32 v4, 0xfffff0, v146
	v_lshlrev_b32_e32 v5, 1, v146
	s_addc_u32 s19, s5, 0
	s_ashr_i32 s5, s4, 31
	v_and_b32_e32 v3, 0x78, v2
	v_and_or_b32 v4, v5, 8, v4
	v_lshrrev_b32_e32 v5, 1, v146
	v_and_b32_e32 v6, 3, v146
	v_add_u32_e32 v8, 32, v146
	s_lshl_b64 s[4:5], s[4:5], 19
	v_and_or_b32 v5, v5, 4, v6
	s_waitcnt vmcnt(0) lgkmcnt(0)
	v_lshlrev_b32_e32 v50, 1, v3
	v_and_b32_e32 v3, 0xfffff0, v8
	v_lshlrev_b32_e32 v6, 1, v8
	s_add_u32 s2, s22, s4
	v_and_or_b32 v3, v6, 8, v3
	s_addc_u32 s5, s23, s5
	v_lshrrev_b32_e32 v4, 1, v4
	v_bfe_u32 v2, v2, 5, 2
	v_lshrrev_b32_e32 v3, 1, v3
	s_add_u32 s4, s2, s3
	v_readfirstlane_b32 s2, v155
	v_or_b32_e32 v4, v4, v2
	v_or_b32_e32 v2, v3, v2
	s_addc_u32 s5, s5, 0
	s_ashr_i32 s35, s2, 6
	v_and_b32_e32 v1, 63, v155
	s_and_b32 s2, s2, 0x3fffffc0
	v_lshlrev_b32_e32 v6, 9, v2
	v_lshlrev_b32_e32 v2, 8, v146
	v_and_b32_e32 v3, 0x70, v155
	v_lshlrev_b32_e32 v154, 4, v155
	s_lshl_b32 s2, s2, 2
	v_bitop3_b32 v20, v50, v2, v3 bitop3:0xde
	v_lshlrev_b32_e32 v2, 3, v1
	v_and_b32_e32 v3, 0xc0, v154
	v_lshlrev_b32_e32 v7, 1, v155
	v_and_b32_e32 v156, 31, v155
	s_add_i32 s42, s2, 0
	v_and_or_b32 v3, v2, 24, v3
	v_and_b32_e32 v7, 32, v7
	v_and_b32_e32 v2, 0x100, v2
	s_lshl_b32 s2, s35, 5
	v_or3_b32 v7, v3, v7, v2
	v_or_b32_e32 v2, s2, v156
	v_ashrrev_i32_e32 v3, 31, v2
	v_bfe_u32 v157, v155, 5, 1
	v_lshlrev_b64 v[2:3], 10, v[2:3]
	v_lshl_add_u64 v[2:3], s[18:19], 0, v[2:3]
	v_lshlrev_b32_e32 v162, 4, v157
	v_lshl_add_u64 v[2:3], v[2:3], 0, v[162:163]
	v_ashrrev_i32_e32 v147, 31, v146
	v_ashrrev_i32_e32 v9, 31, v8
	v_lshlrev_b32_e32 v4, 9, v4
	v_lshlrev_b32_e32 v5, 6, v5
	global_load_dwordx4 v[126:129], v[2:3], off
	global_load_dwordx4 v[122:125], v[2:3], off offset:32
	global_load_dwordx4 v[118:121], v[2:3], off offset:64
	global_load_dwordx4 v[114:117], v[2:3], off offset:96
	global_load_dwordx4 v[110:113], v[2:3], off offset:128
	global_load_dwordx4 v[106:109], v[2:3], off offset:160
	global_load_dwordx4 v[102:105], v[2:3], off offset:192
	global_load_dwordx4 v[98:101], v[2:3], off offset:224
	v_and_b32_e32 v2, 48, v50
	v_lshlrev_b64 v[52:53], 11, v[146:147]
	v_lshlrev_b64 v[8:9], 11, v[8:9]
	v_or3_b32 v21, v4, v5, v2
	v_or3_b32 v22, v6, v5, v2
	v_mov_b32_e32 v51, v163
	v_lshl_add_u64 v[2:3], s[4:5], 0, v[52:53]
	v_lshl_add_u64 v[8:9], s[4:5], 0, v[8:9]
	v_lshl_add_u64 v[2:3], v[2:3], 0, v[50:51]
	v_lshl_add_u64 v[16:17], v[8:9], 0, v[50:51]
	v_add_u32_e32 v158, 0, v7
	global_load_dwordx4 v[4:7], v[2:3], off offset:1024
	global_load_dwordx4 v[8:11], v[16:17], off offset:1024
	global_load_dwordx4 v[12:15], v[2:3], off
	s_nop 0
	global_load_dwordx4 v[16:19], v[16:17], off
	v_add_u32_e32 v165, 0, v20
	v_add_u32_e32 v166, 0, v21
	s_mov_b64 s[8:9], 0x20000
	v_add_u32_e32 v167, 0, v22
	s_add_i32 s42, s42, 0x10000
	s_waitcnt vmcnt(1)
	ds_write_b128 v165, v[12:15] offset:32768
	s_waitcnt vmcnt(0)
	ds_write_b128 v165, v[16:19] offset:40960
	ds_write_b128 v166, v[4:7]
	v_lshl_add_u64 v[4:5], v[2:3], 0, s[8:9]
	s_mov_b64 s[8:9], 0x30000
	ds_write_b128 v167, v[8:11]
	s_waitcnt lgkmcnt(0)
	s_barrier
	global_load_dwordx4 v[34:37], v[4:5], off offset:1024
	v_lshl_add_u64 v[4:5], v[2:3], 0, s[8:9]
	s_mov_b32 s8, 0x20000
	global_load_dwordx4 v[38:41], v[4:5], off offset:1024
	v_add_co_u32_e32 v4, vcc, s8, v2
	s_mov_b32 s8, 0x30000
	s_nop 0
	v_addc_co_u32_e32 v5, vcc, 0, v3, vcc
	v_add_co_u32_e32 v2, vcc, s8, v2
	global_load_dwordx4 v[42:45], v[4:5], off
	s_nop 0
	v_addc_co_u32_e32 v3, vcc, 0, v3, vcc
	global_load_dwordx4 v[46:49], v[2:3], off
	s_movk_i32 s8, 0x70
	v_and_b32_e32 v2, 0x70, v154
	v_lshl_add_u32 v3, v156, 8, 0
	v_bitop3_b32 v4, v162, v154, s8 bitop3:0x78
	v_add_u32_e32 v168, v3, v4
	v_bitop3_b32 v4, v162, v2, 32 bitop3:0x36
	s_movk_i32 s8, 0x60
	v_add_u32_e32 v164, v3, v4
	v_bitop3_b32 v4, v162, v2, 64 bitop3:0x36
	v_bitop3_b32 v2, v162, v2, s8 bitop3:0x36
	v_add_u32_e32 v161, v3, v4
	v_add_u32_e32 v160, v3, v2
	ds_read_b128 v[2:5], v168 offset:32768
	ds_read_b128 v[18:21], v168 offset:40960
	s_waitcnt lgkmcnt(1)
	v_mfma_f32_32x32x16_bf16 v[2:17], v[2:5], v[126:129], 0
	ds_read_b128 v[54:57], v164 offset:32768
	ds_read_b128 v[58:61], v164 offset:40960
	v_lshl_add_u64 v[148:149], s[4:5], 0, v[50:51]
	s_mov_b64 s[4:5], 0x40000
	v_cmp_gt_u32_e64 s[38:39], 32, v1
	v_lshl_add_u32 v159, v156, 2, s42
	s_waitcnt lgkmcnt(2)
	v_mfma_f32_32x32x16_bf16 v[18:33], v[18:21], v[126:129], 0
	s_waitcnt lgkmcnt(1)
	v_mfma_f32_32x32x16_bf16 v[2:17], v[54:57], v[122:125], v[2:17]
	s_waitcnt lgkmcnt(0)
	v_mfma_f32_32x32x16_bf16 v[18:33], v[58:61], v[122:125], v[18:33]
	ds_read_b128 v[54:57], v161 offset:32768
	ds_read_b128 v[58:61], v161 offset:40960
	s_waitcnt lgkmcnt(1)
	v_mfma_f32_32x32x16_bf16 v[2:17], v[54:57], v[118:121], v[2:17]
	s_waitcnt lgkmcnt(0)
	v_mfma_f32_32x32x16_bf16 v[18:33], v[58:61], v[118:121], v[18:33]
	ds_read_b128 v[54:57], v160 offset:32768
	ds_read_b128 v[58:61], v160 offset:40960
	s_waitcnt lgkmcnt(1)
	v_mfma_f32_32x32x16_bf16 v[2:17], v[54:57], v[114:117], v[2:17]
	s_waitcnt lgkmcnt(0)
	v_mfma_f32_32x32x16_bf16 v[18:33], v[58:61], v[114:117], v[18:33]
	ds_read_b128 v[54:57], v168 offset:32896
	ds_read_b128 v[58:61], v168 offset:41088
	s_waitcnt lgkmcnt(1)
	v_mfma_f32_32x32x16_bf16 v[2:17], v[54:57], v[110:113], v[2:17]
	s_waitcnt lgkmcnt(0)
	v_mfma_f32_32x32x16_bf16 v[18:33], v[58:61], v[110:113], v[18:33]
	ds_read_b128 v[54:57], v164 offset:32896
	ds_read_b128 v[58:61], v164 offset:41088
	s_waitcnt lgkmcnt(1)
	v_mfma_f32_32x32x16_bf16 v[2:17], v[54:57], v[106:109], v[2:17]
	s_waitcnt lgkmcnt(0)
	v_mfma_f32_32x32x16_bf16 v[18:33], v[58:61], v[106:109], v[18:33]
	ds_read_b128 v[54:57], v161 offset:32896
	ds_read_b128 v[58:61], v161 offset:41088
	s_waitcnt lgkmcnt(1)
	v_mfma_f32_32x32x16_bf16 v[2:17], v[54:57], v[102:105], v[2:17]
	s_waitcnt lgkmcnt(0)
	v_mfma_f32_32x32x16_bf16 v[18:33], v[58:61], v[102:105], v[18:33]
	ds_read_b128 v[54:57], v160 offset:32896
	ds_read_b128 v[58:61], v160 offset:41088
	s_waitcnt vmcnt(1)
	ds_write_b128 v165, v[42:45] offset:49152
	s_waitcnt vmcnt(0)
	ds_write_b128 v165, v[46:49] offset:57344
	ds_write_b128 v166, v[34:37] offset:16384
	ds_write_b128 v167, v[38:41] offset:16384
	v_lshl_add_u64 v[34:35], v[148:149], 0, v[52:53]
	v_lshl_add_u64 v[36:37], v[34:35], 0, s[4:5]
	s_mov_b64 s[4:5], 0x50000
	s_waitcnt lgkmcnt(0)
	s_barrier
	v_mfma_f32_32x32x16_bf16 v[2:17], v[54:57], v[98:101], v[2:17]
	global_load_dwordx4 v[130:133], v[36:37], off offset:1024
	v_lshl_add_u64 v[36:37], v[34:35], 0, s[4:5]
	s_mov_b32 s4, 0x40000
	global_load_dwordx4 v[134:137], v[36:37], off offset:1024
	s_nop 7
	v_max_f32_e32 v54, v3, v3
	v_max_f32_e32 v55, v2, v2
	v_mfma_f32_32x32x16_bf16 v[18:33], v[58:61], v[98:101], v[18:33]
	v_max_f32_e32 v54, v55, v54
	v_max3_f32 v54, v54, v4, v5
	v_max3_f32 v54, v54, v6, v7
	v_max3_f32 v54, v54, v8, v9
	v_max3_f32 v54, v54, v10, v11
	v_max3_f32 v54, v54, v12, v13
	v_max3_f32 v54, v54, v14, v15
	v_max3_f32 v54, v54, v16, v17
	s_nop 3
	v_max3_f32 v54, v54, v18, v19
	v_max3_f32 v54, v54, v20, v21
	v_max3_f32 v54, v54, v22, v23
	v_max3_f32 v54, v54, v24, v25
	v_max3_f32 v54, v54, v26, v27
	v_max3_f32 v54, v54, v28, v29
	v_max3_f32 v54, v54, v30, v31
	v_max3_f32 v54, v54, v32, v33
	v_mov_b32_e32 v55, v54
	s_nop 1
	v_permlane32_swap_b32_e32 v54, v55
	v_max_f32_e32 v55, v55, v55
	v_max_f32_e32 v54, v54, v54
	v_max_f32_e32 v54, v54, v55
	v_add_f32_e32 v55, 0x7149f2ca, v54
	v_mul_f32_e32 v55, 0x3e0293ee, v55
	v_cmp_ge_f32_e32 vcc, s24, v55
	s_cmp_eq_u64 vcc, exec
	v_add_co_u32_e32 v36, vcc, s4, v34
	s_mov_b32 s4, 0x50000
	s_nop 0
	v_addc_co_u32_e32 v37, vcc, 0, v35, vcc
	v_add_co_u32_e32 v34, vcc, s4, v34
	global_load_dwordx4 v[138:141], v[36:37], off
	s_nop 0
	v_addc_co_u32_e32 v35, vcc, 0, v35, vcc
	global_load_dwordx4 v[142:145], v[34:35], off
	s_cselect_b64 s[36:37], -1, 0
	v_max_f32_e32 v151, 0xf149f2ca, v54
	v_cndmask_b32_e64 v150, v151, v177, s[36:37]
	v_mul_f32_e32 v54, 0xbe0293ee, v150
	v_fmamk_f32 v2, v2, 0x3e0293ee, v54
	v_fmamk_f32 v3, v3, 0x3e0293ee, v54
	v_fmamk_f32 v4, v4, 0x3e0293ee, v54
	v_fmamk_f32 v5, v5, 0x3e0293ee, v54
	v_fmamk_f32 v6, v6, 0x3e0293ee, v54
	v_fmamk_f32 v7, v7, 0x3e0293ee, v54
	v_fmamk_f32 v8, v8, 0x3e0293ee, v54
	v_fmamk_f32 v9, v9, 0x3e0293ee, v54
	v_fmamk_f32 v55, v10, 0x3e0293ee, v54
	v_fmamk_f32 v56, v11, 0x3e0293ee, v54
	v_fmamk_f32 v57, v12, 0x3e0293ee, v54
	v_fmamk_f32 v58, v13, 0x3e0293ee, v54
	v_fmamk_f32 v59, v14, 0x3e0293ee, v54
	v_fmamk_f32 v60, v15, 0x3e0293ee, v54
	v_fmamk_f32 v61, v16, 0x3e0293ee, v54
	v_fmamk_f32 v62, v17, 0x3e0293ee, v54
	v_exp_f32_e32 v10, v2
	v_exp_f32_e32 v11, v3
	v_exp_f32_e32 v12, v4
	v_exp_f32_e32 v13, v5
	v_exp_f32_e32 v14, v6
	v_exp_f32_e32 v15, v7
	v_exp_f32_e32 v16, v8
	v_exp_f32_e32 v17, v9
	v_exp_f32_e32 v2, v55
	v_exp_f32_e32 v3, v56
	v_exp_f32_e32 v4, v57
	v_exp_f32_e32 v5, v58
	v_exp_f32_e32 v6, v59
	v_exp_f32_e32 v7, v60
	v_exp_f32_e32 v8, v61
	v_exp_f32_e32 v9, v62
	v_fmamk_f32 v18, v18, 0x3e0293ee, v54
	v_fmamk_f32 v19, v19, 0x3e0293ee, v54
	v_fmamk_f32 v20, v20, 0x3e0293ee, v54
	v_fmamk_f32 v21, v21, 0x3e0293ee, v54
	v_fmamk_f32 v22, v22, 0x3e0293ee, v54
	v_fmamk_f32 v23, v23, 0x3e0293ee, v54
	v_fmamk_f32 v24, v24, 0x3e0293ee, v54
	v_fmamk_f32 v25, v25, 0x3e0293ee, v54
	v_fmamk_f32 v26, v26, 0x3e0293ee, v54
	v_fmamk_f32 v27, v27, 0x3e0293ee, v54
	v_fmamk_f32 v28, v28, 0x3e0293ee, v54
	v_fmamk_f32 v29, v29, 0x3e0293ee, v54
	v_fmamk_f32 v30, v30, 0x3e0293ee, v54
	v_fmamk_f32 v31, v31, 0x3e0293ee, v54
	v_fmamk_f32 v32, v32, 0x3e0293ee, v54
	v_fmac_f32_e32 v54, 0x3e0293ee, v33
	ds_read_b128 v[228:231], v168 offset:49152
	ds_read_b128 v[232:235], v168 offset:57344
	ds_read_b128 v[236:239], v164 offset:49152
	ds_read_b128 v[248:251], v164 offset:57344
	ds_read_b128 v[252:255], v161 offset:49152
	s_waitcnt lgkmcnt(3)
	v_mfma_f32_32x32x16_bf16 v[82:97], v[228:231], v[126:129], 0
	ds_read_b128 v[228:231], v161 offset:57344
	v_mfma_f32_32x32x16_bf16 v[66:81], v[232:235], v[126:129], 0
	ds_read_b128 v[232:235], v160 offset:49152
	s_waitcnt lgkmcnt(3)
	v_mfma_f32_32x32x16_bf16 v[82:97], v[236:239], v[122:125], v[82:97]
	ds_read_b128 v[236:239], v160 offset:57344
	v_mfma_f32_32x32x16_bf16 v[66:81], v[248:251], v[122:125], v[66:81]
	ds_read_b128 v[248:251], v168 offset:49280
	s_waitcnt lgkmcnt(3)
	v_mfma_f32_32x32x16_bf16 v[82:97], v[252:255], v[118:121], v[82:97]
	ds_read_b128 v[252:255], v168 offset:57472
	v_mfma_f32_32x32x16_bf16 v[66:81], v[228:231], v[118:121], v[66:81]
	ds_read_b128 v[228:231], v164 offset:49280
	s_waitcnt lgkmcnt(3)
	v_mfma_f32_32x32x16_bf16 v[82:97], v[232:235], v[114:117], v[82:97]
	ds_read_b128 v[232:235], v164 offset:57472
	v_mfma_f32_32x32x16_bf16 v[66:81], v[236:239], v[114:117], v[66:81]
	ds_read_b128 v[236:239], v161 offset:49280
	s_waitcnt lgkmcnt(3)
	v_mfma_f32_32x32x16_bf16 v[82:97], v[248:251], v[110:113], v[82:97]
	ds_read_b128 v[248:251], v161 offset:57472
	v_mfma_f32_32x32x16_bf16 v[66:81], v[252:255], v[110:113], v[66:81]
	ds_read_b128 v[252:255], v160 offset:49280
	s_waitcnt lgkmcnt(3)
	v_mfma_f32_32x32x16_bf16 v[82:97], v[228:231], v[106:109], v[82:97]
	ds_read_b128 v[228:231], v160 offset:57472
	v_mfma_f32_32x32x16_bf16 v[66:81], v[232:235], v[106:109], v[66:81]
	s_waitcnt lgkmcnt(2)
	v_mfma_f32_32x32x16_bf16 v[82:97], v[236:239], v[102:105], v[82:97]
	v_mfma_f32_32x32x16_bf16 v[66:81], v[248:251], v[102:105], v[66:81]
	s_waitcnt lgkmcnt(0)
	v_mfma_f32_32x32x16_bf16 v[82:97], v[252:255], v[98:101], v[82:97]
	v_mfma_f32_32x32x16_bf16 v[66:81], v[228:231], v[98:101], v[66:81]
	v_add_f32_e32 v34, 0, v10
	v_add_f32_e32 v34, v11, v34
	v_add_f32_e32 v34, v12, v34
	v_add_f32_e32 v34, v13, v34
	v_add_f32_e32 v34, v14, v34
	v_add_f32_e32 v34, v15, v34
	v_add_f32_e32 v34, v16, v34
	v_add_f32_e32 v34, v17, v34
	v_add_f32_e32 v34, v2, v34
	v_add_f32_e32 v34, v3, v34
	v_add_f32_e32 v34, v4, v34
	v_add_f32_e32 v34, v5, v34
	v_exp_f32_e32 v18, v18
	v_add_f32_e32 v34, v6, v34
	v_exp_f32_e32 v19, v19
	v_add_f32_e32 v34, v7, v34
	v_exp_f32_e32 v20, v20
	v_add_f32_e32 v34, v8, v34
	v_exp_f32_e32 v21, v21
	v_add_f32_e32 v34, v9, v34
	v_exp_f32_e32 v22, v22
	v_add_f32_e32 v34, v18, v34
	v_exp_f32_e32 v23, v23
	v_add_f32_e32 v34, v19, v34
	v_exp_f32_e32 v24, v24
	v_add_f32_e32 v34, v20, v34
	v_exp_f32_e32 v25, v25
	v_add_f32_e32 v34, v21, v34
	v_exp_f32_e32 v26, v26
	v_add_f32_e32 v34, v22, v34
	v_exp_f32_e32 v27, v27
	v_add_f32_e32 v34, v23, v34
	v_exp_f32_e32 v28, v28
	v_add_f32_e32 v34, v24, v34
	v_exp_f32_e32 v29, v29
	v_add_f32_e32 v34, v25, v34
	v_exp_f32_e32 v30, v30
	v_add_f32_e32 v34, v26, v34
	v_exp_f32_e32 v31, v31
	v_add_f32_e32 v34, v27, v34
	v_exp_f32_e32 v32, v32
	v_add_f32_e32 v34, v28, v34
	v_exp_f32_e32 v33, v54
	v_add_f32_e32 v34, v29, v34
	v_add_f32_e32 v34, v30, v34
	v_add_f32_e32 v34, v31, v34
	v_add_f32_e32 v34, v32, v34
	v_add_f32_e32 v169, v33, v34
	v_mov_b32_e32 v179, v169
	v_cvt_pk_bf16_f32 v50, v10, v11
	v_cvt_pk_bf16_f32 v51, v12, v13
	v_cvt_pk_bf16_f32 v52, v14, v15
	v_cvt_pk_bf16_f32 v53, v16, v17
	v_cvt_pk_bf16_f32 v180, v2, v3
	v_cvt_pk_bf16_f32 v181, v4, v5
	v_cvt_pk_bf16_f32 v182, v6, v7
	s_nop 1
	v_permlane32_swap_b32_e32 v169, v179
	v_permlane32_swap_b32_e32 v50, v52
	v_permlane32_swap_b32_e32 v51, v53
	v_cvt_pk_bf16_f32 v183, v8, v9
	v_permlane32_swap_b32_e32 v180, v182
	v_cvt_pk_bf16_f32 v184, v18, v19
	v_cvt_pk_bf16_f32 v185, v20, v21
	v_cvt_pk_bf16_f32 v186, v22, v23
	v_cvt_pk_bf16_f32 v187, v24, v25
	v_cvt_pk_bf16_f32 v188, v26, v27
	v_cvt_pk_bf16_f32 v189, v28, v29
	v_cvt_pk_bf16_f32 v190, v30, v31
	v_cvt_pk_bf16_f32 v191, v32, v33
	v_permlane32_swap_b32_e32 v181, v183
	v_permlane32_swap_b32_e32 v184, v186
	v_permlane32_swap_b32_e32 v185, v187
	v_permlane32_swap_b32_e32 v188, v190
	v_permlane32_swap_b32_e32 v189, v191
	ds_read_b64_tr_b16 v[2:3], v158 offset:0
	ds_read_b64_tr_b16 v[4:5], v158 offset:0x800
	ds_read_b64_tr_b16 v[18:19], v158 offset:0x1000
	ds_read_b64_tr_b16 v[20:21], v158 offset:0x1800
	ds_read_b64_tr_b16 v[22:23], v158 offset:0x2000
	ds_read_b64_tr_b16 v[24:25], v158 offset:0x2800
	ds_read_b64_tr_b16 v[26:27], v158 offset:0x3000
	ds_read_b64_tr_b16 v[28:29], v158 offset:0x3800
	s_nop 0
	s_waitcnt lgkmcnt(4)
	v_mfma_f32_32x32x16_bf16 v[2:17], v[50:53], v[2:5], 0
	v_mfma_f32_32x32x16_bf16 v[2:17], v[180:183], v[18:21], v[2:17]
	ds_read_b64_tr_b16 v[18:19], v158 offset:0x200
	ds_read_b64_tr_b16 v[20:21], v158 offset:0xa00
	ds_read_b64_tr_b16 v[34:35], v158 offset:0x1200
	ds_read_b64_tr_b16 v[36:37], v158 offset:0x1a00
	ds_read_b64_tr_b16 v[38:39], v158 offset:0x2200
	ds_read_b64_tr_b16 v[40:41], v158 offset:0x2a00
	ds_read_b64_tr_b16 v[42:43], v158 offset:0x3200
	s_waitcnt lgkmcnt(7)
	v_mfma_f32_32x32x16_bf16 v[2:17], v[184:187], v[22:25], v[2:17]
	ds_read_b64_tr_b16 v[44:45], v158 offset:0x3a00
	v_mfma_f32_32x32x16_bf16 v[2:17], v[188:191], v[26:29], v[2:17]
	s_waitcnt lgkmcnt(4)
	v_mfma_f32_32x32x16_bf16 v[18:33], v[50:53], v[18:21], 0
	v_mfma_f32_32x32x16_bf16 v[18:33], v[180:183], v[34:37], v[18:33]
	ds_read_b64_tr_b16 v[34:35], v158 offset:0x400
	ds_read_b64_tr_b16 v[36:37], v158 offset:0xc00
	ds_read_b64_tr_b16 v[54:55], v158 offset:0x1400
	ds_read_b64_tr_b16 v[56:57], v158 offset:0x1c00
	ds_read_b64_tr_b16 v[58:59], v158 offset:0x2400
	ds_read_b64_tr_b16 v[60:61], v158 offset:0x2c00
	ds_read_b64_tr_b16 v[62:63], v158 offset:0x3400
	s_waitcnt lgkmcnt(7)
	v_mfma_f32_32x32x16_bf16 v[18:33], v[184:187], v[38:41], v[18:33]
	ds_read_b64_tr_b16 v[64:65], v158 offset:0x3c00
	v_mfma_f32_32x32x16_bf16 v[18:33], v[188:191], v[42:45], v[18:33]
	s_waitcnt lgkmcnt(4)
	v_mfma_f32_32x32x16_bf16 v[34:49], v[50:53], v[34:37], 0
	v_mfma_f32_32x32x16_bf16 v[34:49], v[180:183], v[54:57], v[34:49]
	ds_read_b64_tr_b16 v[54:55], v158 offset:0x600
	ds_read_b64_tr_b16 v[56:57], v158 offset:0xe00
	ds_read_b64_tr_b16 v[192:193], v158 offset:0x1600
	ds_read_b64_tr_b16 v[194:195], v158 offset:0x1e00
	ds_read_b64_tr_b16 v[196:197], v158 offset:0x2600
	ds_read_b64_tr_b16 v[198:199], v158 offset:0x2e00
	ds_read_b64_tr_b16 v[200:201], v158 offset:0x3600
	s_waitcnt lgkmcnt(7)
	v_mfma_f32_32x32x16_bf16 v[34:49], v[184:187], v[58:61], v[34:49]
	ds_read_b64_tr_b16 v[202:203], v158 offset:0x3e00
	v_mfma_f32_32x32x16_bf16 v[34:49], v[188:191], v[62:65], v[34:49]
	s_waitcnt lgkmcnt(4)
	v_mfma_f32_32x32x16_bf16 v[50:65], v[50:53], v[54:57], 0
	v_mfma_f32_32x32x16_bf16 v[50:65], v[180:183], v[192:195], v[50:65]
	s_waitcnt lgkmcnt(0)
	v_mfma_f32_32x32x16_bf16 v[50:65], v[184:187], v[196:199], v[50:65]
	v_mfma_f32_32x32x16_bf16 v[50:65], v[188:191], v[200:203], v[50:65]
	v_max_f32_e32 v152, v83, v83
	v_max_f32_e32 v153, v82, v82
	v_max_f32_e32 v152, v153, v152
	v_max3_f32 v152, v152, v84, v85
	v_max3_f32 v152, v152, v86, v87
	v_max3_f32 v152, v152, v88, v89
	v_max3_f32 v152, v152, v90, v91
	v_max3_f32 v152, v152, v92, v93
	v_max3_f32 v152, v152, v94, v95
	v_max3_f32 v152, v152, v96, v97
	v_max3_f32 v152, v152, v66, v67
	v_max3_f32 v152, v152, v68, v69
	v_max3_f32 v152, v152, v70, v71
	v_max3_f32 v152, v152, v72, v73
	v_max3_f32 v152, v152, v74, v75
	v_max3_f32 v152, v152, v76, v77
	v_max3_f32 v152, v152, v78, v79
	v_max3_f32 v152, v152, v80, v81
	v_mov_b32_e32 v153, v152
	s_nop 1
	v_permlane32_swap_b32_e32 v152, v153
	v_max_f32_e32 v153, v153, v153
	v_max_f32_e32 v152, v152, v152
	v_max_f32_e32 v152, v152, v153
	v_sub_f32_e32 v153, v152, v150
	v_mul_f32_e32 v153, 0x3e0293ee, v153
	v_max_f32_e32 v152, v150, v152
	v_cmp_ge_f32_e32 vcc, s24, v153
	v_sub_f32_e32 v153, v150, v152
	v_mul_f32_e32 v153, 0x3e0293ee, v153
	v_exp_f32_e32 v153, v153
	s_cmp_eq_u64 vcc, exec
	s_cselect_b64 s[40:41], -1, 0
	v_cndmask_b32_e64 v180, v153, 1.0, s[40:41]
	v_cmp_gt_f32_e32 vcc, 1.0, v180
	s_barrier
	s_waitcnt vmcnt(1)
	ds_write_b128 v165, v[138:141] offset:32768
	s_waitcnt vmcnt(0)
	ds_write_b128 v165, v[142:145] offset:40960
	ds_write_b128 v166, v[130:133]
	ds_write_b128 v167, v[134:137]
	s_cbranch_vccz .LBB0_1418
	s_and_saveexec_b64 s[4:5], s[38:39]
	ds_write_b32 v159, v180 offset:128
	s_or_b64 exec, exec, s[4:5]
	s_waitcnt lgkmcnt(0)
	v_add_u32_e32 v142, s42, v162
	ds_read_b128 v[130:133], v142 offset:224
	ds_read_b128 v[134:137], v142 offset:192
	ds_read_b128 v[138:141], v142 offset:160
	ds_read_b128 v[142:145], v142 offset:128
	s_waitcnt lgkmcnt(3)
	v_pk_mul_f32 v[14:15], v[14:15], v[130:131]
	s_waitcnt lgkmcnt(2)
	v_pk_mul_f32 v[10:11], v[10:11], v[134:135]
	s_waitcnt lgkmcnt(1)
	v_pk_mul_f32 v[6:7], v[6:7], v[138:139]
	v_pk_mul_f32 v[16:17], v[16:17], v[132:133]
	v_pk_mul_f32 v[12:13], v[12:13], v[136:137]
	v_pk_mul_f32 v[8:9], v[8:9], v[140:141]
	s_waitcnt lgkmcnt(0)
	v_pk_mul_f32 v[4:5], v[4:5], v[144:145]
	v_pk_mul_f32 v[2:3], v[2:3], v[142:143]
	v_pk_mul_f32 v[30:31], v[30:31], v[130:131]
	v_pk_mul_f32 v[26:27], v[26:27], v[134:135]
	v_pk_mul_f32 v[22:23], v[22:23], v[138:139]
	v_pk_mul_f32 v[32:33], v[32:33], v[132:133]
	v_pk_mul_f32 v[28:29], v[28:29], v[136:137]
	v_pk_mul_f32 v[24:25], v[24:25], v[140:141]
	v_pk_mul_f32 v[20:21], v[20:21], v[144:145]
	v_pk_mul_f32 v[18:19], v[18:19], v[142:143]
	v_pk_mul_f32 v[46:47], v[46:47], v[130:131]
	v_pk_mul_f32 v[42:43], v[42:43], v[134:135]
	v_pk_mul_f32 v[38:39], v[38:39], v[138:139]
	v_pk_mul_f32 v[48:49], v[48:49], v[132:133]
	v_pk_mul_f32 v[44:45], v[44:45], v[136:137]
	v_pk_mul_f32 v[40:41], v[40:41], v[140:141]
	v_pk_mul_f32 v[36:37], v[36:37], v[144:145]
	v_pk_mul_f32 v[34:35], v[34:35], v[142:143]
	v_pk_mul_f32 v[62:63], v[62:63], v[130:131]
	v_pk_mul_f32 v[58:59], v[58:59], v[134:135]
	v_pk_mul_f32 v[54:55], v[54:55], v[138:139]
	v_pk_mul_f32 v[64:65], v[64:65], v[132:133]
	v_pk_mul_f32 v[60:61], v[60:61], v[136:137]
	v_pk_mul_f32 v[56:57], v[56:57], v[140:141]
	v_pk_mul_f32 v[52:53], v[52:53], v[144:145]
	v_pk_mul_f32 v[50:51], v[50:51], v[142:143]
.LBB0_1418:
	v_cndmask_b32_e64 v184, v152, v150, s[40:41]
	v_mul_f32_e32 v182, 0xbe0293ee, v184
	v_fmamk_f32 v183, v66, 0x3e0293ee, v182
	v_fmamk_f32 v66, v83, 0x3e0293ee, v182
	v_fmamk_f32 v197, v67, 0x3e0293ee, v182
	v_fmamk_f32 v67, v84, 0x3e0293ee, v182
	v_exp_f32_e32 v196, v66
	v_exp_f32_e32 v192, v67
	v_lshlrev_b64 v[66:67], 11, v[146:147]
	v_sub_f32_e32 v130, 0xf149f2ca, v151
	v_fmamk_f32 v198, v68, 0x3e0293ee, v182
	v_fmamk_f32 v68, v85, 0x3e0293ee, v182
	v_fmamk_f32 v199, v69, 0x3e0293ee, v182
	v_fmamk_f32 v69, v86, 0x3e0293ee, v182
	v_lshl_add_u64 v[66:67], v[148:149], 0, v[66:67]
	s_mov_b64 s[4:5], 0x60000
	v_mul_f32_e32 v130, 0x3e0293ee, v130
	v_fmamk_f32 v200, v70, 0x3e0293ee, v182
	v_fmamk_f32 v70, v87, 0x3e0293ee, v182
	v_fmamk_f32 v201, v71, 0x3e0293ee, v182
	v_fmamk_f32 v71, v88, 0x3e0293ee, v182
	v_exp_f32_e32 v195, v68
	v_exp_f32_e32 v190, v69
	v_lshl_add_u64 v[68:69], v[66:67], 0, s[4:5]
	s_mov_b64 s[4:5], 0x70000
	v_exp_f32_e32 v181, v130
	v_exp_f32_e32 v193, v70
	v_exp_f32_e32 v189, v71
	s_waitcnt lgkmcnt(0)
	s_barrier
	v_lshl_add_u64 v[70:71], v[66:67], 0, s[4:5]
	global_load_dwordx4 v[130:133], v[68:69], off offset:1024
	global_load_dwordx4 v[134:137], v[70:71], off offset:1024
	v_add_co_u32_e32 v68, vcc, 0x60000, v66
	s_mov_b32 s4, 0x70000
	s_nop 0
	v_addc_co_u32_e32 v69, vcc, 0, v67, vcc
	v_add_co_u32_e32 v66, vcc, s4, v66
	v_fmamk_f32 v82, v82, 0x3e0293ee, v182
	s_nop 0
	v_addc_co_u32_e32 v67, vcc, 0, v67, vcc
	global_load_dwordx4 v[138:141], v[68:69], off
	global_load_dwordx4 v[142:145], v[66:67], off
	v_fmamk_f32 v202, v72, 0x3e0293ee, v182
	v_fmamk_f32 v72, v89, 0x3e0293ee, v182
	v_fmamk_f32 v203, v73, 0x3e0293ee, v182
	v_fmamk_f32 v73, v90, 0x3e0293ee, v182
	v_fmamk_f32 v204, v74, 0x3e0293ee, v182
	v_fmamk_f32 v74, v91, 0x3e0293ee, v182
	v_fmamk_f32 v205, v75, 0x3e0293ee, v182
	v_fmamk_f32 v75, v92, 0x3e0293ee, v182
	v_fmamk_f32 v206, v76, 0x3e0293ee, v182
	v_fmamk_f32 v76, v93, 0x3e0293ee, v182
	v_fmamk_f32 v207, v77, 0x3e0293ee, v182
	v_fmamk_f32 v77, v94, 0x3e0293ee, v182
	v_fmamk_f32 v208, v78, 0x3e0293ee, v182
	v_fmamk_f32 v78, v95, 0x3e0293ee, v182
	v_fmamk_f32 v83, v96, 0x3e0293ee, v182
	v_fmamk_f32 v84, v97, 0x3e0293ee, v182
	v_fmamk_f32 v209, v79, 0x3e0293ee, v182
	v_fmamk_f32 v210, v80, 0x3e0293ee, v182
	v_fmac_f32_e32 v182, 0x3e0293ee, v81
	v_exp_f32_e32 v194, v82
	v_exp_f32_e32 v191, v72
	v_exp_f32_e32 v150, v73
	v_exp_f32_e32 v188, v74
	v_exp_f32_e32 v151, v75
	v_exp_f32_e32 v187, v76
	v_exp_f32_e32 v152, v77
	v_exp_f32_e32 v186, v78
	v_exp_f32_e32 v153, v83
	v_exp_f32_e32 v185, v84
	ds_read_b128 v[228:231], v168 offset:32768
	ds_read_b128 v[232:235], v164 offset:32768
	ds_read_b128 v[236:239], v168 offset:40960
	ds_read_b128 v[248:251], v164 offset:40960
	ds_read_b128 v[252:255], v161 offset:32768
	s_waitcnt lgkmcnt(3)
	v_mfma_f32_32x32x16_bf16 v[82:97], v[228:231], v[126:129], 0
	ds_read_b128 v[228:231], v161 offset:40960
	v_mfma_f32_32x32x16_bf16 v[82:97], v[232:235], v[122:125], v[82:97]
	ds_read_b128 v[232:235], v160 offset:32768
	s_waitcnt lgkmcnt(3)
	v_mfma_f32_32x32x16_bf16 v[66:81], v[236:239], v[126:129], 0
	ds_read_b128 v[236:239], v160 offset:40960
	v_mfma_f32_32x32x16_bf16 v[66:81], v[248:251], v[122:125], v[66:81]
	ds_read_b128 v[248:251], v168 offset:32896
	s_waitcnt lgkmcnt(3)
	v_mfma_f32_32x32x16_bf16 v[82:97], v[252:255], v[118:121], v[82:97]
	ds_read_b128 v[252:255], v168 offset:41088
	v_mfma_f32_32x32x16_bf16 v[66:81], v[228:231], v[118:121], v[66:81]
	ds_read_b128 v[228:231], v164 offset:32896
	s_waitcnt lgkmcnt(3)
	v_mfma_f32_32x32x16_bf16 v[82:97], v[232:235], v[114:117], v[82:97]
	ds_read_b128 v[232:235], v164 offset:41088
	v_mfma_f32_32x32x16_bf16 v[66:81], v[236:239], v[114:117], v[66:81]
	ds_read_b128 v[236:239], v161 offset:32896
	s_waitcnt lgkmcnt(3)
	v_mfma_f32_32x32x16_bf16 v[82:97], v[248:251], v[110:113], v[82:97]
	ds_read_b128 v[248:251], v161 offset:41088
	v_mfma_f32_32x32x16_bf16 v[66:81], v[252:255], v[110:113], v[66:81]
	ds_read_b128 v[252:255], v160 offset:32896
	s_waitcnt lgkmcnt(3)
	v_mfma_f32_32x32x16_bf16 v[82:97], v[228:231], v[106:109], v[82:97]
	ds_read_b128 v[228:231], v160 offset:41088
	v_mfma_f32_32x32x16_bf16 v[66:81], v[232:235], v[106:109], v[66:81]
	s_waitcnt lgkmcnt(2)
	v_mfma_f32_32x32x16_bf16 v[82:97], v[236:239], v[102:105], v[82:97]
	v_mfma_f32_32x32x16_bf16 v[66:81], v[248:251], v[102:105], v[66:81]
	s_waitcnt lgkmcnt(0)
	v_mfma_f32_32x32x16_bf16 v[82:97], v[252:255], v[98:101], v[82:97]
	v_mfma_f32_32x32x16_bf16 v[66:81], v[228:231], v[98:101], v[66:81]
	v_add_f32_e32 v146, 0, v194
	v_add_f32_e32 v146, v196, v146
	v_add_f32_e32 v146, v192, v146
	v_add_f32_e32 v146, v195, v146
	v_add_f32_e32 v146, v190, v146
	v_add_f32_e32 v146, v193, v146
	v_add_f32_e32 v146, v189, v146
	v_add_f32_e32 v146, v191, v146
	v_add_f32_e32 v146, v150, v146
	v_add_f32_e32 v146, v188, v146
	v_add_f32_e32 v146, v151, v146
	v_add_f32_e32 v146, v187, v146
	v_exp_f32_e32 v211, v183
	v_add_f32_e32 v146, v152, v146
	v_exp_f32_e32 v197, v197
	v_add_f32_e32 v146, v186, v146
	v_exp_f32_e32 v198, v198
	v_add_f32_e32 v146, v153, v146
	v_exp_f32_e32 v199, v199
	v_add_f32_e32 v146, v185, v146
	v_exp_f32_e32 v200, v200
	v_add_f32_e32 v146, v211, v146
	v_exp_f32_e32 v201, v201
	v_add_f32_e32 v146, v197, v146
	v_exp_f32_e32 v202, v202
	v_add_f32_e32 v146, v198, v146
	v_exp_f32_e32 v203, v203
	v_add_f32_e32 v146, v199, v146
	v_exp_f32_e32 v204, v204
	v_add_f32_e32 v146, v200, v146
	v_exp_f32_e32 v205, v205
	v_add_f32_e32 v146, v201, v146
	v_exp_f32_e32 v206, v206
	v_add_f32_e32 v146, v202, v146
	v_exp_f32_e32 v207, v207
	v_add_f32_e32 v146, v203, v146
	v_exp_f32_e32 v208, v208
	v_add_f32_e32 v146, v204, v146
	v_exp_f32_e32 v209, v209
	v_add_f32_e32 v146, v205, v146
	v_exp_f32_e32 v210, v210
	v_add_f32_e32 v146, v206, v146
	v_exp_f32_e32 v212, v182
	v_add_f32_e32 v146, v207, v146
	v_add_f32_e32 v146, v208, v146
	v_add_f32_e32 v146, v209, v146
	v_add_f32_e32 v146, v210, v146
	v_add_f32_e32 v182, v212, v146
	v_mov_b32_e32 v183, v182
	v_cvt_pk_bf16_f32 v146, v194, v196
	v_cvt_pk_bf16_f32 v147, v192, v195
	v_cvt_pk_bf16_f32 v148, v190, v193
	v_cvt_pk_bf16_f32 v149, v189, v191
	s_nop 1
	v_permlane32_swap_b32_e32 v182, v183
	v_permlane32_swap_b32_e32 v146, v148
	v_permlane32_swap_b32_e32 v147, v149
	v_cvt_pk_bf16_f32 v150, v150, v188
	v_cvt_pk_bf16_f32 v151, v151, v187
	v_cvt_pk_bf16_f32 v152, v152, v186
	v_cvt_pk_bf16_f32 v153, v153, v185
	v_cvt_pk_bf16_f32 v186, v211, v197
	v_cvt_pk_bf16_f32 v187, v198, v199
	v_cvt_pk_bf16_f32 v188, v200, v201
	v_cvt_pk_bf16_f32 v189, v202, v203
	v_cvt_pk_bf16_f32 v190, v204, v205
	v_cvt_pk_bf16_f32 v191, v206, v207
	v_cvt_pk_bf16_f32 v192, v208, v209
	v_cvt_pk_bf16_f32 v193, v210, v212
	s_nop 0
	v_permlane32_swap_b32_e32 v150, v152
	v_permlane32_swap_b32_e32 v151, v153
	v_permlane32_swap_b32_e32 v186, v188
	v_permlane32_swap_b32_e32 v187, v189
	v_permlane32_swap_b32_e32 v190, v192
	v_permlane32_swap_b32_e32 v191, v193
	ds_read_b64_tr_b16 v[194:195], v158 offset:0x4000
	ds_read_b64_tr_b16 v[196:197], v158 offset:0x4800
	ds_read_b64_tr_b16 v[198:199], v158 offset:0x5000
	ds_read_b64_tr_b16 v[200:201], v158 offset:0x5800
	ds_read_b64_tr_b16 v[202:203], v158 offset:0x6000
	ds_read_b64_tr_b16 v[204:205], v158 offset:0x6800
	ds_read_b64_tr_b16 v[206:207], v158 offset:0x7000
	ds_read_b64_tr_b16 v[208:209], v158 offset:0x7800
	s_nop 0
	s_waitcnt lgkmcnt(4)
	v_mfma_f32_32x32x16_bf16 v[2:17], v[146:149], v[194:197], v[2:17]
	ds_read_b64_tr_b16 v[194:195], v158 offset:0x4200
	ds_read_b64_tr_b16 v[196:197], v158 offset:0x4a00
	v_mfma_f32_32x32x16_bf16 v[2:17], v[150:153], v[198:201], v[2:17]
	ds_read_b64_tr_b16 v[198:199], v158 offset:0x5200
	ds_read_b64_tr_b16 v[200:201], v158 offset:0x5a00
	s_waitcnt lgkmcnt(4)
	v_mfma_f32_32x32x16_bf16 v[2:17], v[186:189], v[202:205], v[2:17]
	ds_read_b64_tr_b16 v[202:203], v158 offset:0x6200
	ds_read_b64_tr_b16 v[204:205], v158 offset:0x6a00
	v_mfma_f32_32x32x16_bf16 v[2:17], v[190:193], v[206:209], v[2:17]
	ds_read_b64_tr_b16 v[206:207], v158 offset:0x7200
	ds_read_b64_tr_b16 v[208:209], v158 offset:0x7a00
	s_waitcnt lgkmcnt(4)
	v_mfma_f32_32x32x16_bf16 v[18:33], v[146:149], v[194:197], v[18:33]
	ds_read_b64_tr_b16 v[194:195], v158 offset:0x4400
	ds_read_b64_tr_b16 v[196:197], v158 offset:0x4c00
	v_mfma_f32_32x32x16_bf16 v[18:33], v[150:153], v[198:201], v[18:33]
	ds_read_b64_tr_b16 v[198:199], v158 offset:0x5400
	ds_read_b64_tr_b16 v[200:201], v158 offset:0x5c00
	s_waitcnt lgkmcnt(4)
	v_mfma_f32_32x32x16_bf16 v[18:33], v[186:189], v[202:205], v[18:33]
	ds_read_b64_tr_b16 v[202:203], v158 offset:0x6400
	ds_read_b64_tr_b16 v[204:205], v158 offset:0x6c00
	v_mfma_f32_32x32x16_bf16 v[18:33], v[190:193], v[206:209], v[18:33]
	ds_read_b64_tr_b16 v[206:207], v158 offset:0x7400
	ds_read_b64_tr_b16 v[208:209], v158 offset:0x7c00
	s_waitcnt lgkmcnt(4)
	v_mfma_f32_32x32x16_bf16 v[34:49], v[146:149], v[194:197], v[34:49]
	ds_read_b64_tr_b16 v[194:195], v158 offset:0x4600
	ds_read_b64_tr_b16 v[196:197], v158 offset:0x4e00
	v_mfma_f32_32x32x16_bf16 v[34:49], v[150:153], v[198:201], v[34:49]
	ds_read_b64_tr_b16 v[198:199], v158 offset:0x5600
	ds_read_b64_tr_b16 v[200:201], v158 offset:0x5e00
	s_waitcnt lgkmcnt(4)
	v_mfma_f32_32x32x16_bf16 v[34:49], v[186:189], v[202:205], v[34:49]
	ds_read_b64_tr_b16 v[202:203], v158 offset:0x6600
	ds_read_b64_tr_b16 v[204:205], v158 offset:0x6e00
	v_mfma_f32_32x32x16_bf16 v[34:49], v[190:193], v[206:209], v[34:49]
	ds_read_b64_tr_b16 v[206:207], v158 offset:0x7600
	ds_read_b64_tr_b16 v[208:209], v158 offset:0x7e00
	s_waitcnt lgkmcnt(4)
	v_mfma_f32_32x32x16_bf16 v[50:65], v[146:149], v[194:197], v[50:65]
	v_mfma_f32_32x32x16_bf16 v[50:65], v[150:153], v[198:201], v[50:65]
	s_waitcnt lgkmcnt(0)
	v_mfma_f32_32x32x16_bf16 v[50:65], v[186:189], v[202:205], v[50:65]
	v_mfma_f32_32x32x16_bf16 v[50:65], v[190:193], v[206:209], v[50:65]
	v_max_f32_e32 v146, v83, v83
	v_max_f32_e32 v147, v82, v82
	v_max_f32_e32 v146, v147, v146
	v_max3_f32 v146, v146, v84, v85
	v_max3_f32 v146, v146, v86, v87
	v_max3_f32 v146, v146, v88, v89
	v_max3_f32 v146, v146, v90, v91
	v_max3_f32 v146, v146, v92, v93
	v_max3_f32 v146, v146, v94, v95
	v_max3_f32 v146, v146, v96, v97
	v_max3_f32 v146, v146, v66, v67
	v_max3_f32 v146, v146, v68, v69
	v_max3_f32 v146, v146, v70, v71
	v_max3_f32 v146, v146, v72, v73
	v_max3_f32 v146, v146, v74, v75
	v_max3_f32 v146, v146, v76, v77
	v_max3_f32 v146, v146, v78, v79
	v_max3_f32 v146, v146, v80, v81
	v_mov_b32_e32 v147, v146
	s_nop 1
	v_permlane32_swap_b32_e32 v146, v147
	v_max_f32_e32 v147, v147, v147
	v_max_f32_e32 v146, v146, v146
	v_max_f32_e32 v146, v146, v147
	v_sub_f32_e32 v147, v146, v184
	v_mul_f32_e32 v147, 0x3e0293ee, v147
	v_cmp_ge_f32_e32 vcc, s24, v147
	v_max_f32_e32 v147, v184, v184
	v_max_f32_e32 v147, v147, v146
	v_sub_f32_e32 v146, v184, v147
	v_mul_f32_e32 v146, 0x3e0293ee, v146
	v_exp_f32_e32 v146, v146
	s_cmp_eq_u64 vcc, exec
	s_cselect_b64 s[40:41], -1, 0
	v_cndmask_b32_e64 v146, v146, 1.0, s[40:41]
	v_cmp_gt_f32_e32 vcc, 1.0, v146
	s_barrier
	s_waitcnt vmcnt(1)
	ds_write_b128 v165, v[138:141] offset:49152
	s_waitcnt vmcnt(0)
	ds_write_b128 v165, v[142:145] offset:57344
	ds_write_b128 v166, v[130:133] offset:16384
	ds_write_b128 v167, v[134:137] offset:16384
	s_cbranch_vccz .LBB0_1422
	s_and_saveexec_b64 s[4:5], s[38:39]
	ds_write_b32 v159, v146 offset:128
	s_or_b64 exec, exec, s[4:5]
	s_waitcnt lgkmcnt(0)
	v_add_u32_e32 v142, s42, v162
	ds_read_b128 v[130:133], v142 offset:224
	ds_read_b128 v[134:137], v142 offset:192
	ds_read_b128 v[138:141], v142 offset:160
	ds_read_b128 v[142:145], v142 offset:128
	s_waitcnt lgkmcnt(3)
	v_pk_mul_f32 v[14:15], v[14:15], v[130:131]
	s_waitcnt lgkmcnt(2)
	v_pk_mul_f32 v[10:11], v[10:11], v[134:135]
	s_waitcnt lgkmcnt(1)
	v_pk_mul_f32 v[6:7], v[6:7], v[138:139]
	v_pk_mul_f32 v[16:17], v[16:17], v[132:133]
	v_pk_mul_f32 v[12:13], v[12:13], v[136:137]
	v_pk_mul_f32 v[8:9], v[8:9], v[140:141]
	s_waitcnt lgkmcnt(0)
	v_pk_mul_f32 v[4:5], v[4:5], v[144:145]
	v_pk_mul_f32 v[2:3], v[2:3], v[142:143]
	v_pk_mul_f32 v[30:31], v[30:31], v[130:131]
	v_pk_mul_f32 v[26:27], v[26:27], v[134:135]
	v_pk_mul_f32 v[22:23], v[22:23], v[138:139]
	v_pk_mul_f32 v[32:33], v[32:33], v[132:133]
	v_pk_mul_f32 v[28:29], v[28:29], v[136:137]
	v_pk_mul_f32 v[24:25], v[24:25], v[140:141]
	v_pk_mul_f32 v[20:21], v[20:21], v[144:145]
	v_pk_mul_f32 v[18:19], v[18:19], v[142:143]
	v_pk_mul_f32 v[46:47], v[46:47], v[130:131]
	v_pk_mul_f32 v[42:43], v[42:43], v[134:135]
	v_pk_mul_f32 v[38:39], v[38:39], v[138:139]
	v_pk_mul_f32 v[48:49], v[48:49], v[132:133]
	v_pk_mul_f32 v[44:45], v[44:45], v[136:137]
	v_pk_mul_f32 v[40:41], v[40:41], v[140:141]
	v_pk_mul_f32 v[36:37], v[36:37], v[144:145]
	v_pk_mul_f32 v[34:35], v[34:35], v[142:143]
	v_pk_mul_f32 v[62:63], v[62:63], v[130:131]
	v_pk_mul_f32 v[58:59], v[58:59], v[134:135]
	v_pk_mul_f32 v[54:55], v[54:55], v[138:139]
	v_pk_mul_f32 v[64:65], v[64:65], v[132:133]
	v_pk_mul_f32 v[60:61], v[60:61], v[136:137]
	v_pk_mul_f32 v[56:57], v[56:57], v[140:141]
	v_pk_mul_f32 v[52:53], v[52:53], v[144:145]
	v_pk_mul_f32 v[50:51], v[50:51], v[142:143]
.LBB0_1422:
	v_cndmask_b32_e64 v130, v147, v184, s[40:41]
	v_mul_f32_e32 v148, 0xbe0293ee, v130
	v_fmamk_f32 v82, v82, 0x3e0293ee, v148
	v_fmamk_f32 v149, v66, 0x3e0293ee, v148
	v_fmamk_f32 v66, v83, 0x3e0293ee, v148
	v_fmamk_f32 v150, v67, 0x3e0293ee, v148
	v_fmamk_f32 v67, v84, 0x3e0293ee, v148
	v_fmamk_f32 v151, v68, 0x3e0293ee, v148
	v_fmamk_f32 v68, v85, 0x3e0293ee, v148
	v_fmamk_f32 v152, v69, 0x3e0293ee, v148
	v_fmamk_f32 v69, v86, 0x3e0293ee, v148
	v_fmamk_f32 v153, v70, 0x3e0293ee, v148
	v_fmamk_f32 v70, v87, 0x3e0293ee, v148
	v_fmamk_f32 v165, v71, 0x3e0293ee, v148
	v_fmamk_f32 v71, v88, 0x3e0293ee, v148
	v_fmamk_f32 v166, v72, 0x3e0293ee, v148
	v_fmamk_f32 v72, v89, 0x3e0293ee, v148
	v_fmamk_f32 v167, v73, 0x3e0293ee, v148
	v_fmamk_f32 v73, v90, 0x3e0293ee, v148
	v_fmamk_f32 v184, v74, 0x3e0293ee, v148
	v_fmamk_f32 v74, v91, 0x3e0293ee, v148
	v_fmamk_f32 v185, v75, 0x3e0293ee, v148
	v_fmamk_f32 v75, v92, 0x3e0293ee, v148
	v_fmamk_f32 v186, v76, 0x3e0293ee, v148
	v_fmamk_f32 v76, v93, 0x3e0293ee, v148
	v_fmamk_f32 v187, v77, 0x3e0293ee, v148
	v_fmamk_f32 v77, v94, 0x3e0293ee, v148
	v_fmamk_f32 v188, v78, 0x3e0293ee, v148
	v_fmamk_f32 v78, v95, 0x3e0293ee, v148
	v_fmamk_f32 v83, v96, 0x3e0293ee, v148
	v_fmamk_f32 v84, v97, 0x3e0293ee, v148
	v_exp_f32_e32 v144, v82
	v_exp_f32_e32 v147, v66
	v_exp_f32_e32 v142, v67
	v_exp_f32_e32 v145, v68
	v_exp_f32_e32 v140, v69
	v_exp_f32_e32 v143, v70
	v_exp_f32_e32 v139, v71
	v_exp_f32_e32 v141, v72
	v_exp_f32_e32 v136, v73
	v_exp_f32_e32 v138, v74
	v_exp_f32_e32 v134, v75
	v_exp_f32_e32 v137, v76
	v_exp_f32_e32 v132, v77
	v_exp_f32_e32 v135, v78
	v_exp_f32_e32 v131, v83
	v_exp_f32_e32 v133, v84
	v_fmamk_f32 v189, v79, 0x3e0293ee, v148
	v_fmamk_f32 v190, v80, 0x3e0293ee, v148
	v_fmac_f32_e32 v148, 0x3e0293ee, v81
	s_waitcnt lgkmcnt(0)
	s_barrier
	ds_read_b128 v[228:231], v168 offset:49152
	ds_read_b128 v[232:235], v168 offset:57344
	ds_read_b128 v[236:239], v164 offset:49152
	ds_read_b128 v[248:251], v164 offset:57344
	ds_read_b128 v[252:255], v161 offset:49152
	s_waitcnt lgkmcnt(3)
	v_mfma_f32_32x32x16_bf16 v[82:97], v[228:231], v[126:129], 0
	ds_read_b128 v[228:231], v161 offset:57344
	v_mfma_f32_32x32x16_bf16 v[66:81], v[232:235], v[126:129], 0
	ds_read_b128 v[232:235], v160 offset:49152
	s_waitcnt lgkmcnt(3)
	v_mfma_f32_32x32x16_bf16 v[82:97], v[236:239], v[122:125], v[82:97]
	ds_read_b128 v[236:239], v160 offset:57344
	v_mfma_f32_32x32x16_bf16 v[66:81], v[248:251], v[122:125], v[66:81]
	ds_read_b128 v[248:251], v168 offset:49280
	s_waitcnt lgkmcnt(3)
	v_mfma_f32_32x32x16_bf16 v[82:97], v[252:255], v[118:121], v[82:97]
	ds_read_b128 v[252:255], v168 offset:57472
	v_mfma_f32_32x32x16_bf16 v[66:81], v[228:231], v[118:121], v[66:81]
	ds_read_b128 v[228:231], v164 offset:49280
	s_waitcnt lgkmcnt(3)
	v_mfma_f32_32x32x16_bf16 v[82:97], v[232:235], v[114:117], v[82:97]
	ds_read_b128 v[232:235], v164 offset:57472
	v_mfma_f32_32x32x16_bf16 v[66:81], v[236:239], v[114:117], v[66:81]
	ds_read_b128 v[236:239], v161 offset:49280
	s_waitcnt lgkmcnt(3)
	v_mfma_f32_32x32x16_bf16 v[82:97], v[248:251], v[110:113], v[82:97]
	ds_read_b128 v[248:251], v161 offset:57472
	v_mfma_f32_32x32x16_bf16 v[66:81], v[252:255], v[110:113], v[66:81]
	ds_read_b128 v[252:255], v160 offset:49280
	s_waitcnt lgkmcnt(3)
	v_mfma_f32_32x32x16_bf16 v[82:97], v[228:231], v[106:109], v[82:97]
	ds_read_b128 v[228:231], v160 offset:57472
	v_mfma_f32_32x32x16_bf16 v[66:81], v[232:235], v[106:109], v[66:81]
	s_waitcnt lgkmcnt(2)
	v_mfma_f32_32x32x16_bf16 v[82:97], v[236:239], v[102:105], v[82:97]
	v_mfma_f32_32x32x16_bf16 v[66:81], v[248:251], v[102:105], v[66:81]
	s_waitcnt lgkmcnt(0)
	v_mfma_f32_32x32x16_bf16 v[82:97], v[252:255], v[98:101], v[82:97]
	v_mfma_f32_32x32x16_bf16 v[66:81], v[228:231], v[98:101], v[66:81]
	v_add_f32_e32 v98, 0, v144
	v_add_f32_e32 v98, v147, v98
	v_add_f32_e32 v98, v142, v98
	v_add_f32_e32 v98, v145, v98
	v_add_f32_e32 v98, v140, v98
	v_add_f32_e32 v98, v143, v98
	v_add_f32_e32 v98, v139, v98
	v_add_f32_e32 v98, v141, v98
	v_add_f32_e32 v98, v136, v98
	v_add_f32_e32 v98, v138, v98
	v_add_f32_e32 v98, v134, v98
	v_add_f32_e32 v98, v137, v98
	v_exp_f32_e32 v108, v149
	v_add_f32_e32 v98, v132, v98
	v_exp_f32_e32 v109, v150
	v_add_f32_e32 v98, v135, v98
	v_exp_f32_e32 v110, v151
	v_add_f32_e32 v98, v131, v98
	v_exp_f32_e32 v111, v152
	v_add_f32_e32 v98, v133, v98
	v_exp_f32_e32 v112, v153
	v_add_f32_e32 v98, v108, v98
	v_exp_f32_e32 v113, v165
	v_add_f32_e32 v98, v109, v98
	v_exp_f32_e32 v114, v166
	v_add_f32_e32 v98, v110, v98
	v_exp_f32_e32 v115, v167
	v_add_f32_e32 v98, v111, v98
	v_exp_f32_e32 v116, v184
	v_add_f32_e32 v98, v112, v98
	v_exp_f32_e32 v117, v185
	v_add_f32_e32 v98, v113, v98
	v_exp_f32_e32 v118, v186
	v_add_f32_e32 v98, v114, v98
	v_exp_f32_e32 v119, v187
	v_add_f32_e32 v98, v115, v98
	v_exp_f32_e32 v120, v188
	v_add_f32_e32 v98, v116, v98
	v_exp_f32_e32 v121, v189
	v_add_f32_e32 v98, v117, v98
	v_exp_f32_e32 v122, v190
	v_add_f32_e32 v98, v118, v98
	v_exp_f32_e32 v123, v148
	v_add_f32_e32 v98, v119, v98
	v_add_f32_e32 v98, v120, v98
	v_add_f32_e32 v98, v121, v98
	v_add_f32_e32 v98, v122, v98
	v_add_f32_e32 v102, v123, v98
	v_mov_b32_e32 v103, v102
	v_cvt_pk_bf16_f32 v98, v144, v147
	v_cvt_pk_bf16_f32 v99, v142, v145
	v_cvt_pk_bf16_f32 v100, v140, v143
	v_cvt_pk_bf16_f32 v101, v139, v141
	s_nop 1
	v_permlane32_swap_b32_e32 v102, v103
	v_permlane32_swap_b32_e32 v98, v100
	v_permlane32_swap_b32_e32 v99, v101
	v_cvt_pk_bf16_f32 v104, v136, v138
	v_cvt_pk_bf16_f32 v105, v134, v137
	v_cvt_pk_bf16_f32 v106, v132, v135
	v_cvt_pk_bf16_f32 v107, v131, v133
	v_cvt_pk_bf16_f32 v108, v108, v109
	v_cvt_pk_bf16_f32 v109, v110, v111
	v_cvt_pk_bf16_f32 v110, v112, v113
	v_cvt_pk_bf16_f32 v111, v114, v115
	v_cvt_pk_bf16_f32 v112, v116, v117
	v_cvt_pk_bf16_f32 v113, v118, v119
	v_cvt_pk_bf16_f32 v114, v120, v121
	v_cvt_pk_bf16_f32 v115, v122, v123
	s_nop 0
	v_permlane32_swap_b32_e32 v104, v106
	v_permlane32_swap_b32_e32 v105, v107
	v_permlane32_swap_b32_e32 v108, v110
	v_permlane32_swap_b32_e32 v109, v111
	v_permlane32_swap_b32_e32 v112, v114
	v_permlane32_swap_b32_e32 v113, v115
	ds_read_b64_tr_b16 v[116:117], v158 offset:0
	ds_read_b64_tr_b16 v[118:119], v158 offset:0x800
	ds_read_b64_tr_b16 v[120:121], v158 offset:0x1000
	ds_read_b64_tr_b16 v[122:123], v158 offset:0x1800
	ds_read_b64_tr_b16 v[124:125], v158 offset:0x2000
	ds_read_b64_tr_b16 v[126:127], v158 offset:0x2800
	ds_read_b64_tr_b16 v[132:133], v158 offset:0x3000
	ds_read_b64_tr_b16 v[134:135], v158 offset:0x3800
	s_nop 0
	s_waitcnt lgkmcnt(4)
	v_mfma_f32_32x32x16_bf16 v[2:17], v[98:101], v[116:119], v[2:17]
	ds_read_b64_tr_b16 v[116:117], v158 offset:0x200
	ds_read_b64_tr_b16 v[118:119], v158 offset:0xa00
	v_mfma_f32_32x32x16_bf16 v[2:17], v[104:107], v[120:123], v[2:17]
	ds_read_b64_tr_b16 v[120:121], v158 offset:0x1200
	ds_read_b64_tr_b16 v[122:123], v158 offset:0x1a00
	s_waitcnt lgkmcnt(4)
	v_mfma_f32_32x32x16_bf16 v[2:17], v[108:111], v[124:127], v[2:17]
	ds_read_b64_tr_b16 v[124:125], v158 offset:0x2200
	ds_read_b64_tr_b16 v[126:127], v158 offset:0x2a00
	v_mfma_f32_32x32x16_bf16 v[2:17], v[112:115], v[132:135], v[2:17]
	ds_read_b64_tr_b16 v[132:133], v158 offset:0x3200
	ds_read_b64_tr_b16 v[134:135], v158 offset:0x3a00
	s_waitcnt lgkmcnt(4)
	v_mfma_f32_32x32x16_bf16 v[18:33], v[98:101], v[116:119], v[18:33]
	ds_read_b64_tr_b16 v[116:117], v158 offset:0x400
	ds_read_b64_tr_b16 v[118:119], v158 offset:0xc00
	v_mfma_f32_32x32x16_bf16 v[18:33], v[104:107], v[120:123], v[18:33]
	ds_read_b64_tr_b16 v[120:121], v158 offset:0x1400
	ds_read_b64_tr_b16 v[122:123], v158 offset:0x1c00
	s_waitcnt lgkmcnt(4)
	v_mfma_f32_32x32x16_bf16 v[18:33], v[108:111], v[124:127], v[18:33]
	ds_read_b64_tr_b16 v[124:125], v158 offset:0x2400
	ds_read_b64_tr_b16 v[126:127], v158 offset:0x2c00
	v_mfma_f32_32x32x16_bf16 v[18:33], v[112:115], v[132:135], v[18:33]
	ds_read_b64_tr_b16 v[132:133], v158 offset:0x3400
	ds_read_b64_tr_b16 v[134:135], v158 offset:0x3c00
	s_waitcnt lgkmcnt(4)
	v_mfma_f32_32x32x16_bf16 v[34:49], v[98:101], v[116:119], v[34:49]
	ds_read_b64_tr_b16 v[116:117], v158 offset:0x600
	ds_read_b64_tr_b16 v[118:119], v158 offset:0xe00
	v_mfma_f32_32x32x16_bf16 v[34:49], v[104:107], v[120:123], v[34:49]
	ds_read_b64_tr_b16 v[120:121], v158 offset:0x1600
	ds_read_b64_tr_b16 v[122:123], v158 offset:0x1e00
	s_waitcnt lgkmcnt(4)
	v_mfma_f32_32x32x16_bf16 v[34:49], v[108:111], v[124:127], v[34:49]
	ds_read_b64_tr_b16 v[124:125], v158 offset:0x2600
	ds_read_b64_tr_b16 v[126:127], v158 offset:0x2e00
	v_mfma_f32_32x32x16_bf16 v[34:49], v[112:115], v[132:135], v[34:49]
	ds_read_b64_tr_b16 v[132:133], v158 offset:0x3600
	ds_read_b64_tr_b16 v[134:135], v158 offset:0x3e00
	s_waitcnt lgkmcnt(4)
	v_mfma_f32_32x32x16_bf16 v[50:65], v[98:101], v[116:119], v[50:65]
	v_max_f32_e32 v98, v83, v83
	v_max_f32_e32 v99, v82, v82
	v_max_f32_e32 v98, v99, v98
	v_max3_f32 v98, v98, v84, v85
	v_max3_f32 v98, v98, v86, v87
	v_max3_f32 v98, v98, v88, v89
	v_max3_f32 v98, v98, v90, v91
	v_max3_f32 v98, v98, v92, v93
	v_max3_f32 v98, v98, v94, v95
	v_max3_f32 v98, v98, v96, v97
	v_mfma_f32_32x32x16_bf16 v[50:65], v[104:107], v[120:123], v[50:65]
	v_max3_f32 v98, v98, v66, v67
	v_max3_f32 v98, v98, v68, v69
	v_max3_f32 v98, v98, v70, v71
	v_max3_f32 v98, v98, v72, v73
	v_max3_f32 v98, v98, v74, v75
	v_max3_f32 v98, v98, v76, v77
	v_max3_f32 v98, v98, v78, v79
	v_max3_f32 v98, v98, v80, v81
	s_waitcnt lgkmcnt(0)
	v_mfma_f32_32x32x16_bf16 v[50:65], v[108:111], v[124:127], v[50:65]
	v_mov_b32_e32 v99, v98
	s_nop 1
	v_permlane32_swap_b32_e32 v98, v99
	v_max_f32_e32 v99, v99, v99
	v_max_f32_e32 v98, v98, v98
	v_max_f32_e32 v98, v98, v99
	v_sub_f32_e32 v99, v98, v130
	v_mul_f32_e32 v99, 0x3e0293ee, v99
	v_cmp_ge_f32_e32 vcc, s24, v99
	v_max_f32_e32 v99, v130, v130
	v_max_f32_e32 v99, v99, v98
	v_mfma_f32_32x32x16_bf16 v[50:65], v[112:115], v[132:135], v[50:65]
	v_sub_f32_e32 v98, v130, v99
	v_mul_f32_e32 v98, 0x3e0293ee, v98
	v_exp_f32_e32 v98, v98
	s_cmp_eq_u64 vcc, exec
	s_cselect_b64 s[40:41], -1, 0
	v_cndmask_b32_e64 v98, v98, 1.0, s[40:41]
	v_cmp_gt_f32_e32 vcc, 1.0, v98
	s_cbranch_vccz .LBB0_1426
	s_and_saveexec_b64 s[4:5], s[38:39]
	ds_write_b32 v159, v98 offset:128
	s_or_b64 exec, exec, s[4:5]
	s_waitcnt lgkmcnt(0)
	v_add_u32_e32 v100, s42, v162
	ds_read_b128 v[104:107], v100 offset:224
	ds_read_b128 v[108:111], v100 offset:192
	ds_read_b128 v[112:115], v100 offset:160
	ds_read_b128 v[116:119], v100 offset:128
	s_waitcnt lgkmcnt(3)
	v_pk_mul_f32 v[14:15], v[14:15], v[104:105]
	s_waitcnt lgkmcnt(2)
	v_pk_mul_f32 v[10:11], v[10:11], v[108:109]
	s_waitcnt lgkmcnt(1)
	v_pk_mul_f32 v[6:7], v[6:7], v[112:113]
	v_pk_mul_f32 v[16:17], v[16:17], v[106:107]
	v_pk_mul_f32 v[12:13], v[12:13], v[110:111]
	v_pk_mul_f32 v[8:9], v[8:9], v[114:115]
	s_waitcnt lgkmcnt(0)
	v_pk_mul_f32 v[4:5], v[4:5], v[118:119]
	v_pk_mul_f32 v[2:3], v[2:3], v[116:117]
	v_pk_mul_f32 v[30:31], v[30:31], v[104:105]
	v_pk_mul_f32 v[26:27], v[26:27], v[108:109]
	v_pk_mul_f32 v[22:23], v[22:23], v[112:113]
	v_pk_mul_f32 v[32:33], v[32:33], v[106:107]
	v_pk_mul_f32 v[28:29], v[28:29], v[110:111]
	v_pk_mul_f32 v[24:25], v[24:25], v[114:115]
	v_pk_mul_f32 v[20:21], v[20:21], v[118:119]
	v_pk_mul_f32 v[18:19], v[18:19], v[116:117]
	v_pk_mul_f32 v[46:47], v[46:47], v[104:105]
	v_pk_mul_f32 v[42:43], v[42:43], v[108:109]
	v_pk_mul_f32 v[38:39], v[38:39], v[112:113]
	v_pk_mul_f32 v[48:49], v[48:49], v[106:107]
	v_pk_mul_f32 v[44:45], v[44:45], v[110:111]
	v_pk_mul_f32 v[40:41], v[40:41], v[114:115]
	v_pk_mul_f32 v[36:37], v[36:37], v[118:119]
	v_pk_mul_f32 v[34:35], v[34:35], v[116:117]
	v_pk_mul_f32 v[62:63], v[62:63], v[104:105]
	v_pk_mul_f32 v[58:59], v[58:59], v[108:109]
	v_pk_mul_f32 v[54:55], v[54:55], v[112:113]
	v_pk_mul_f32 v[64:65], v[64:65], v[106:107]
	v_pk_mul_f32 v[60:61], v[60:61], v[110:111]
	v_pk_mul_f32 v[56:57], v[56:57], v[114:115]
	v_pk_mul_f32 v[52:53], v[52:53], v[118:119]
	v_pk_mul_f32 v[50:51], v[50:51], v[116:117]
.LBB0_1426:
	v_cndmask_b32_e64 v99, v99, v130, s[40:41]
	v_mul_f32_e32 v99, 0xbe0293ee, v99
	v_fmamk_f32 v82, v82, 0x3e0293ee, v99
	v_fmamk_f32 v66, v66, 0x3e0293ee, v99
	v_fmamk_f32 v83, v83, 0x3e0293ee, v99
	v_fmamk_f32 v67, v67, 0x3e0293ee, v99
	v_fmamk_f32 v84, v84, 0x3e0293ee, v99
	v_fmamk_f32 v68, v68, 0x3e0293ee, v99
	v_fmamk_f32 v85, v85, 0x3e0293ee, v99
	v_fmamk_f32 v69, v69, 0x3e0293ee, v99
	v_fmamk_f32 v86, v86, 0x3e0293ee, v99
	v_fmamk_f32 v70, v70, 0x3e0293ee, v99
	v_fmamk_f32 v87, v87, 0x3e0293ee, v99
	v_fmamk_f32 v71, v71, 0x3e0293ee, v99
	v_fmamk_f32 v88, v88, 0x3e0293ee, v99
	v_fmamk_f32 v72, v72, 0x3e0293ee, v99
	v_fmamk_f32 v89, v89, 0x3e0293ee, v99
	v_fmamk_f32 v73, v73, 0x3e0293ee, v99
	v_fmamk_f32 v90, v90, 0x3e0293ee, v99
	v_fmamk_f32 v74, v74, 0x3e0293ee, v99
	v_fmamk_f32 v91, v91, 0x3e0293ee, v99
	v_fmamk_f32 v75, v75, 0x3e0293ee, v99
	v_fmamk_f32 v92, v92, 0x3e0293ee, v99
	v_fmamk_f32 v76, v76, 0x3e0293ee, v99
	v_fmamk_f32 v93, v93, 0x3e0293ee, v99
	v_fmamk_f32 v77, v77, 0x3e0293ee, v99
	v_fmamk_f32 v94, v94, 0x3e0293ee, v99
	v_fmamk_f32 v78, v78, 0x3e0293ee, v99
	v_fmamk_f32 v95, v95, 0x3e0293ee, v99
	v_fmamk_f32 v79, v79, 0x3e0293ee, v99
	v_fmamk_f32 v96, v96, 0x3e0293ee, v99
	v_fmamk_f32 v80, v80, 0x3e0293ee, v99
	v_fmamk_f32 v97, v97, 0x3e0293ee, v99
	v_fmac_f32_e32 v99, 0x3e0293ee, v81
	v_exp_f32_e32 v81, v82
	v_exp_f32_e32 v82, v83
	v_exp_f32_e32 v83, v84
	v_exp_f32_e32 v84, v85
	v_exp_f32_e32 v85, v86
	v_exp_f32_e32 v86, v87
	v_exp_f32_e32 v87, v88
	v_exp_f32_e32 v88, v89
	v_exp_f32_e32 v89, v90
	v_exp_f32_e32 v90, v91
	v_exp_f32_e32 v91, v92
	v_exp_f32_e32 v92, v93
	v_exp_f32_e32 v93, v94
	v_exp_f32_e32 v94, v95
	v_exp_f32_e32 v95, v96
	v_exp_f32_e32 v96, v97
	v_exp_f32_e32 v97, v66
	v_add_f32_e32 v66, 0, v81
	v_add_f32_e32 v66, v82, v66
	v_add_f32_e32 v66, v83, v66
	v_add_f32_e32 v66, v84, v66
	v_add_f32_e32 v66, v85, v66
	v_add_f32_e32 v66, v86, v66
	v_add_f32_e32 v66, v87, v66
	v_add_f32_e32 v66, v88, v66
	v_add_f32_e32 v66, v89, v66
	v_add_f32_e32 v66, v90, v66
	v_add_f32_e32 v66, v91, v66
	v_add_f32_e32 v66, v92, v66
	v_add_f32_e32 v66, v93, v66
	v_exp_f32_e32 v100, v67
	v_add_f32_e32 v66, v94, v66
	v_exp_f32_e32 v101, v68
	v_add_f32_e32 v66, v95, v66
	v_exp_f32_e32 v104, v69
	v_add_f32_e32 v66, v96, v66
	v_exp_f32_e32 v105, v70
	v_add_f32_e32 v66, v97, v66
	v_exp_f32_e32 v106, v71
	v_add_f32_e32 v66, v100, v66
	v_exp_f32_e32 v107, v72
	v_add_f32_e32 v66, v101, v66
	v_exp_f32_e32 v108, v73
	v_add_f32_e32 v66, v104, v66
	v_exp_f32_e32 v109, v74
	v_add_f32_e32 v66, v105, v66
	v_exp_f32_e32 v110, v75
	v_add_f32_e32 v66, v106, v66
	v_exp_f32_e32 v111, v76
	v_add_f32_e32 v66, v107, v66
	v_exp_f32_e32 v112, v77
	v_add_f32_e32 v66, v108, v66
	v_exp_f32_e32 v113, v78
	v_add_f32_e32 v66, v109, v66
	v_exp_f32_e32 v114, v79
	v_add_f32_e32 v66, v110, v66
	v_exp_f32_e32 v115, v80
	v_add_f32_e32 v66, v111, v66
	v_exp_f32_e32 v99, v99
	v_add_f32_e32 v66, v112, v66
	v_add_f32_e32 v66, v113, v66
	v_add_f32_e32 v66, v114, v66
	v_add_f32_e32 v66, v115, v66
	v_add_f32_e32 v70, v99, v66
	v_mov_b32_e32 v71, v70
	s_nop 1
	v_permlane32_swap_b32_e32 v70, v71
	v_cvt_pk_bf16_f32 v66, v81, v82
	v_cvt_pk_bf16_f32 v67, v83, v84
	v_cvt_pk_bf16_f32 v68, v85, v86
	v_cvt_pk_bf16_f32 v69, v87, v88
	v_cvt_pk_bf16_f32 v72, v89, v90
	v_cvt_pk_bf16_f32 v73, v91, v92
	v_cvt_pk_bf16_f32 v74, v93, v94
	v_cvt_pk_bf16_f32 v75, v95, v96
	v_cvt_pk_bf16_f32 v76, v97, v100
	v_cvt_pk_bf16_f32 v77, v101, v104
	v_cvt_pk_bf16_f32 v78, v105, v106
	v_cvt_pk_bf16_f32 v79, v107, v108
	v_cvt_pk_bf16_f32 v80, v109, v110
	v_cvt_pk_bf16_f32 v81, v111, v112
	v_cvt_pk_bf16_f32 v82, v113, v114
	v_cvt_pk_bf16_f32 v83, v115, v99
	s_nop 0
	v_permlane32_swap_b32_e32 v66, v68
	v_permlane32_swap_b32_e32 v67, v69
	v_permlane32_swap_b32_e32 v72, v74
	v_permlane32_swap_b32_e32 v73, v75
	v_permlane32_swap_b32_e32 v76, v78
	v_permlane32_swap_b32_e32 v77, v79
	v_permlane32_swap_b32_e32 v80, v82
	v_permlane32_swap_b32_e32 v81, v83
	ds_read_b64_tr_b16 v[84:85], v158 offset:0x4000
	ds_read_b64_tr_b16 v[86:87], v158 offset:0x4800
	ds_read_b64_tr_b16 v[88:89], v158 offset:0x5000
	ds_read_b64_tr_b16 v[90:91], v158 offset:0x5800
	ds_read_b64_tr_b16 v[92:93], v158 offset:0x6000
	ds_read_b64_tr_b16 v[94:95], v158 offset:0x6800
	ds_read_b64_tr_b16 v[104:105], v158 offset:0x7000
	ds_read_b64_tr_b16 v[106:107], v158 offset:0x7800
	s_nop 0
	s_waitcnt lgkmcnt(4)
	v_mfma_f32_32x32x16_bf16 v[2:17], v[66:69], v[84:87], v[2:17]
	ds_read_b64_tr_b16 v[84:85], v158 offset:0x4200
	ds_read_b64_tr_b16 v[86:87], v158 offset:0x4a00
	v_mfma_f32_32x32x16_bf16 v[2:17], v[72:75], v[88:91], v[2:17]
	ds_read_b64_tr_b16 v[88:89], v158 offset:0x5200
	ds_read_b64_tr_b16 v[90:91], v158 offset:0x5a00
	s_waitcnt lgkmcnt(4)
	v_mfma_f32_32x32x16_bf16 v[2:17], v[76:79], v[92:95], v[2:17]
	ds_read_b64_tr_b16 v[92:93], v158 offset:0x6200
	ds_read_b64_tr_b16 v[94:95], v158 offset:0x6a00
	v_mfma_f32_32x32x16_bf16 v[2:17], v[80:83], v[104:107], v[2:17]
	ds_read_b64_tr_b16 v[104:105], v158 offset:0x7200
	ds_read_b64_tr_b16 v[106:107], v158 offset:0x7a00
	s_waitcnt lgkmcnt(4)
	v_mfma_f32_32x32x16_bf16 v[18:33], v[66:69], v[84:87], v[18:33]
	ds_read_b64_tr_b16 v[84:85], v158 offset:0x4400
	ds_read_b64_tr_b16 v[86:87], v158 offset:0x4c00
	v_mfma_f32_32x32x16_bf16 v[18:33], v[72:75], v[88:91], v[18:33]
	ds_read_b64_tr_b16 v[88:89], v158 offset:0x5400
	ds_read_b64_tr_b16 v[90:91], v158 offset:0x5c00
	s_waitcnt lgkmcnt(4)
	v_mfma_f32_32x32x16_bf16 v[18:33], v[76:79], v[92:95], v[18:33]
	ds_read_b64_tr_b16 v[92:93], v158 offset:0x6400
	ds_read_b64_tr_b16 v[94:95], v158 offset:0x6c00
	v_mfma_f32_32x32x16_bf16 v[18:33], v[80:83], v[104:107], v[18:33]
	ds_read_b64_tr_b16 v[104:105], v158 offset:0x7400
	ds_read_b64_tr_b16 v[106:107], v158 offset:0x7c00
	s_waitcnt lgkmcnt(4)
	v_mfma_f32_32x32x16_bf16 v[34:49], v[66:69], v[84:87], v[34:49]
	ds_read_b64_tr_b16 v[84:85], v158 offset:0x4600
	ds_read_b64_tr_b16 v[86:87], v158 offset:0x4e00
	v_mfma_f32_32x32x16_bf16 v[34:49], v[72:75], v[88:91], v[34:49]
	ds_read_b64_tr_b16 v[88:89], v158 offset:0x5600
	ds_read_b64_tr_b16 v[90:91], v158 offset:0x5e00
	s_waitcnt lgkmcnt(4)
	v_mfma_f32_32x32x16_bf16 v[34:49], v[76:79], v[92:95], v[34:49]
	ds_read_b64_tr_b16 v[92:93], v158 offset:0x6600
	ds_read_b64_tr_b16 v[94:95], v158 offset:0x6e00
	v_mfma_f32_32x32x16_bf16 v[34:49], v[80:83], v[104:107], v[34:49]
	ds_read_b64_tr_b16 v[104:105], v158 offset:0x7600
	ds_read_b64_tr_b16 v[106:107], v158 offset:0x7e00
	s_waitcnt lgkmcnt(4)
	v_mfma_f32_32x32x16_bf16 v[50:65], v[66:69], v[84:87], v[50:65]
	v_mfma_f32_32x32x16_bf16 v[50:65], v[72:75], v[88:91], v[50:65]
	s_waitcnt lgkmcnt(0)
	v_mfma_f32_32x32x16_bf16 v[50:65], v[76:79], v[92:95], v[50:65]
	v_mfma_f32_32x32x16_bf16 v[50:65], v[80:83], v[104:107], v[50:65]
	s_and_saveexec_b64 s[4:5], s[38:39]
	s_cbranch_execz .LBB0_1428
	v_mul_f32_e32 v66, 0, v181
	v_cndmask_b32_e64 v66, v66, 0, s[36:37]
	v_add_f32_e32 v67, v169, v179
	v_add_f32_e32 v66, v66, v67
	v_add_f32_e32 v67, v182, v183
	v_fmac_f32_e32 v67, v66, v180
	v_add_f32_e32 v66, v102, v103
	v_fmac_f32_e32 v66, v67, v146
	v_add_f32_e32 v67, v70, v71
	v_fmac_f32_e32 v67, v66, v98
	ds_write_b32 v159, v67
